# GEMM K-loops: removed the back-to-back s_setprio 0 / s_setprio 1 pair in the middle of each 32-MFMA segment (prio stays 1 across the segment)
# speedup vs baseline: 1.0026x; 1.0026x over previous
; #define PG8_STAGE(bufoff, gbase, voff) do { _Pragma("unroll") for (int _i = 0; _i < 2; ++_i) \
;         __builtin_amdgcn_global_load_lds((const unsigned*)((const char*)(gbase) + (voff)[_i]), (PG8_LAS unsigned*)(lds + (bufoff) + ldsw + _i * 8192), 16, 0, 0); } while (0)
; #define PG8_LDA(dst, b, h) do { _Pragma("unroll") for (int m = 0; m < 4; ++m) _Pragma("unroll") for (int k = 0; k < 2; ++k) dst[m][k] = *(const PG8_LAS bf16x8*)(lds + PG8_SA(b, h) + aoff + m * 2048 + k * 1024); } while (0)
; #define PG8_LDB(dst, b, h) do { _Pragma("unroll") for (int n = 0; n < 2; ++n) _Pragma("unroll") for (int k = 0; k < 2; ++k) dst[n][k] = *(const PG8_LAS bf16x8*)(lds + PG8_SB(b, h) + boff + n * 2048 + k * 1024); } while (0)
; #define PG8_MMA(ai, bj, At, Bt) do { __builtin_amdgcn_s_setprio(1); _Pragma("unroll") for (int m = 0; m < 4; ++m) _Pragma("unroll") for (int n = 0; n < 2; ++n) _Pragma("unroll") for (int k = 0; k < 2; ++k) \
;         acc[ai][bj][m][n] = __builtin_amdgcn_mfma_f32_16x16x32_bf16(Bt[n][k], At[m][k], acc[ai][bj][m][n], 0, 0, 0); __builtin_amdgcn_s_setprio(0); } while (0)
; #define PG8_WAIT_V(n) asm volatile("s_waitcnt vmcnt(" #n ")" ::: "memory")
; #define PG8_WAIT_L(n) asm volatile("s_waitcnt lgkmcnt(" #n ")" ::: "memory")
; #define PG8_BAR __builtin_amdgcn_s_barrier()
; template <class Epi, class Sched, bool ALIGN_EPI = false, bool SP2 = false>
; __device__ __forceinline__ void gemm_phase(PG8_LAS unsigned char* lds, const Gemm g, const Sched& S, const Epi& E) {
;     ...
;             const char* a1 = cA + (size_t)(t + 1) * kstep;
;             const char* a2 = last ? nA : cA + (size_t)(t + 2) * kstep; const char* b2 = last ? nB : cB + (size_t)(t + 2) * kstep;
;             const char* a3 = a2 + kstep; const char* b3 = b2 + kstep;
;             if (last && has_next) S.a_ready(nxt);
;             if constexpr (SP2) {
;             PG8_LDB(B0, 0, 0); PG8_LDB(B1, 0, 1); PG8_SCHED; PG8_LDA(At, 0, 0); PG8_STAGE(PG8_SA(1, 1), a1 + hstepA, voffA);
;             PG8_WAIT_V(8); PG8_WAIT_L(0); PG8_BAR; PG8_MMA(0, 0, At, B0); PG8_MMA(0, 1, At, B1); PG8_BAR; PG8_SCHED;
;             PG8_LDA(At, 0, 1); PG8_STAGE(PG8_SB(0, 0), b2, voffB); PG8_STAGE(PG8_SB(0, 1), b2 + hstepB, voffB); PG8_STAGE(PG8_SA(0, 0), a2, voffA);
;             PG8_WAIT_V(8); PG8_WAIT_L(0); PG8_BAR; PG8_MMA(1, 0, At, B0); PG8_MMA(1, 1, At, B1); PG8_BAR; PG8_SCHED;
.LBB0_454:
	s_add_u32 s0, s40, 0xfffc0080
	s_addc_u32 s1, s41, -1
	s_add_i32 s16, 0, 0x10000
	s_cmp_eq_u32 s13, 12
	s_cselect_b32 s1, s2, s1
	s_cselect_b32 s0, s3, s0
	s_cselect_b32 s49, s8, s12
	s_cselect_b32 s48, s9, s10
	s_add_i32 s18, 0, 0x14000
	v_add_u32_e32 v152, s16, v158
	v_add_u32_e32 v156, s18, v158
	ds_read_b128 v[140:143], v152
	ds_read_b128 v[144:147], v152 offset:1024
	ds_read_b128 v[148:151], v152 offset:2048
	ds_read_b128 v[152:155], v152 offset:3072
	ds_read_b128 v[160:163], v156
	ds_read_b128 v[186:189], v156 offset:1024
	ds_read_b128 v[190:193], v156 offset:2048
	ds_read_b128 v[194:197], v156 offset:3072
	v_lshl_add_u64 v[156:157], s[40:41], 0, v[138:139]
	s_add_i32 m0, s59, 0xc000
	ds_read_b128 v[198:201], v159
	ds_read_b128 v[202:205], v159 offset:1024
	ds_read_b128 v[214:217], v159 offset:2048
	ds_read_b128 v[218:221], v159 offset:3072
	ds_read_b128 v[222:225], v159 offset:4096
	ds_read_b128 v[226:229], v159 offset:5120
	ds_read_b128 v[230:233], v159 offset:6144
	ds_read_b128 v[234:237], v159 offset:7168
	global_load_lds_dwordx4 v[156:157], off
	v_lshl_add_u64 v[156:157], s[40:41], 0, v[136:137]
	s_add_i32 m0, s59, 0xe000
	s_nop 0
	global_load_lds_dwordx4 v[156:157], off
	s_waitcnt vmcnt(8)
	s_waitcnt lgkmcnt(0)
	s_barrier
	s_setprio 1
	s_waitcnt lgkmcnt(0)
	v_mfma_f32_16x16x32_bf16 v[116:119], v[140:143], v[198:201], v[116:119]
	v_mfma_f32_16x16x32_bf16 v[112:115], v[148:151], v[198:201], v[112:115]
	v_mfma_f32_16x16x32_bf16 v[100:103], v[140:143], v[214:217], v[100:103]
	v_mfma_f32_16x16x32_bf16 v[96:99], v[148:151], v[214:217], v[96:99]
	v_mfma_f32_16x16x32_bf16 v[84:87], v[140:143], v[222:225], v[84:87]
	v_mfma_f32_16x16x32_bf16 v[80:83], v[148:151], v[222:225], v[80:83]
	v_mfma_f32_16x16x32_bf16 v[68:71], v[140:143], v[230:233], v[68:71]
	v_mfma_f32_16x16x32_bf16 v[64:67], v[148:151], v[230:233], v[64:67]
	v_mfma_f32_16x16x32_bf16 v[116:119], v[144:147], v[202:205], v[116:119]
	v_mfma_f32_16x16x32_bf16 v[112:115], v[152:155], v[202:205], v[112:115]
	v_mfma_f32_16x16x32_bf16 v[100:103], v[144:147], v[218:221], v[100:103]
	v_mfma_f32_16x16x32_bf16 v[96:99], v[152:155], v[218:221], v[96:99]
	v_mfma_f32_16x16x32_bf16 v[84:87], v[144:147], v[226:229], v[84:87]
	v_mfma_f32_16x16x32_bf16 v[80:83], v[152:155], v[226:229], v[80:83]
	v_mfma_f32_16x16x32_bf16 v[68:71], v[144:147], v[234:237], v[68:71]
	v_mfma_f32_16x16x32_bf16 v[64:67], v[152:155], v[234:237], v[64:67]
	v_mfma_f32_16x16x32_bf16 v[124:127], v[160:163], v[198:201], v[124:127]
	v_mfma_f32_16x16x32_bf16 v[120:123], v[190:193], v[198:201], v[120:123]
	v_mfma_f32_16x16x32_bf16 v[108:111], v[160:163], v[214:217], v[108:111]
	v_mfma_f32_16x16x32_bf16 v[104:107], v[190:193], v[214:217], v[104:107]
	v_mfma_f32_16x16x32_bf16 v[92:95], v[160:163], v[222:225], v[92:95]
	v_mfma_f32_16x16x32_bf16 v[88:91], v[190:193], v[222:225], v[88:91]
	v_mfma_f32_16x16x32_bf16 v[76:79], v[160:163], v[230:233], v[76:79]
	v_mfma_f32_16x16x32_bf16 v[72:75], v[190:193], v[230:233], v[72:75]
	v_mfma_f32_16x16x32_bf16 v[124:127], v[186:189], v[202:205], v[124:127]
	v_mfma_f32_16x16x32_bf16 v[120:123], v[194:197], v[202:205], v[120:123]
	v_mfma_f32_16x16x32_bf16 v[108:111], v[186:189], v[218:221], v[108:111]
	v_mfma_f32_16x16x32_bf16 v[104:107], v[194:197], v[218:221], v[104:107]
	v_mfma_f32_16x16x32_bf16 v[92:95], v[186:189], v[226:229], v[92:95]
	v_mfma_f32_16x16x32_bf16 v[88:91], v[194:197], v[226:229], v[88:91]
	v_mfma_f32_16x16x32_bf16 v[76:79], v[186:189], v[234:237], v[76:79]
	v_mfma_f32_16x16x32_bf16 v[72:75], v[194:197], v[234:237], v[72:75]
	s_setprio 0
	s_barrier
	s_add_i32 s16, s16, s58
	v_lshl_add_u64 v[156:157], s[48:49], 0, v[130:131]
	s_mov_b32 m0, s16
	ds_read_b128 v[198:201], v159 offset:16384
	ds_read_b128 v[202:205], v159 offset:17408
	ds_read_b128 v[214:217], v159 offset:18432
	ds_read_b128 v[218:221], v159 offset:19456
	ds_read_b128 v[222:225], v159 offset:20480
	ds_read_b128 v[226:229], v159 offset:21504
	ds_read_b128 v[230:233], v159 offset:22528
	ds_read_b128 v[234:237], v159 offset:23552
	global_load_lds_dwordx4 v[156:157], off
	s_add_i32 m0, s16, 0x2000
	s_add_u32 s16, s48, 0x40000
	v_lshl_add_u64 v[166:167], s[48:49], 0, v[134:135]
	s_addc_u32 s17, s49, 0
	s_add_i32 s18, s18, s58
	global_load_lds_dwordx4 v[166:167], off
	v_lshl_add_u64 v[168:169], s[16:17], 0, v[130:131]
	s_mov_b32 m0, s18
	v_lshl_add_u64 v[238:239], s[0:1], 0, v[132:133]
	global_load_lds_dwordx4 v[168:169], off
	v_lshl_add_u64 v[168:169], s[16:17], 0, v[134:135]
	s_add_i32 m0, s18, 0x2000
	s_nop 0
	global_load_lds_dwordx4 v[168:169], off
	v_lshl_add_u64 v[168:169], s[0:1], 0, v[128:129]
	s_mov_b32 m0, s59
	s_nop 0
	global_load_lds_dwordx4 v[168:169], off
	s_mov_b32 m0, s60
	s_nop 0
	global_load_lds_dwordx4 v[238:239], off
	s_waitcnt vmcnt(8)
	s_waitcnt lgkmcnt(0)
	s_barrier
; #define PG8_STAGE(bufoff, gbase, voff) do { _Pragma("unroll") for (int _i = 0; _i < 2; ++_i) \
;         __builtin_amdgcn_global_load_lds((const unsigned*)((const char*)(gbase) + (voff)[_i]), (PG8_LAS unsigned*)(lds + (bufoff) + ldsw + _i * 8192), 16, 0, 0); } while (0)
; #define PG8_LDA(dst, b, h) do { _Pragma("unroll") for (int m = 0; m < 4; ++m) _Pragma("unroll") for (int k = 0; k < 2; ++k) dst[m][k] = *(const PG8_LAS bf16x8*)(lds + PG8_SA(b, h) + aoff + m * 2048 + k * 1024); } while (0)
; #define PG8_LDB(dst, b, h) do { _Pragma("unroll") for (int n = 0; n < 2; ++n) _Pragma("unroll") for (int k = 0; k < 2; ++k) dst[n][k] = *(const PG8_LAS bf16x8*)(lds + PG8_SB(b, h) + boff + n * 2048 + k * 1024); } while (0)
; #define PG8_MMA(ai, bj, At, Bt) do { __builtin_amdgcn_s_setprio(1); _Pragma("unroll") for (int m = 0; m < 4; ++m) _Pragma("unroll") for (int n = 0; n < 2; ++n) _Pragma("unroll") for (int k = 0; k < 2; ++k) \
;         acc[ai][bj][m][n] = __builtin_amdgcn_mfma_f32_16x16x32_bf16(Bt[n][k], At[m][k], acc[ai][bj][m][n], 0, 0, 0); __builtin_amdgcn_s_setprio(0); } while (0)
; #define PG8_WAIT_V(n) asm volatile("s_waitcnt vmcnt(" #n ")" ::: "memory")
; #define PG8_WAIT_L(n) asm volatile("s_waitcnt lgkmcnt(" #n ")" ::: "memory")
; #define PG8_BAR __builtin_amdgcn_s_barrier()
; #define PG8_SCHED __builtin_amdgcn_sched_barrier(0)
; template <class Epi, class Sched, bool ALIGN_EPI = false, bool SP2 = false>
; __device__ __forceinline__ void gemm_phase(PG8_LAS unsigned char* lds, const Gemm g, const Sched& S, const Epi& E) {
;     ...
;             PG8_WAIT_V(8); PG8_WAIT_L(0); PG8_BAR; PG8_MMA(1, 0, At, B0); PG8_MMA(1, 1, At, B1); PG8_BAR; PG8_SCHED;
;             PG8_LDB(B0, 1, 0); PG8_LDB(B1, 1, 1); PG8_SCHED; PG8_LDA(At, 1, 0); PG8_STAGE(PG8_SA(0, 1), a2 + hstepA, voffA);
;             PG8_WAIT_V(8); PG8_WAIT_L(0); PG8_BAR; PG8_MMA(0, 0, At, B0); PG8_MMA(0, 1, At, B1); PG8_BAR; PG8_SCHED;
	s_setprio 1
	s_waitcnt lgkmcnt(0)
	v_mfma_f32_16x16x32_bf16 v[52:55], v[140:143], v[198:201], v[52:55]
	v_mfma_f32_16x16x32_bf16 v[48:51], v[148:151], v[198:201], v[48:51]
	v_mfma_f32_16x16x32_bf16 v[36:39], v[140:143], v[214:217], v[36:39]
	v_mfma_f32_16x16x32_bf16 v[32:35], v[148:151], v[214:217], v[32:35]
	v_mfma_f32_16x16x32_bf16 v[20:23], v[140:143], v[222:225], v[20:23]
	v_mfma_f32_16x16x32_bf16 v[16:19], v[148:151], v[222:225], v[16:19]
	v_mfma_f32_16x16x32_bf16 v[4:7], v[140:143], v[230:233], v[4:7]
	v_mfma_f32_16x16x32_bf16 v[0:3], v[148:151], v[230:233], v[0:3]
	v_mfma_f32_16x16x32_bf16 v[52:55], v[144:147], v[202:205], v[52:55]
	v_mfma_f32_16x16x32_bf16 v[48:51], v[152:155], v[202:205], v[48:51]
	v_mfma_f32_16x16x32_bf16 v[36:39], v[144:147], v[218:221], v[36:39]
	v_mfma_f32_16x16x32_bf16 v[32:35], v[152:155], v[218:221], v[32:35]
	v_mfma_f32_16x16x32_bf16 v[20:23], v[144:147], v[226:229], v[20:23]
	v_mfma_f32_16x16x32_bf16 v[16:19], v[152:155], v[226:229], v[16:19]
	v_mfma_f32_16x16x32_bf16 v[4:7], v[144:147], v[234:237], v[4:7]
	v_mfma_f32_16x16x32_bf16 v[0:3], v[152:155], v[234:237], v[0:3]
	v_mfma_f32_16x16x32_bf16 v[60:63], v[160:163], v[198:201], v[60:63]
	v_mfma_f32_16x16x32_bf16 v[56:59], v[190:193], v[198:201], v[56:59]
	v_mfma_f32_16x16x32_bf16 v[44:47], v[160:163], v[214:217], v[44:47]
	v_mfma_f32_16x16x32_bf16 v[40:43], v[190:193], v[214:217], v[40:43]
	v_mfma_f32_16x16x32_bf16 v[28:31], v[160:163], v[222:225], v[28:31]
	v_mfma_f32_16x16x32_bf16 v[24:27], v[190:193], v[222:225], v[24:27]
	v_mfma_f32_16x16x32_bf16 v[12:15], v[160:163], v[230:233], v[12:15]
	v_mfma_f32_16x16x32_bf16 v[8:11], v[190:193], v[230:233], v[8:11]
	v_mfma_f32_16x16x32_bf16 v[60:63], v[186:189], v[202:205], v[60:63]
	v_mfma_f32_16x16x32_bf16 v[56:59], v[194:197], v[202:205], v[56:59]
	v_mfma_f32_16x16x32_bf16 v[44:47], v[186:189], v[218:221], v[44:47]
	v_mfma_f32_16x16x32_bf16 v[40:43], v[194:197], v[218:221], v[40:43]
	v_mfma_f32_16x16x32_bf16 v[28:31], v[186:189], v[226:229], v[28:31]
	v_mfma_f32_16x16x32_bf16 v[24:27], v[194:197], v[226:229], v[24:27]
	v_mfma_f32_16x16x32_bf16 v[12:15], v[186:189], v[234:237], v[12:15]
	v_mfma_f32_16x16x32_bf16 v[8:11], v[194:197], v[234:237], v[8:11]
	s_setprio 0
	s_barrier
	s_add_i32 s16, 0, 0x18000
	s_add_i32 s17, 0, 0x1c000
	v_add_u32_e32 v152, s16, v158
	v_add_u32_e32 v164, s17, v158
	ds_read_b128 v[140:143], v152
	ds_read_b128 v[144:147], v152 offset:1024
	ds_read_b128 v[148:151], v152 offset:2048
	ds_read_b128 v[152:155], v152 offset:3072
	ds_read_b128 v[160:163], v164
	ds_read_b128 v[186:189], v164 offset:1024
	ds_read_b128 v[190:193], v164 offset:2048
	ds_read_b128 v[194:197], v164 offset:3072
	s_add_u32 s0, s0, 0x40000
	s_addc_u32 s1, s1, 0
	s_mov_b32 m0, s61
	v_lshl_add_u64 v[240:241], s[0:1], 0, v[128:129]
	ds_read_b128 v[198:201], v159 offset:32768
	ds_read_b128 v[202:205], v159 offset:33792
	ds_read_b128 v[214:217], v159 offset:34816
	ds_read_b128 v[218:221], v159 offset:35840
	ds_read_b128 v[222:225], v159 offset:36864
	ds_read_b128 v[226:229], v159 offset:37888
	ds_read_b128 v[230:233], v159 offset:38912
	ds_read_b128 v[234:237], v159 offset:39936
	global_load_lds_dwordx4 v[240:241], off
	v_lshl_add_u64 v[240:241], s[0:1], 0, v[132:133]
	s_mov_b32 m0, s62
	s_nop 0
	global_load_lds_dwordx4 v[240:241], off
	s_waitcnt vmcnt(8)
	s_waitcnt lgkmcnt(0)
	s_barrier
	s_setprio 1
	s_waitcnt lgkmcnt(0)
	v_mfma_f32_16x16x32_bf16 v[116:119], v[140:143], v[198:201], v[116:119]
	v_mfma_f32_16x16x32_bf16 v[112:115], v[148:151], v[198:201], v[112:115]
	v_mfma_f32_16x16x32_bf16 v[100:103], v[140:143], v[214:217], v[100:103]
	v_mfma_f32_16x16x32_bf16 v[96:99], v[148:151], v[214:217], v[96:99]
	v_mfma_f32_16x16x32_bf16 v[84:87], v[140:143], v[222:225], v[84:87]
	v_mfma_f32_16x16x32_bf16 v[80:83], v[148:151], v[222:225], v[80:83]
	v_mfma_f32_16x16x32_bf16 v[68:71], v[140:143], v[230:233], v[68:71]
	v_mfma_f32_16x16x32_bf16 v[64:67], v[148:151], v[230:233], v[64:67]
	v_mfma_f32_16x16x32_bf16 v[116:119], v[144:147], v[202:205], v[116:119]
	v_mfma_f32_16x16x32_bf16 v[112:115], v[152:155], v[202:205], v[112:115]
	v_mfma_f32_16x16x32_bf16 v[100:103], v[144:147], v[218:221], v[100:103]
	v_mfma_f32_16x16x32_bf16 v[96:99], v[152:155], v[218:221], v[96:99]
	v_mfma_f32_16x16x32_bf16 v[84:87], v[144:147], v[226:229], v[84:87]
	v_mfma_f32_16x16x32_bf16 v[80:83], v[152:155], v[226:229], v[80:83]
	v_mfma_f32_16x16x32_bf16 v[68:71], v[144:147], v[234:237], v[68:71]
	v_mfma_f32_16x16x32_bf16 v[64:67], v[152:155], v[234:237], v[64:67]
	v_mfma_f32_16x16x32_bf16 v[124:127], v[160:163], v[198:201], v[124:127]
	v_mfma_f32_16x16x32_bf16 v[120:123], v[190:193], v[198:201], v[120:123]
	v_mfma_f32_16x16x32_bf16 v[108:111], v[160:163], v[214:217], v[108:111]
	v_mfma_f32_16x16x32_bf16 v[104:107], v[190:193], v[214:217], v[104:107]
	v_mfma_f32_16x16x32_bf16 v[92:95], v[160:163], v[222:225], v[92:95]
	v_mfma_f32_16x16x32_bf16 v[88:91], v[190:193], v[222:225], v[88:91]
	v_mfma_f32_16x16x32_bf16 v[76:79], v[160:163], v[230:233], v[76:79]
	v_mfma_f32_16x16x32_bf16 v[72:75], v[190:193], v[230:233], v[72:75]
	v_mfma_f32_16x16x32_bf16 v[124:127], v[186:189], v[202:205], v[124:127]
	v_mfma_f32_16x16x32_bf16 v[120:123], v[194:197], v[202:205], v[120:123]
	v_mfma_f32_16x16x32_bf16 v[108:111], v[186:189], v[218:221], v[108:111]
	v_mfma_f32_16x16x32_bf16 v[104:107], v[194:197], v[218:221], v[104:107]
	v_mfma_f32_16x16x32_bf16 v[92:95], v[186:189], v[226:229], v[92:95]
	v_mfma_f32_16x16x32_bf16 v[88:91], v[194:197], v[226:229], v[88:91]
	v_mfma_f32_16x16x32_bf16 v[76:79], v[186:189], v[234:237], v[76:79]
	v_mfma_f32_16x16x32_bf16 v[72:75], v[194:197], v[234:237], v[72:75]
	s_setprio 0
	s_barrier
; #define PG8_STAGE(bufoff, gbase, voff) do { _Pragma("unroll") for (int _i = 0; _i < 2; ++_i) \
;         __builtin_amdgcn_global_load_lds((const unsigned*)((const char*)(gbase) + (voff)[_i]), (PG8_LAS unsigned*)(lds + (bufoff) + ldsw + _i * 8192), 16, 0, 0); } while (0)
; #define PG8_LDA(dst, b, h) do { _Pragma("unroll") for (int m = 0; m < 4; ++m) _Pragma("unroll") for (int k = 0; k < 2; ++k) dst[m][k] = *(const PG8_LAS bf16x8*)(lds + PG8_SA(b, h) + aoff + m * 2048 + k * 1024); } while (0)
; #define PG8_MMA(ai, bj, At, Bt) do { __builtin_amdgcn_s_setprio(1); _Pragma("unroll") for (int m = 0; m < 4; ++m) _Pragma("unroll") for (int n = 0; n < 2; ++n) _Pragma("unroll") for (int k = 0; k < 2; ++k) \
;         acc[ai][bj][m][n] = __builtin_amdgcn_mfma_f32_16x16x32_bf16(Bt[n][k], At[m][k], acc[ai][bj][m][n], 0, 0, 0); __builtin_amdgcn_s_setprio(0); } while (0)
; #define PG8_WAIT_V(n) asm volatile("s_waitcnt vmcnt(" #n ")" ::: "memory")
; #define PG8_WAIT_L(n) asm volatile("s_waitcnt lgkmcnt(" #n ")" ::: "memory")
; #define PG8_BAR __builtin_amdgcn_s_barrier()
; #define PG8_SCHED __builtin_amdgcn_sched_barrier(0)
; template <class Epi, class Sched, bool ALIGN_EPI = false, bool SP2 = false>
; __device__ __forceinline__ void gemm_phase(PG8_LAS unsigned char* lds, const Gemm g, const Sched& S, const Epi& E) {
;     ...
;             PG8_LDA(At, 1, 1); PG8_STAGE(PG8_SB(1, 0), b3, voffB); PG8_STAGE(PG8_SB(1, 1), b3 + hstepB, voffB); PG8_STAGE(PG8_SA(1, 0), a3, voffA);
;             PG8_WAIT_V(8); PG8_WAIT_L(0); PG8_BAR; PG8_MMA(1, 0, At, B0); PG8_MMA(1, 1, At, B1); PG8_BAR; PG8_SCHED;
;     ...
;         if constexpr (ALIGN_EPI) { if (wr == 0) PG8_BAR; }
	s_add_i32 s0, s16, s58
	v_lshl_add_u64 v[156:157], v[156:157], 0, s[14:15]
	s_mov_b32 m0, s0
	ds_read_b128 v[198:201], v159 offset:49152
	ds_read_b128 v[202:205], v159 offset:50176
	ds_read_b128 v[214:217], v159 offset:51200
	ds_read_b128 v[218:221], v159 offset:52224
	ds_read_b128 v[222:225], v159 offset:53248
	ds_read_b128 v[226:229], v159 offset:54272
	ds_read_b128 v[230:233], v159 offset:55296
	ds_read_b128 v[234:237], v159 offset:56320
	global_load_lds_dwordx4 v[156:157], off
	s_add_i32 m0, s0, 0x2000
	s_add_u32 s0, s48, 0x40080
	v_lshl_add_u64 v[156:157], v[166:167], 0, s[14:15]
	s_addc_u32 s1, s49, 0
	s_add_i32 s16, s17, s58
	global_load_lds_dwordx4 v[156:157], off
	v_lshl_add_u64 v[156:157], s[0:1], 0, v[130:131]
	s_mov_b32 m0, s16
	s_nop 0
	global_load_lds_dwordx4 v[156:157], off
	v_lshl_add_u64 v[156:157], s[0:1], 0, v[134:135]
	s_add_i32 m0, s16, 0x2000
	s_nop 0
	global_load_lds_dwordx4 v[156:157], off
	v_lshl_add_u64 v[156:157], v[168:169], 0, s[14:15]
	s_mov_b32 m0, s79
	s_nop 0
	global_load_lds_dwordx4 v[156:157], off
	v_lshl_add_u64 v[156:157], v[238:239], 0, s[14:15]
	s_mov_b32 m0, s94
	s_nop 0
	global_load_lds_dwordx4 v[156:157], off
	s_waitcnt vmcnt(8)
	s_waitcnt lgkmcnt(0)
	s_barrier
	s_setprio 1
	s_waitcnt lgkmcnt(0)
	v_mfma_f32_16x16x32_bf16 v[52:55], v[140:143], v[198:201], v[52:55]
	v_mfma_f32_16x16x32_bf16 v[48:51], v[148:151], v[198:201], v[48:51]
	v_mfma_f32_16x16x32_bf16 v[36:39], v[140:143], v[214:217], v[36:39]
	v_mfma_f32_16x16x32_bf16 v[32:35], v[148:151], v[214:217], v[32:35]
	v_mfma_f32_16x16x32_bf16 v[20:23], v[140:143], v[222:225], v[20:23]
	v_mfma_f32_16x16x32_bf16 v[16:19], v[148:151], v[222:225], v[16:19]
	v_mfma_f32_16x16x32_bf16 v[4:7], v[140:143], v[230:233], v[4:7]
	v_mfma_f32_16x16x32_bf16 v[0:3], v[148:151], v[230:233], v[0:3]
	v_mfma_f32_16x16x32_bf16 v[52:55], v[144:147], v[202:205], v[52:55]
	v_mfma_f32_16x16x32_bf16 v[48:51], v[152:155], v[202:205], v[48:51]
	v_mfma_f32_16x16x32_bf16 v[36:39], v[144:147], v[218:221], v[36:39]
	v_mfma_f32_16x16x32_bf16 v[32:35], v[152:155], v[218:221], v[32:35]
	v_mfma_f32_16x16x32_bf16 v[20:23], v[144:147], v[226:229], v[20:23]
	v_mfma_f32_16x16x32_bf16 v[16:19], v[152:155], v[226:229], v[16:19]
	v_mfma_f32_16x16x32_bf16 v[4:7], v[144:147], v[234:237], v[4:7]
	v_mfma_f32_16x16x32_bf16 v[0:3], v[152:155], v[234:237], v[0:3]
	v_mfma_f32_16x16x32_bf16 v[60:63], v[160:163], v[198:201], v[60:63]
	v_mfma_f32_16x16x32_bf16 v[56:59], v[190:193], v[198:201], v[56:59]
	v_mfma_f32_16x16x32_bf16 v[44:47], v[160:163], v[214:217], v[44:47]
	v_mfma_f32_16x16x32_bf16 v[40:43], v[190:193], v[214:217], v[40:43]
	v_mfma_f32_16x16x32_bf16 v[28:31], v[160:163], v[222:225], v[28:31]
	v_mfma_f32_16x16x32_bf16 v[24:27], v[190:193], v[222:225], v[24:27]
	v_mfma_f32_16x16x32_bf16 v[12:15], v[160:163], v[230:233], v[12:15]
	v_mfma_f32_16x16x32_bf16 v[8:11], v[190:193], v[230:233], v[8:11]
	v_mfma_f32_16x16x32_bf16 v[60:63], v[186:189], v[202:205], v[60:63]
	v_mfma_f32_16x16x32_bf16 v[56:59], v[194:197], v[202:205], v[56:59]
	v_mfma_f32_16x16x32_bf16 v[44:47], v[186:189], v[218:221], v[44:47]
	v_mfma_f32_16x16x32_bf16 v[40:43], v[194:197], v[218:221], v[40:43]
	v_mfma_f32_16x16x32_bf16 v[28:31], v[186:189], v[226:229], v[28:31]
	v_mfma_f32_16x16x32_bf16 v[24:27], v[194:197], v[226:229], v[24:27]
	v_mfma_f32_16x16x32_bf16 v[12:15], v[186:189], v[234:237], v[12:15]
	v_mfma_f32_16x16x32_bf16 v[8:11], v[194:197], v[234:237], v[8:11]
	s_setprio 0
	s_barrier
	s_add_i32 s13, s13, 2
	s_add_u32 s10, s10, 0x100
	s_addc_u32 s12, s12, 0
	s_add_u32 s40, s40, 0x100
	s_addc_u32 s41, s41, 0
	s_cmp_gt_u32 s13, 13
	s_cbranch_scc0 .LBB0_454
	s_and_b64 vcc, exec, s[66:67]
	s_cbranch_vccz .LBB0_457
	s_barrier

; #define PG8_STAGE(bufoff, gbase, voff) do { _Pragma("unroll") for (int _i = 0; _i < 2; ++_i) \
;         __builtin_amdgcn_global_load_lds((const unsigned*)((const char*)(gbase) + (voff)[_i]), (PG8_LAS unsigned*)(lds + (bufoff) + ldsw + _i * 8192), 16, 0, 0); } while (0)
; #define PG8_LDA(dst, b, h) do { _Pragma("unroll") for (int m = 0; m < 4; ++m) _Pragma("unroll") for (int k = 0; k < 2; ++k) dst[m][k] = *(const PG8_LAS bf16x8*)(lds + PG8_SA(b, h) + aoff + m * 2048 + k * 1024); } while (0)
; #define PG8_LDB(dst, b, h) do { _Pragma("unroll") for (int n = 0; n < 2; ++n) _Pragma("unroll") for (int k = 0; k < 2; ++k) dst[n][k] = *(const PG8_LAS bf16x8*)(lds + PG8_SB(b, h) + boff + n * 2048 + k * 1024); } while (0)
; #define PG8_MMA(ai, bj, At, Bt) do { __builtin_amdgcn_s_setprio(1); _Pragma("unroll") for (int m = 0; m < 4; ++m) _Pragma("unroll") for (int n = 0; n < 2; ++n) _Pragma("unroll") for (int k = 0; k < 2; ++k) \
;         acc[ai][bj][m][n] = __builtin_amdgcn_mfma_f32_16x16x32_bf16(Bt[n][k], At[m][k], acc[ai][bj][m][n], 0, 0, 0); __builtin_amdgcn_s_setprio(0); } while (0)
; #define PG8_WAIT_V(n) asm volatile("s_waitcnt vmcnt(" #n ")" ::: "memory")
; #define PG8_WAIT_L(n) asm volatile("s_waitcnt lgkmcnt(" #n ")" ::: "memory")
; #define PG8_BAR __builtin_amdgcn_s_barrier()
; template <class Epi, class Sched, bool ALIGN_EPI = false, bool SP2 = false>
; __device__ __forceinline__ void gemm_phase(PG8_LAS unsigned char* lds, const Gemm g, const Sched& S, const Epi& E) {
;     ...
;             const char* a1 = cA + (size_t)(t + 1) * kstep;
;             const char* a2 = last ? nA : cA + (size_t)(t + 2) * kstep; const char* b2 = last ? nB : cB + (size_t)(t + 2) * kstep;
;             const char* a3 = a2 + kstep; const char* b3 = b2 + kstep;
;             if (last && has_next) S.a_ready(nxt);
;             if constexpr (SP2) {
;             PG8_LDB(B0, 0, 0); PG8_LDB(B1, 0, 1); PG8_SCHED; PG8_LDA(At, 0, 0); PG8_STAGE(PG8_SA(1, 1), a1 + hstepA, voffA);
;             PG8_WAIT_V(8); PG8_WAIT_L(0); PG8_BAR; PG8_MMA(0, 0, At, B0); PG8_MMA(0, 1, At, B1); PG8_BAR; PG8_SCHED;
;             PG8_LDA(At, 0, 1); PG8_STAGE(PG8_SB(0, 0), b2, voffB); PG8_STAGE(PG8_SB(0, 1), b2 + hstepB, voffB); PG8_STAGE(PG8_SA(0, 0), a2, voffA);
;             PG8_WAIT_V(8); PG8_WAIT_L(0); PG8_BAR; PG8_MMA(1, 0, At, B0); PG8_MMA(1, 1, At, B1); PG8_BAR; PG8_SCHED;
.LBB0_760:
	s_add_u32 s48, s22, 0x100
	s_addc_u32 s49, s23, 0
	s_add_i32 s13, 0, 0x10000
	s_cmp_eq_u32 s12, 2
	s_cselect_b32 s1, s41, s49
	s_cselect_b32 s0, s40, s48
	v_add_u32_e32 v148, s13, v150
	s_cselect_b32 s51, s69, s10
	s_cselect_b32 s50, s68, s9
	s_add_i32 s18, 0, 0x14000
	ds_read_b128 v[128:131], v148
	ds_read_b128 v[132:135], v148 offset:1024
	ds_read_b128 v[152:155], v148 offset:2048
	ds_read_b128 v[156:159], v148 offset:3072
	v_add_u32_e32 v148, s18, v150
	ds_read_b128 v[160:163], v148
	ds_read_b128 v[186:189], v148 offset:1024
	ds_read_b128 v[190:193], v148 offset:2048
	ds_read_b128 v[194:197], v148 offset:3072
	v_lshl_add_u64 v[148:149], s[22:23], 0, v[146:147]
	s_add_i32 m0, s59, 0xc000
	ds_read_b128 v[198:201], v151
	ds_read_b128 v[202:205], v151 offset:1024
	ds_read_b128 v[214:217], v151 offset:2048
	ds_read_b128 v[218:221], v151 offset:3072
	ds_read_b128 v[222:225], v151 offset:4096
	ds_read_b128 v[226:229], v151 offset:5120
	ds_read_b128 v[230:233], v151 offset:6144
	ds_read_b128 v[234:237], v151 offset:7168
	global_load_lds_dwordx4 v[148:149], off
	v_lshl_add_u64 v[148:149], s[22:23], 0, v[144:145]
	s_add_i32 m0, s59, 0xe000
	s_nop 0
	global_load_lds_dwordx4 v[148:149], off
	s_waitcnt vmcnt(8)
	s_waitcnt lgkmcnt(0)
	s_barrier
	s_setprio 1
	s_waitcnt lgkmcnt(0)
	v_mfma_f32_16x16x32_bf16 v[124:127], v[128:131], v[198:201], v[124:127]
	v_mfma_f32_16x16x32_bf16 v[120:123], v[152:155], v[198:201], v[120:123]
	v_mfma_f32_16x16x32_bf16 v[116:119], v[128:131], v[214:217], v[116:119]
	v_mfma_f32_16x16x32_bf16 v[108:111], v[152:155], v[214:217], v[108:111]
	v_mfma_f32_16x16x32_bf16 v[100:103], v[128:131], v[222:225], v[100:103]
	v_mfma_f32_16x16x32_bf16 v[92:95], v[152:155], v[222:225], v[92:95]
	v_mfma_f32_16x16x32_bf16 v[84:87], v[128:131], v[230:233], v[84:87]
	v_mfma_f32_16x16x32_bf16 v[76:79], v[152:155], v[230:233], v[76:79]
	v_mfma_f32_16x16x32_bf16 v[124:127], v[132:135], v[202:205], v[124:127]
	v_mfma_f32_16x16x32_bf16 v[120:123], v[156:159], v[202:205], v[120:123]
	v_mfma_f32_16x16x32_bf16 v[116:119], v[132:135], v[218:221], v[116:119]
	v_mfma_f32_16x16x32_bf16 v[108:111], v[156:159], v[218:221], v[108:111]
	v_mfma_f32_16x16x32_bf16 v[100:103], v[132:135], v[226:229], v[100:103]
	v_mfma_f32_16x16x32_bf16 v[92:95], v[156:159], v[226:229], v[92:95]
	v_mfma_f32_16x16x32_bf16 v[84:87], v[132:135], v[234:237], v[84:87]
	v_mfma_f32_16x16x32_bf16 v[76:79], v[156:159], v[234:237], v[76:79]
	v_mfma_f32_16x16x32_bf16 v[112:115], v[160:163], v[198:201], v[112:115]
	v_mfma_f32_16x16x32_bf16 v[104:107], v[190:193], v[198:201], v[104:107]
	v_mfma_f32_16x16x32_bf16 v[96:99], v[160:163], v[214:217], v[96:99]
	v_mfma_f32_16x16x32_bf16 v[88:91], v[190:193], v[214:217], v[88:91]
	v_mfma_f32_16x16x32_bf16 v[80:83], v[160:163], v[222:225], v[80:83]
	v_mfma_f32_16x16x32_bf16 v[72:75], v[190:193], v[222:225], v[72:75]
	v_mfma_f32_16x16x32_bf16 v[68:71], v[160:163], v[230:233], v[68:71]
	v_mfma_f32_16x16x32_bf16 v[64:67], v[190:193], v[230:233], v[64:67]
	v_mfma_f32_16x16x32_bf16 v[112:115], v[186:189], v[202:205], v[112:115]
	v_mfma_f32_16x16x32_bf16 v[104:107], v[194:197], v[202:205], v[104:107]
	v_mfma_f32_16x16x32_bf16 v[96:99], v[186:189], v[218:221], v[96:99]
	v_mfma_f32_16x16x32_bf16 v[88:91], v[194:197], v[218:221], v[88:91]
	v_mfma_f32_16x16x32_bf16 v[80:83], v[186:189], v[226:229], v[80:83]
	v_mfma_f32_16x16x32_bf16 v[72:75], v[194:197], v[226:229], v[72:75]
	v_mfma_f32_16x16x32_bf16 v[68:71], v[186:189], v[234:237], v[68:71]
	v_mfma_f32_16x16x32_bf16 v[64:67], v[194:197], v[234:237], v[64:67]
	s_setprio 0
	s_barrier
	s_add_i32 s13, s13, s57
	v_lshl_add_u64 v[148:149], s[50:51], 0, v[140:141]
	s_mov_b32 m0, s13
	ds_read_b128 v[198:201], v151 offset:16384
	ds_read_b128 v[202:205], v151 offset:17408
	ds_read_b128 v[214:217], v151 offset:18432
	ds_read_b128 v[218:221], v151 offset:19456
	ds_read_b128 v[222:225], v151 offset:20480
	ds_read_b128 v[226:229], v151 offset:21504
	ds_read_b128 v[230:233], v151 offset:22528
	ds_read_b128 v[234:237], v151 offset:23552
	global_load_lds_dwordx4 v[148:149], off
	s_add_i32 m0, s13, 0x2000
	s_add_u32 s16, s50, 0x18000
	v_lshl_add_u64 v[166:167], s[50:51], 0, v[136:137]
	s_addc_u32 s17, s51, 0
	s_add_i32 s13, s18, s57
	global_load_lds_dwordx4 v[166:167], off
	v_lshl_add_u64 v[168:169], s[16:17], 0, v[140:141]
	s_mov_b32 m0, s13
	v_lshl_add_u64 v[238:239], s[0:1], 0, v[138:139]
	global_load_lds_dwordx4 v[168:169], off
	v_lshl_add_u64 v[168:169], s[16:17], 0, v[136:137]
	s_add_i32 m0, s13, 0x2000
	s_nop 0
	global_load_lds_dwordx4 v[168:169], off
	v_lshl_add_u64 v[168:169], s[0:1], 0, v[142:143]
	s_mov_b32 m0, s59
	s_nop 0
	global_load_lds_dwordx4 v[168:169], off
	s_mov_b32 m0, s60
	s_nop 0
	global_load_lds_dwordx4 v[238:239], off
	s_waitcnt vmcnt(8)
	s_waitcnt lgkmcnt(0)
	s_barrier
; #define PG8_STAGE(bufoff, gbase, voff) do { _Pragma("unroll") for (int _i = 0; _i < 2; ++_i) \
;         __builtin_amdgcn_global_load_lds((const unsigned*)((const char*)(gbase) + (voff)[_i]), (PG8_LAS unsigned*)(lds + (bufoff) + ldsw + _i * 8192), 16, 0, 0); } while (0)
; #define PG8_LDA(dst, b, h) do { _Pragma("unroll") for (int m = 0; m < 4; ++m) _Pragma("unroll") for (int k = 0; k < 2; ++k) dst[m][k] = *(const PG8_LAS bf16x8*)(lds + PG8_SA(b, h) + aoff + m * 2048 + k * 1024); } while (0)
; #define PG8_LDB(dst, b, h) do { _Pragma("unroll") for (int n = 0; n < 2; ++n) _Pragma("unroll") for (int k = 0; k < 2; ++k) dst[n][k] = *(const PG8_LAS bf16x8*)(lds + PG8_SB(b, h) + boff + n * 2048 + k * 1024); } while (0)
; #define PG8_MMA(ai, bj, At, Bt) do { __builtin_amdgcn_s_setprio(1); _Pragma("unroll") for (int m = 0; m < 4; ++m) _Pragma("unroll") for (int n = 0; n < 2; ++n) _Pragma("unroll") for (int k = 0; k < 2; ++k) \
;         acc[ai][bj][m][n] = __builtin_amdgcn_mfma_f32_16x16x32_bf16(Bt[n][k], At[m][k], acc[ai][bj][m][n], 0, 0, 0); __builtin_amdgcn_s_setprio(0); } while (0)
; #define PG8_WAIT_V(n) asm volatile("s_waitcnt vmcnt(" #n ")" ::: "memory")
; #define PG8_WAIT_L(n) asm volatile("s_waitcnt lgkmcnt(" #n ")" ::: "memory")
; #define PG8_BAR __builtin_amdgcn_s_barrier()
; #define PG8_SCHED __builtin_amdgcn_sched_barrier(0)
; template <class Epi, class Sched, bool ALIGN_EPI = false, bool SP2 = false>
; __device__ __forceinline__ void gemm_phase(PG8_LAS unsigned char* lds, const Gemm g, const Sched& S, const Epi& E) {
;     ...
;             PG8_WAIT_V(8); PG8_WAIT_L(0); PG8_BAR; PG8_MMA(1, 0, At, B0); PG8_MMA(1, 1, At, B1); PG8_BAR; PG8_SCHED;
;             PG8_LDB(B0, 1, 0); PG8_LDB(B1, 1, 1); PG8_SCHED; PG8_LDA(At, 1, 0); PG8_STAGE(PG8_SA(0, 1), a2 + hstepA, voffA);
;             PG8_WAIT_V(8); PG8_WAIT_L(0); PG8_BAR; PG8_MMA(0, 0, At, B0); PG8_MMA(0, 1, At, B1); PG8_BAR; PG8_SCHED;
	s_setprio 1
	s_waitcnt lgkmcnt(0)
	v_mfma_f32_16x16x32_bf16 v[60:63], v[128:131], v[198:201], v[60:63]
	v_mfma_f32_16x16x32_bf16 v[56:59], v[152:155], v[198:201], v[56:59]
	v_mfma_f32_16x16x32_bf16 v[52:55], v[128:131], v[214:217], v[52:55]
	v_mfma_f32_16x16x32_bf16 v[44:47], v[152:155], v[214:217], v[44:47]
	v_mfma_f32_16x16x32_bf16 v[36:39], v[128:131], v[222:225], v[36:39]
	v_mfma_f32_16x16x32_bf16 v[28:31], v[152:155], v[222:225], v[28:31]
	v_mfma_f32_16x16x32_bf16 v[20:23], v[128:131], v[230:233], v[20:23]
	v_mfma_f32_16x16x32_bf16 v[12:15], v[152:155], v[230:233], v[12:15]
	v_mfma_f32_16x16x32_bf16 v[60:63], v[132:135], v[202:205], v[60:63]
	v_mfma_f32_16x16x32_bf16 v[56:59], v[156:159], v[202:205], v[56:59]
	v_mfma_f32_16x16x32_bf16 v[52:55], v[132:135], v[218:221], v[52:55]
	v_mfma_f32_16x16x32_bf16 v[44:47], v[156:159], v[218:221], v[44:47]
	v_mfma_f32_16x16x32_bf16 v[36:39], v[132:135], v[226:229], v[36:39]
	v_mfma_f32_16x16x32_bf16 v[28:31], v[156:159], v[226:229], v[28:31]
	v_mfma_f32_16x16x32_bf16 v[20:23], v[132:135], v[234:237], v[20:23]
	v_mfma_f32_16x16x32_bf16 v[12:15], v[156:159], v[234:237], v[12:15]
	v_mfma_f32_16x16x32_bf16 v[48:51], v[160:163], v[198:201], v[48:51]
	v_mfma_f32_16x16x32_bf16 v[40:43], v[190:193], v[198:201], v[40:43]
	v_mfma_f32_16x16x32_bf16 v[32:35], v[160:163], v[214:217], v[32:35]
	v_mfma_f32_16x16x32_bf16 v[24:27], v[190:193], v[214:217], v[24:27]
	v_mfma_f32_16x16x32_bf16 v[16:19], v[160:163], v[222:225], v[16:19]
	v_mfma_f32_16x16x32_bf16 v[8:11], v[190:193], v[222:225], v[8:11]
	v_mfma_f32_16x16x32_bf16 v[4:7], v[160:163], v[230:233], v[4:7]
	v_mfma_f32_16x16x32_bf16 v[0:3], v[190:193], v[230:233], v[0:3]
	v_mfma_f32_16x16x32_bf16 v[48:51], v[186:189], v[202:205], v[48:51]
	v_mfma_f32_16x16x32_bf16 v[40:43], v[194:197], v[202:205], v[40:43]
	v_mfma_f32_16x16x32_bf16 v[32:35], v[186:189], v[218:221], v[32:35]
	v_mfma_f32_16x16x32_bf16 v[24:27], v[194:197], v[218:221], v[24:27]
	v_mfma_f32_16x16x32_bf16 v[16:19], v[186:189], v[226:229], v[16:19]
	v_mfma_f32_16x16x32_bf16 v[8:11], v[194:197], v[226:229], v[8:11]
	v_mfma_f32_16x16x32_bf16 v[4:7], v[186:189], v[234:237], v[4:7]
	v_mfma_f32_16x16x32_bf16 v[0:3], v[194:197], v[234:237], v[0:3]
	s_setprio 0
	s_barrier
	s_add_i32 s13, 0, 0x18000
	s_add_i32 s16, 0, 0x1c000
	v_add_u32_e32 v156, s13, v150
	v_add_u32_e32 v164, s16, v150
	ds_read_b128 v[128:131], v156
	ds_read_b128 v[132:135], v156 offset:1024
	ds_read_b128 v[152:155], v156 offset:2048
	ds_read_b128 v[156:159], v156 offset:3072
	ds_read_b128 v[160:163], v164
	ds_read_b128 v[186:189], v164 offset:1024
	ds_read_b128 v[190:193], v164 offset:2048
	ds_read_b128 v[194:197], v164 offset:3072
	s_add_u32 s0, s0, 0x18000
	s_addc_u32 s1, s1, 0
	s_mov_b32 m0, s61
	v_lshl_add_u64 v[240:241], s[0:1], 0, v[142:143]
	ds_read_b128 v[198:201], v151 offset:32768
	ds_read_b128 v[202:205], v151 offset:33792
	ds_read_b128 v[214:217], v151 offset:34816
	ds_read_b128 v[218:221], v151 offset:35840
	ds_read_b128 v[222:225], v151 offset:36864
	ds_read_b128 v[226:229], v151 offset:37888
	ds_read_b128 v[230:233], v151 offset:38912
	ds_read_b128 v[234:237], v151 offset:39936
	global_load_lds_dwordx4 v[240:241], off
	v_lshl_add_u64 v[240:241], s[0:1], 0, v[138:139]
	s_mov_b32 m0, s62
	s_nop 0
	global_load_lds_dwordx4 v[240:241], off
	s_waitcnt vmcnt(8)
	s_waitcnt lgkmcnt(0)
	s_barrier
	s_setprio 1
	s_waitcnt lgkmcnt(0)
	v_mfma_f32_16x16x32_bf16 v[124:127], v[128:131], v[198:201], v[124:127]
	v_mfma_f32_16x16x32_bf16 v[120:123], v[152:155], v[198:201], v[120:123]
	v_mfma_f32_16x16x32_bf16 v[116:119], v[128:131], v[214:217], v[116:119]
	v_mfma_f32_16x16x32_bf16 v[108:111], v[152:155], v[214:217], v[108:111]
	v_mfma_f32_16x16x32_bf16 v[100:103], v[128:131], v[222:225], v[100:103]
	v_mfma_f32_16x16x32_bf16 v[92:95], v[152:155], v[222:225], v[92:95]
	v_mfma_f32_16x16x32_bf16 v[84:87], v[128:131], v[230:233], v[84:87]
	v_mfma_f32_16x16x32_bf16 v[76:79], v[152:155], v[230:233], v[76:79]
	v_mfma_f32_16x16x32_bf16 v[124:127], v[132:135], v[202:205], v[124:127]
	v_mfma_f32_16x16x32_bf16 v[120:123], v[156:159], v[202:205], v[120:123]
	v_mfma_f32_16x16x32_bf16 v[116:119], v[132:135], v[218:221], v[116:119]
	v_mfma_f32_16x16x32_bf16 v[108:111], v[156:159], v[218:221], v[108:111]
	v_mfma_f32_16x16x32_bf16 v[100:103], v[132:135], v[226:229], v[100:103]
	v_mfma_f32_16x16x32_bf16 v[92:95], v[156:159], v[226:229], v[92:95]
	v_mfma_f32_16x16x32_bf16 v[84:87], v[132:135], v[234:237], v[84:87]
	v_mfma_f32_16x16x32_bf16 v[76:79], v[156:159], v[234:237], v[76:79]
	v_mfma_f32_16x16x32_bf16 v[112:115], v[160:163], v[198:201], v[112:115]
	v_mfma_f32_16x16x32_bf16 v[104:107], v[190:193], v[198:201], v[104:107]
	v_mfma_f32_16x16x32_bf16 v[96:99], v[160:163], v[214:217], v[96:99]
	v_mfma_f32_16x16x32_bf16 v[88:91], v[190:193], v[214:217], v[88:91]
	v_mfma_f32_16x16x32_bf16 v[80:83], v[160:163], v[222:225], v[80:83]
	v_mfma_f32_16x16x32_bf16 v[72:75], v[190:193], v[222:225], v[72:75]
	v_mfma_f32_16x16x32_bf16 v[68:71], v[160:163], v[230:233], v[68:71]
	v_mfma_f32_16x16x32_bf16 v[64:67], v[190:193], v[230:233], v[64:67]
	v_mfma_f32_16x16x32_bf16 v[112:115], v[186:189], v[202:205], v[112:115]
	v_mfma_f32_16x16x32_bf16 v[104:107], v[194:197], v[202:205], v[104:107]
	v_mfma_f32_16x16x32_bf16 v[96:99], v[186:189], v[218:221], v[96:99]
	v_mfma_f32_16x16x32_bf16 v[88:91], v[194:197], v[218:221], v[88:91]
	v_mfma_f32_16x16x32_bf16 v[80:83], v[186:189], v[226:229], v[80:83]
	v_mfma_f32_16x16x32_bf16 v[72:75], v[194:197], v[226:229], v[72:75]
	v_mfma_f32_16x16x32_bf16 v[68:71], v[186:189], v[234:237], v[68:71]
	v_mfma_f32_16x16x32_bf16 v[64:67], v[194:197], v[234:237], v[64:67]
	s_setprio 0
	s_barrier
; #define PG8_STAGE(bufoff, gbase, voff) do { _Pragma("unroll") for (int _i = 0; _i < 2; ++_i) \
;         __builtin_amdgcn_global_load_lds((const unsigned*)((const char*)(gbase) + (voff)[_i]), (PG8_LAS unsigned*)(lds + (bufoff) + ldsw + _i * 8192), 16, 0, 0); } while (0)
; #define PG8_LDA(dst, b, h) do { _Pragma("unroll") for (int m = 0; m < 4; ++m) _Pragma("unroll") for (int k = 0; k < 2; ++k) dst[m][k] = *(const PG8_LAS bf16x8*)(lds + PG8_SA(b, h) + aoff + m * 2048 + k * 1024); } while (0)
; #define PG8_MMA(ai, bj, At, Bt) do { __builtin_amdgcn_s_setprio(1); _Pragma("unroll") for (int m = 0; m < 4; ++m) _Pragma("unroll") for (int n = 0; n < 2; ++n) _Pragma("unroll") for (int k = 0; k < 2; ++k) \
;         acc[ai][bj][m][n] = __builtin_amdgcn_mfma_f32_16x16x32_bf16(Bt[n][k], At[m][k], acc[ai][bj][m][n], 0, 0, 0); __builtin_amdgcn_s_setprio(0); } while (0)
; #define PG8_WAIT_V(n) asm volatile("s_waitcnt vmcnt(" #n ")" ::: "memory")
; #define PG8_WAIT_L(n) asm volatile("s_waitcnt lgkmcnt(" #n ")" ::: "memory")
; #define PG8_BAR __builtin_amdgcn_s_barrier()
; #define PG8_SCHED __builtin_amdgcn_sched_barrier(0)
; template <class Epi, class Sched, bool ALIGN_EPI = false, bool SP2 = false>
; __device__ __forceinline__ void gemm_phase(PG8_LAS unsigned char* lds, const Gemm g, const Sched& S, const Epi& E) {
;     ...
;             PG8_LDA(At, 1, 1); PG8_STAGE(PG8_SB(1, 0), b3, voffB); PG8_STAGE(PG8_SB(1, 1), b3 + hstepB, voffB); PG8_STAGE(PG8_SA(1, 0), a3, voffA);
;             PG8_WAIT_V(8); PG8_WAIT_L(0); PG8_BAR; PG8_MMA(1, 0, At, B0); PG8_MMA(1, 1, At, B1); PG8_BAR; PG8_SCHED;
;     ...
;         if constexpr (ALIGN_EPI) { if (wr == 0) PG8_BAR; }
	s_add_i32 s0, s13, s57
	v_lshl_add_u64 v[148:149], v[148:149], 0, s[14:15]
	s_mov_b32 m0, s0
	ds_read_b128 v[198:201], v151 offset:49152
	ds_read_b128 v[202:205], v151 offset:50176
	ds_read_b128 v[214:217], v151 offset:51200
	ds_read_b128 v[218:221], v151 offset:52224
	ds_read_b128 v[222:225], v151 offset:53248
	ds_read_b128 v[226:229], v151 offset:54272
	ds_read_b128 v[230:233], v151 offset:55296
	ds_read_b128 v[234:237], v151 offset:56320
	global_load_lds_dwordx4 v[148:149], off
	s_add_i32 m0, s0, 0x2000
	s_add_u32 s0, s50, 0x18080
	v_lshl_add_u64 v[148:149], v[166:167], 0, s[14:15]
	s_addc_u32 s1, s51, 0
	s_add_i32 s13, s16, s57
	global_load_lds_dwordx4 v[148:149], off
	v_lshl_add_u64 v[148:149], s[0:1], 0, v[140:141]
	s_mov_b32 m0, s13
	s_nop 0
	global_load_lds_dwordx4 v[148:149], off
	v_lshl_add_u64 v[148:149], s[0:1], 0, v[136:137]
	s_add_i32 m0, s13, 0x2000
	s_nop 0
	global_load_lds_dwordx4 v[148:149], off
	v_lshl_add_u64 v[148:149], v[168:169], 0, s[14:15]
	s_mov_b32 m0, s70
	s_nop 0
	global_load_lds_dwordx4 v[148:149], off
	v_lshl_add_u64 v[148:149], v[238:239], 0, s[14:15]
	s_mov_b32 m0, s71
	s_nop 0
	global_load_lds_dwordx4 v[148:149], off
	s_waitcnt vmcnt(8)
	s_waitcnt lgkmcnt(0)
	s_barrier
	s_setprio 1
	s_waitcnt lgkmcnt(0)
	v_mfma_f32_16x16x32_bf16 v[60:63], v[128:131], v[198:201], v[60:63]
	v_mfma_f32_16x16x32_bf16 v[56:59], v[152:155], v[198:201], v[56:59]
	v_mfma_f32_16x16x32_bf16 v[52:55], v[128:131], v[214:217], v[52:55]
	v_mfma_f32_16x16x32_bf16 v[44:47], v[152:155], v[214:217], v[44:47]
	v_mfma_f32_16x16x32_bf16 v[36:39], v[128:131], v[222:225], v[36:39]
	v_mfma_f32_16x16x32_bf16 v[28:31], v[152:155], v[222:225], v[28:31]
	v_mfma_f32_16x16x32_bf16 v[20:23], v[128:131], v[230:233], v[20:23]
	v_mfma_f32_16x16x32_bf16 v[12:15], v[152:155], v[230:233], v[12:15]
	v_mfma_f32_16x16x32_bf16 v[60:63], v[132:135], v[202:205], v[60:63]
	v_mfma_f32_16x16x32_bf16 v[56:59], v[156:159], v[202:205], v[56:59]
	v_mfma_f32_16x16x32_bf16 v[52:55], v[132:135], v[218:221], v[52:55]
	v_mfma_f32_16x16x32_bf16 v[44:47], v[156:159], v[218:221], v[44:47]
	v_mfma_f32_16x16x32_bf16 v[36:39], v[132:135], v[226:229], v[36:39]
	v_mfma_f32_16x16x32_bf16 v[28:31], v[156:159], v[226:229], v[28:31]
	v_mfma_f32_16x16x32_bf16 v[20:23], v[132:135], v[234:237], v[20:23]
	v_mfma_f32_16x16x32_bf16 v[12:15], v[156:159], v[234:237], v[12:15]
	v_mfma_f32_16x16x32_bf16 v[48:51], v[160:163], v[198:201], v[48:51]
	v_mfma_f32_16x16x32_bf16 v[40:43], v[190:193], v[198:201], v[40:43]
	v_mfma_f32_16x16x32_bf16 v[32:35], v[160:163], v[214:217], v[32:35]
	v_mfma_f32_16x16x32_bf16 v[24:27], v[190:193], v[214:217], v[24:27]
	v_mfma_f32_16x16x32_bf16 v[16:19], v[160:163], v[222:225], v[16:19]
	v_mfma_f32_16x16x32_bf16 v[8:11], v[190:193], v[222:225], v[8:11]
	v_mfma_f32_16x16x32_bf16 v[4:7], v[160:163], v[230:233], v[4:7]
	v_mfma_f32_16x16x32_bf16 v[0:3], v[190:193], v[230:233], v[0:3]
	v_mfma_f32_16x16x32_bf16 v[48:51], v[186:189], v[202:205], v[48:51]
	v_mfma_f32_16x16x32_bf16 v[40:43], v[194:197], v[202:205], v[40:43]
	v_mfma_f32_16x16x32_bf16 v[32:35], v[186:189], v[218:221], v[32:35]
	v_mfma_f32_16x16x32_bf16 v[24:27], v[194:197], v[218:221], v[24:27]
	v_mfma_f32_16x16x32_bf16 v[16:19], v[186:189], v[226:229], v[16:19]
	v_mfma_f32_16x16x32_bf16 v[8:11], v[194:197], v[226:229], v[8:11]
	v_mfma_f32_16x16x32_bf16 v[4:7], v[186:189], v[234:237], v[4:7]
	v_mfma_f32_16x16x32_bf16 v[0:3], v[194:197], v[234:237], v[0:3]
	s_setprio 0
	s_barrier
	s_add_i32 s12, s12, 2
	s_add_u32 s9, s9, 0x100
	s_addc_u32 s10, s10, 0
	s_cmp_gt_u32 s12, 3
	s_mov_b64 s[22:23], s[48:49]
	s_cbranch_scc0 .LBB0_760
	s_and_b64 vcc, exec, s[66:67]
	s_cbranch_vccz .LBB0_763
	s_barrier

; #define PG8_STAGE(bufoff, gbase, voff) do { _Pragma("unroll") for (int _i = 0; _i < 2; ++_i) \
;         __builtin_amdgcn_global_load_lds((const unsigned*)((const char*)(gbase) + (voff)[_i]), (PG8_LAS unsigned*)(lds + (bufoff) + ldsw + _i * 8192), 16, 0, 0); } while (0)
; #define PG8_LDA(dst, b, h) do { _Pragma("unroll") for (int m = 0; m < 4; ++m) _Pragma("unroll") for (int k = 0; k < 2; ++k) dst[m][k] = *(const PG8_LAS bf16x8*)(lds + PG8_SA(b, h) + aoff + m * 2048 + k * 1024); } while (0)
; #define PG8_LDB(dst, b, h) do { _Pragma("unroll") for (int n = 0; n < 2; ++n) _Pragma("unroll") for (int k = 0; k < 2; ++k) dst[n][k] = *(const PG8_LAS bf16x8*)(lds + PG8_SB(b, h) + boff + n * 2048 + k * 1024); } while (0)
; #define PG8_MMA(ai, bj, At, Bt) do { __builtin_amdgcn_s_setprio(1); _Pragma("unroll") for (int m = 0; m < 4; ++m) _Pragma("unroll") for (int n = 0; n < 2; ++n) _Pragma("unroll") for (int k = 0; k < 2; ++k) \
;         acc[ai][bj][m][n] = __builtin_amdgcn_mfma_f32_16x16x32_bf16(Bt[n][k], At[m][k], acc[ai][bj][m][n], 0, 0, 0); __builtin_amdgcn_s_setprio(0); } while (0)
; #define PG8_WAIT_V(n) asm volatile("s_waitcnt vmcnt(" #n ")" ::: "memory")
; #define PG8_WAIT_L(n) asm volatile("s_waitcnt lgkmcnt(" #n ")" ::: "memory")
; #define PG8_BAR __builtin_amdgcn_s_barrier()
; template <class Epi, class Sched, bool ALIGN_EPI = false, bool SP2 = false>
; __device__ __forceinline__ void gemm_phase(PG8_LAS unsigned char* lds, const Gemm g, const Sched& S, const Epi& E) {
;     ...
;             const char* a1 = cA + (size_t)(t + 1) * kstep;
;             const char* a2 = last ? nA : cA + (size_t)(t + 2) * kstep; const char* b2 = last ? nB : cB + (size_t)(t + 2) * kstep;
;             const char* a3 = a2 + kstep; const char* b3 = b2 + kstep;
;             if (last && has_next) S.a_ready(nxt);
;             if constexpr (SP2) {
;             PG8_LDB(B0, 0, 0); PG8_LDB(B1, 0, 1); PG8_SCHED; PG8_LDA(At, 0, 0); PG8_STAGE(PG8_SA(1, 1), a1 + hstepA, voffA);
;             PG8_WAIT_V(8); PG8_WAIT_L(0); PG8_BAR; PG8_MMA(0, 0, At, B0); PG8_MMA(0, 1, At, B1); PG8_BAR; PG8_SCHED;
;             PG8_LDA(At, 0, 1); PG8_STAGE(PG8_SB(0, 0), b2, voffB); PG8_STAGE(PG8_SB(0, 1), b2 + hstepB, voffB); PG8_STAGE(PG8_SA(0, 0), a2, voffA);
;             PG8_WAIT_V(8); PG8_WAIT_L(0); PG8_BAR; PG8_MMA(1, 0, At, B0); PG8_MMA(1, 1, At, B1); PG8_BAR; PG8_SCHED;
.LBB0_783:
	s_add_u32 s31, s60, s0
	s_addc_u32 s33, s61, 0
	s_add_u32 s1, s31, 0x100
	s_addc_u32 s44, s33, 0
	s_and_b64 s[36:37], s[64:65], exec
	s_cselect_b32 s69, s17, s44
	s_cselect_b32 s68, s51, s1
	s_add_u32 s0, s54, s0
	s_addc_u32 s1, s55, 0
	s_add_u32 s36, s0, 0x100
	s_addc_u32 s37, s1, 0
	s_add_i32 s44, 0, 0x10000
	s_and_b64 s[0:1], s[64:65], exec
	s_cselect_b32 s71, s49, s37
	s_cselect_b32 s70, s30, s36
	s_add_i32 s45, 0, 0x14000
	s_add_u32 s0, s31, 0x10080
	s_addc_u32 s1, s33, 0
	s_add_i32 s97, s44, s80
	s_add_i32 m0, s4, 0xc000
	s_add_i32 s53, s4, 0xe000
	s_add_i32 s36, s97, 0x2000
	s_add_u32 s72, s70, 0x10000
	v_add_u32_e32 v148, s44, v134
	v_add_u32_e32 v166, s45, v134
	s_addc_u32 s73, s71, 0
	s_add_i32 s37, s45, s80
	ds_read_b128 v[136:139], v148
	ds_read_b128 v[140:143], v148 offset:1024
	ds_read_b128 v[144:147], v148 offset:2048
	ds_read_b128 v[148:151], v148 offset:3072
	ds_read_b128 v[152:155], v166
	ds_read_b128 v[156:159], v166 offset:1024
	ds_read_b128 v[160:163], v166 offset:2048
	ds_read_b128 v[186:189], v166 offset:3072
	s_add_i32 s96, s37, 0x2000
	s_add_i32 vcc_lo, 0, 0x18000
	s_add_i32 vcc_hi, 0, 0x1c000
	s_add_u32 s66, s68, 0x10000
	s_addc_u32 s67, s69, 0
	s_add_i32 s31, vcc_lo, s80
	s_add_i32 s33, s31, 0x2000
	s_add_u32 s64, s70, 0x10080
	s_addc_u32 s65, s71, 0
	s_add_i32 s45, vcc_hi, s80
	s_add_i32 s44, s45, 0x2000
	v_lshl_add_u64 v[166:167], s[0:1], 0, v[132:133]
	ds_read_b128 v[190:193], v135
	ds_read_b128 v[194:197], v135 offset:1024
	ds_read_b128 v[198:201], v135 offset:2048
	ds_read_b128 v[202:205], v135 offset:3072
	ds_read_b128 v[214:217], v135 offset:4096
	ds_read_b128 v[218:221], v135 offset:5120
	ds_read_b128 v[222:225], v135 offset:6144
	ds_read_b128 v[226:229], v135 offset:7168
	global_load_lds_dwordx4 v[166:167], off
	v_lshl_add_u64 v[166:167], s[0:1], 0, v[130:131]
	s_mov_b32 m0, s53
	s_nop 0
	global_load_lds_dwordx4 v[166:167], off
	s_waitcnt vmcnt(8)
	s_waitcnt lgkmcnt(0)
	s_barrier
	s_setprio 1
	s_waitcnt lgkmcnt(0)
	v_mfma_f32_16x16x32_bf16 v[124:127], v[136:139], v[190:193], v[124:127]
	v_mfma_f32_16x16x32_bf16 v[120:123], v[144:147], v[190:193], v[120:123]
	v_mfma_f32_16x16x32_bf16 v[116:119], v[136:139], v[198:201], v[116:119]
	v_mfma_f32_16x16x32_bf16 v[112:115], v[144:147], v[198:201], v[112:115]
	v_mfma_f32_16x16x32_bf16 v[100:103], v[136:139], v[214:217], v[100:103]
	v_mfma_f32_16x16x32_bf16 v[96:99], v[144:147], v[214:217], v[96:99]
	v_mfma_f32_16x16x32_bf16 v[84:87], v[136:139], v[222:225], v[84:87]
	v_mfma_f32_16x16x32_bf16 v[80:83], v[144:147], v[222:225], v[80:83]
	v_mfma_f32_16x16x32_bf16 v[124:127], v[140:143], v[194:197], v[124:127]
	v_mfma_f32_16x16x32_bf16 v[120:123], v[148:151], v[194:197], v[120:123]
	v_mfma_f32_16x16x32_bf16 v[116:119], v[140:143], v[202:205], v[116:119]
	v_mfma_f32_16x16x32_bf16 v[112:115], v[148:151], v[202:205], v[112:115]
	v_mfma_f32_16x16x32_bf16 v[100:103], v[140:143], v[218:221], v[100:103]
	v_mfma_f32_16x16x32_bf16 v[96:99], v[148:151], v[218:221], v[96:99]
	v_mfma_f32_16x16x32_bf16 v[84:87], v[140:143], v[226:229], v[84:87]
	v_mfma_f32_16x16x32_bf16 v[80:83], v[148:151], v[226:229], v[80:83]
	v_mfma_f32_16x16x32_bf16 v[108:111], v[152:155], v[190:193], v[108:111]
	v_mfma_f32_16x16x32_bf16 v[104:107], v[160:163], v[190:193], v[104:107]
	v_mfma_f32_16x16x32_bf16 v[92:95], v[152:155], v[198:201], v[92:95]
	v_mfma_f32_16x16x32_bf16 v[88:91], v[160:163], v[198:201], v[88:91]
	v_mfma_f32_16x16x32_bf16 v[76:79], v[152:155], v[214:217], v[76:79]
	v_mfma_f32_16x16x32_bf16 v[72:75], v[160:163], v[214:217], v[72:75]
	v_mfma_f32_16x16x32_bf16 v[68:71], v[152:155], v[222:225], v[68:71]
	v_mfma_f32_16x16x32_bf16 v[64:67], v[160:163], v[222:225], v[64:67]
	v_mfma_f32_16x16x32_bf16 v[108:111], v[156:159], v[194:197], v[108:111]
	v_mfma_f32_16x16x32_bf16 v[104:107], v[186:189], v[194:197], v[104:107]
	v_mfma_f32_16x16x32_bf16 v[92:95], v[156:159], v[202:205], v[92:95]
	v_mfma_f32_16x16x32_bf16 v[88:91], v[186:189], v[202:205], v[88:91]
	v_mfma_f32_16x16x32_bf16 v[76:79], v[156:159], v[218:221], v[76:79]
	v_mfma_f32_16x16x32_bf16 v[72:75], v[186:189], v[218:221], v[72:75]
	v_mfma_f32_16x16x32_bf16 v[68:71], v[156:159], v[226:229], v[68:71]
	v_mfma_f32_16x16x32_bf16 v[64:67], v[186:189], v[226:229], v[64:67]
	s_setprio 0
	s_barrier
	s_mov_b32 m0, s97
	v_lshl_add_u64 v[166:167], s[70:71], 0, v[164:165]
	ds_read_b128 v[190:193], v135 offset:16384
	ds_read_b128 v[194:197], v135 offset:17408
	ds_read_b128 v[198:201], v135 offset:18432
	ds_read_b128 v[202:205], v135 offset:19456
	ds_read_b128 v[214:217], v135 offset:20480
	ds_read_b128 v[218:221], v135 offset:21504
	ds_read_b128 v[222:225], v135 offset:22528
	ds_read_b128 v[226:229], v135 offset:23552
	global_load_lds_dwordx4 v[166:167], off
	v_lshl_add_u64 v[168:169], s[70:71], 0, v[128:129]
	s_mov_b32 m0, s36
	v_lshl_add_u64 v[230:231], s[72:73], 0, v[164:165]
	global_load_lds_dwordx4 v[168:169], off
	s_mov_b32 m0, s37
	v_lshl_add_u64 v[232:233], s[68:69], 0, v[130:131]
	global_load_lds_dwordx4 v[230:231], off
	v_lshl_add_u64 v[230:231], s[72:73], 0, v[128:129]
	s_mov_b32 m0, s96
	s_nop 0
	global_load_lds_dwordx4 v[230:231], off
	v_lshl_add_u64 v[230:231], s[68:69], 0, v[132:133]
	s_mov_b32 m0, s4
	s_nop 0
	global_load_lds_dwordx4 v[230:231], off
	s_mov_b32 m0, s10
	s_nop 0
	global_load_lds_dwordx4 v[232:233], off
	s_waitcnt vmcnt(8)
	s_waitcnt lgkmcnt(0)
	s_barrier
; #define PG8_STAGE(bufoff, gbase, voff) do { _Pragma("unroll") for (int _i = 0; _i < 2; ++_i) \
;         __builtin_amdgcn_global_load_lds((const unsigned*)((const char*)(gbase) + (voff)[_i]), (PG8_LAS unsigned*)(lds + (bufoff) + ldsw + _i * 8192), 16, 0, 0); } while (0)
; #define PG8_LDA(dst, b, h) do { _Pragma("unroll") for (int m = 0; m < 4; ++m) _Pragma("unroll") for (int k = 0; k < 2; ++k) dst[m][k] = *(const PG8_LAS bf16x8*)(lds + PG8_SA(b, h) + aoff + m * 2048 + k * 1024); } while (0)
; #define PG8_LDB(dst, b, h) do { _Pragma("unroll") for (int n = 0; n < 2; ++n) _Pragma("unroll") for (int k = 0; k < 2; ++k) dst[n][k] = *(const PG8_LAS bf16x8*)(lds + PG8_SB(b, h) + boff + n * 2048 + k * 1024); } while (0)
; #define PG8_MMA(ai, bj, At, Bt) do { __builtin_amdgcn_s_setprio(1); _Pragma("unroll") for (int m = 0; m < 4; ++m) _Pragma("unroll") for (int n = 0; n < 2; ++n) _Pragma("unroll") for (int k = 0; k < 2; ++k) \
;         acc[ai][bj][m][n] = __builtin_amdgcn_mfma_f32_16x16x32_bf16(Bt[n][k], At[m][k], acc[ai][bj][m][n], 0, 0, 0); __builtin_amdgcn_s_setprio(0); } while (0)
; #define PG8_WAIT_V(n) asm volatile("s_waitcnt vmcnt(" #n ")" ::: "memory")
; #define PG8_WAIT_L(n) asm volatile("s_waitcnt lgkmcnt(" #n ")" ::: "memory")
; #define PG8_BAR __builtin_amdgcn_s_barrier()
; #define PG8_SCHED __builtin_amdgcn_sched_barrier(0)
; template <class Epi, class Sched, bool ALIGN_EPI = false, bool SP2 = false>
; __device__ __forceinline__ void gemm_phase(PG8_LAS unsigned char* lds, const Gemm g, const Sched& S, const Epi& E) {
;     ...
;             PG8_WAIT_V(8); PG8_WAIT_L(0); PG8_BAR; PG8_MMA(1, 0, At, B0); PG8_MMA(1, 1, At, B1); PG8_BAR; PG8_SCHED;
;             PG8_LDB(B0, 1, 0); PG8_LDB(B1, 1, 1); PG8_SCHED; PG8_LDA(At, 1, 0); PG8_STAGE(PG8_SA(0, 1), a2 + hstepA, voffA);
;             PG8_WAIT_V(8); PG8_WAIT_L(0); PG8_BAR; PG8_MMA(0, 0, At, B0); PG8_MMA(0, 1, At, B1); PG8_BAR; PG8_SCHED;
	s_setprio 1
	s_waitcnt lgkmcnt(0)
	v_mfma_f32_16x16x32_bf16 v[60:63], v[136:139], v[190:193], v[60:63]
	v_mfma_f32_16x16x32_bf16 v[56:59], v[144:147], v[190:193], v[56:59]
	v_mfma_f32_16x16x32_bf16 v[52:55], v[136:139], v[198:201], v[52:55]
	v_mfma_f32_16x16x32_bf16 v[48:51], v[144:147], v[198:201], v[48:51]
	v_mfma_f32_16x16x32_bf16 v[36:39], v[136:139], v[214:217], v[36:39]
	v_mfma_f32_16x16x32_bf16 v[32:35], v[144:147], v[214:217], v[32:35]
	v_mfma_f32_16x16x32_bf16 v[20:23], v[136:139], v[222:225], v[20:23]
	v_mfma_f32_16x16x32_bf16 v[16:19], v[144:147], v[222:225], v[16:19]
	v_mfma_f32_16x16x32_bf16 v[60:63], v[140:143], v[194:197], v[60:63]
	v_mfma_f32_16x16x32_bf16 v[56:59], v[148:151], v[194:197], v[56:59]
	v_mfma_f32_16x16x32_bf16 v[52:55], v[140:143], v[202:205], v[52:55]
	v_mfma_f32_16x16x32_bf16 v[48:51], v[148:151], v[202:205], v[48:51]
	v_mfma_f32_16x16x32_bf16 v[36:39], v[140:143], v[218:221], v[36:39]
	v_mfma_f32_16x16x32_bf16 v[32:35], v[148:151], v[218:221], v[32:35]
	v_mfma_f32_16x16x32_bf16 v[20:23], v[140:143], v[226:229], v[20:23]
	v_mfma_f32_16x16x32_bf16 v[16:19], v[148:151], v[226:229], v[16:19]
	v_mfma_f32_16x16x32_bf16 v[44:47], v[152:155], v[190:193], v[44:47]
	v_mfma_f32_16x16x32_bf16 v[40:43], v[160:163], v[190:193], v[40:43]
	v_mfma_f32_16x16x32_bf16 v[28:31], v[152:155], v[198:201], v[28:31]
	v_mfma_f32_16x16x32_bf16 v[24:27], v[160:163], v[198:201], v[24:27]
	v_mfma_f32_16x16x32_bf16 v[12:15], v[152:155], v[214:217], v[12:15]
	v_mfma_f32_16x16x32_bf16 v[8:11], v[160:163], v[214:217], v[8:11]
	v_mfma_f32_16x16x32_bf16 v[4:7], v[152:155], v[222:225], v[4:7]
	v_mfma_f32_16x16x32_bf16 v[0:3], v[160:163], v[222:225], v[0:3]
	v_mfma_f32_16x16x32_bf16 v[44:47], v[156:159], v[194:197], v[44:47]
	v_mfma_f32_16x16x32_bf16 v[40:43], v[186:189], v[194:197], v[40:43]
	v_mfma_f32_16x16x32_bf16 v[28:31], v[156:159], v[202:205], v[28:31]
	v_mfma_f32_16x16x32_bf16 v[24:27], v[186:189], v[202:205], v[24:27]
	v_mfma_f32_16x16x32_bf16 v[12:15], v[156:159], v[218:221], v[12:15]
	v_mfma_f32_16x16x32_bf16 v[8:11], v[186:189], v[218:221], v[8:11]
	v_mfma_f32_16x16x32_bf16 v[4:7], v[156:159], v[226:229], v[4:7]
	v_mfma_f32_16x16x32_bf16 v[0:3], v[186:189], v[226:229], v[0:3]
	s_setprio 0
	s_barrier
	v_add_u32_e32 v148, vcc_lo, v134
	v_add_u32_e32 v186, vcc_hi, v134
	ds_read_b128 v[136:139], v148
	ds_read_b128 v[140:143], v148 offset:1024
	ds_read_b128 v[144:147], v148 offset:2048
	ds_read_b128 v[148:151], v148 offset:3072
	ds_read_b128 v[152:155], v186
	ds_read_b128 v[156:159], v186 offset:1024
	ds_read_b128 v[160:163], v186 offset:2048
	ds_read_b128 v[186:189], v186 offset:3072
	s_mov_b32 m0, s8
	v_lshl_add_u64 v[234:235], s[66:67], 0, v[132:133]
	ds_read_b128 v[190:193], v135 offset:32768
	ds_read_b128 v[194:197], v135 offset:33792
	ds_read_b128 v[198:201], v135 offset:34816
	ds_read_b128 v[202:205], v135 offset:35840
	ds_read_b128 v[214:217], v135 offset:36864
	ds_read_b128 v[218:221], v135 offset:37888
	ds_read_b128 v[222:225], v135 offset:38912
	ds_read_b128 v[226:229], v135 offset:39936
	global_load_lds_dwordx4 v[234:235], off
	v_lshl_add_u64 v[234:235], s[66:67], 0, v[130:131]
	s_mov_b32 m0, s9
	s_nop 0
	global_load_lds_dwordx4 v[234:235], off
	s_waitcnt vmcnt(8)
	s_waitcnt lgkmcnt(0)
	s_barrier
	s_setprio 1
	s_waitcnt lgkmcnt(0)
	v_mfma_f32_16x16x32_bf16 v[124:127], v[136:139], v[190:193], v[124:127]
	v_mfma_f32_16x16x32_bf16 v[120:123], v[144:147], v[190:193], v[120:123]
	v_mfma_f32_16x16x32_bf16 v[116:119], v[136:139], v[198:201], v[116:119]
	v_mfma_f32_16x16x32_bf16 v[112:115], v[144:147], v[198:201], v[112:115]
	v_mfma_f32_16x16x32_bf16 v[100:103], v[136:139], v[214:217], v[100:103]
	v_mfma_f32_16x16x32_bf16 v[96:99], v[144:147], v[214:217], v[96:99]
	v_mfma_f32_16x16x32_bf16 v[84:87], v[136:139], v[222:225], v[84:87]
	v_mfma_f32_16x16x32_bf16 v[80:83], v[144:147], v[222:225], v[80:83]
	v_mfma_f32_16x16x32_bf16 v[124:127], v[140:143], v[194:197], v[124:127]
	v_mfma_f32_16x16x32_bf16 v[120:123], v[148:151], v[194:197], v[120:123]
	v_mfma_f32_16x16x32_bf16 v[116:119], v[140:143], v[202:205], v[116:119]
	v_mfma_f32_16x16x32_bf16 v[112:115], v[148:151], v[202:205], v[112:115]
	v_mfma_f32_16x16x32_bf16 v[100:103], v[140:143], v[218:221], v[100:103]
	v_mfma_f32_16x16x32_bf16 v[96:99], v[148:151], v[218:221], v[96:99]
	v_mfma_f32_16x16x32_bf16 v[84:87], v[140:143], v[226:229], v[84:87]
	v_mfma_f32_16x16x32_bf16 v[80:83], v[148:151], v[226:229], v[80:83]
	v_mfma_f32_16x16x32_bf16 v[108:111], v[152:155], v[190:193], v[108:111]
	v_mfma_f32_16x16x32_bf16 v[104:107], v[160:163], v[190:193], v[104:107]
	v_mfma_f32_16x16x32_bf16 v[92:95], v[152:155], v[198:201], v[92:95]
	v_mfma_f32_16x16x32_bf16 v[88:91], v[160:163], v[198:201], v[88:91]
	v_mfma_f32_16x16x32_bf16 v[76:79], v[152:155], v[214:217], v[76:79]
	v_mfma_f32_16x16x32_bf16 v[72:75], v[160:163], v[214:217], v[72:75]
	v_mfma_f32_16x16x32_bf16 v[68:71], v[152:155], v[222:225], v[68:71]
	v_mfma_f32_16x16x32_bf16 v[64:67], v[160:163], v[222:225], v[64:67]
	v_mfma_f32_16x16x32_bf16 v[108:111], v[156:159], v[194:197], v[108:111]
	v_mfma_f32_16x16x32_bf16 v[104:107], v[186:189], v[194:197], v[104:107]
	v_mfma_f32_16x16x32_bf16 v[92:95], v[156:159], v[202:205], v[92:95]
	v_mfma_f32_16x16x32_bf16 v[88:91], v[186:189], v[202:205], v[88:91]
	v_mfma_f32_16x16x32_bf16 v[76:79], v[156:159], v[218:221], v[76:79]
	v_mfma_f32_16x16x32_bf16 v[72:75], v[186:189], v[218:221], v[72:75]
	v_mfma_f32_16x16x32_bf16 v[68:71], v[156:159], v[226:229], v[68:71]
	v_mfma_f32_16x16x32_bf16 v[64:67], v[186:189], v[226:229], v[64:67]
	s_setprio 0
	s_barrier
; #define PG8_STAGE(bufoff, gbase, voff) do { _Pragma("unroll") for (int _i = 0; _i < 2; ++_i) \
;         __builtin_amdgcn_global_load_lds((const unsigned*)((const char*)(gbase) + (voff)[_i]), (PG8_LAS unsigned*)(lds + (bufoff) + ldsw + _i * 8192), 16, 0, 0); } while (0)
; #define PG8_LDA(dst, b, h) do { _Pragma("unroll") for (int m = 0; m < 4; ++m) _Pragma("unroll") for (int k = 0; k < 2; ++k) dst[m][k] = *(const PG8_LAS bf16x8*)(lds + PG8_SA(b, h) + aoff + m * 2048 + k * 1024); } while (0)
; #define PG8_MMA(ai, bj, At, Bt) do { __builtin_amdgcn_s_setprio(1); _Pragma("unroll") for (int m = 0; m < 4; ++m) _Pragma("unroll") for (int n = 0; n < 2; ++n) _Pragma("unroll") for (int k = 0; k < 2; ++k) \
;         acc[ai][bj][m][n] = __builtin_amdgcn_mfma_f32_16x16x32_bf16(Bt[n][k], At[m][k], acc[ai][bj][m][n], 0, 0, 0); __builtin_amdgcn_s_setprio(0); } while (0)
; #define PG8_WAIT_V(n) asm volatile("s_waitcnt vmcnt(" #n ")" ::: "memory")
; #define PG8_WAIT_L(n) asm volatile("s_waitcnt lgkmcnt(" #n ")" ::: "memory")
; #define PG8_BAR __builtin_amdgcn_s_barrier()
; #define PG8_SCHED __builtin_amdgcn_sched_barrier(0)
; template <class Epi, class Sched, bool ALIGN_EPI = false, bool SP2 = false>
; __device__ __forceinline__ void gemm_phase(PG8_LAS unsigned char* lds, const Gemm g, const Sched& S, const Epi& E) {
;     ...
;             PG8_LDA(At, 1, 1); PG8_STAGE(PG8_SB(1, 0), b3, voffB); PG8_STAGE(PG8_SB(1, 1), b3 + hstepB, voffB); PG8_STAGE(PG8_SA(1, 0), a3, voffA);
;             PG8_WAIT_V(8); PG8_WAIT_L(0); PG8_BAR; PG8_MMA(1, 0, At, B0); PG8_MMA(1, 1, At, B1); PG8_BAR; PG8_SCHED;
;     ...
;         if constexpr (ALIGN_EPI) { if (wr == 0) PG8_BAR; }
	s_mov_b32 m0, s31
	v_lshl_add_u64 v[166:167], v[166:167], 0, s[14:15]
	ds_read_b128 v[190:193], v135 offset:49152
	ds_read_b128 v[194:197], v135 offset:50176
	ds_read_b128 v[198:201], v135 offset:51200
	ds_read_b128 v[202:205], v135 offset:52224
	ds_read_b128 v[214:217], v135 offset:53248
	ds_read_b128 v[218:221], v135 offset:54272
	ds_read_b128 v[222:225], v135 offset:55296
	ds_read_b128 v[226:229], v135 offset:56320
	global_load_lds_dwordx4 v[166:167], off
	v_lshl_add_u64 v[166:167], v[168:169], 0, s[14:15]
	s_mov_b32 m0, s33
	s_nop 0
	global_load_lds_dwordx4 v[166:167], off
	v_lshl_add_u64 v[166:167], s[64:65], 0, v[164:165]
	s_mov_b32 m0, s45
	s_nop 0
	global_load_lds_dwordx4 v[166:167], off
	v_lshl_add_u64 v[166:167], s[64:65], 0, v[128:129]
	s_mov_b32 m0, s44
	s_nop 0
	global_load_lds_dwordx4 v[166:167], off
	v_lshl_add_u64 v[166:167], v[230:231], 0, s[14:15]
	s_mov_b32 m0, s19
	s_nop 0
	global_load_lds_dwordx4 v[166:167], off
	v_lshl_add_u64 v[166:167], v[232:233], 0, s[14:15]
	s_mov_b32 m0, s92
	s_nop 0
	global_load_lds_dwordx4 v[166:167], off
	s_waitcnt vmcnt(8)
	s_waitcnt lgkmcnt(0)
	s_barrier
	s_setprio 1
	s_waitcnt lgkmcnt(0)
	v_mfma_f32_16x16x32_bf16 v[60:63], v[136:139], v[190:193], v[60:63]
	v_mfma_f32_16x16x32_bf16 v[56:59], v[144:147], v[190:193], v[56:59]
	v_mfma_f32_16x16x32_bf16 v[52:55], v[136:139], v[198:201], v[52:55]
	v_mfma_f32_16x16x32_bf16 v[48:51], v[144:147], v[198:201], v[48:51]
	v_mfma_f32_16x16x32_bf16 v[36:39], v[136:139], v[214:217], v[36:39]
	v_mfma_f32_16x16x32_bf16 v[32:35], v[144:147], v[214:217], v[32:35]
	v_mfma_f32_16x16x32_bf16 v[20:23], v[136:139], v[222:225], v[20:23]
	v_mfma_f32_16x16x32_bf16 v[16:19], v[144:147], v[222:225], v[16:19]
	v_mfma_f32_16x16x32_bf16 v[60:63], v[140:143], v[194:197], v[60:63]
	v_mfma_f32_16x16x32_bf16 v[56:59], v[148:151], v[194:197], v[56:59]
	v_mfma_f32_16x16x32_bf16 v[52:55], v[140:143], v[202:205], v[52:55]
	v_mfma_f32_16x16x32_bf16 v[48:51], v[148:151], v[202:205], v[48:51]
	v_mfma_f32_16x16x32_bf16 v[36:39], v[140:143], v[218:221], v[36:39]
	v_mfma_f32_16x16x32_bf16 v[32:35], v[148:151], v[218:221], v[32:35]
	v_mfma_f32_16x16x32_bf16 v[20:23], v[140:143], v[226:229], v[20:23]
	v_mfma_f32_16x16x32_bf16 v[16:19], v[148:151], v[226:229], v[16:19]
	v_mfma_f32_16x16x32_bf16 v[44:47], v[152:155], v[190:193], v[44:47]
	v_mfma_f32_16x16x32_bf16 v[40:43], v[160:163], v[190:193], v[40:43]
	v_mfma_f32_16x16x32_bf16 v[28:31], v[152:155], v[198:201], v[28:31]
	v_mfma_f32_16x16x32_bf16 v[24:27], v[160:163], v[198:201], v[24:27]
	v_mfma_f32_16x16x32_bf16 v[12:15], v[152:155], v[214:217], v[12:15]
	v_mfma_f32_16x16x32_bf16 v[8:11], v[160:163], v[214:217], v[8:11]
	v_mfma_f32_16x16x32_bf16 v[4:7], v[152:155], v[222:225], v[4:7]
	v_mfma_f32_16x16x32_bf16 v[0:3], v[160:163], v[222:225], v[0:3]
	v_mfma_f32_16x16x32_bf16 v[44:47], v[156:159], v[194:197], v[44:47]
	v_mfma_f32_16x16x32_bf16 v[40:43], v[186:189], v[194:197], v[40:43]
	v_mfma_f32_16x16x32_bf16 v[28:31], v[156:159], v[202:205], v[28:31]
	v_mfma_f32_16x16x32_bf16 v[24:27], v[186:189], v[202:205], v[24:27]
	v_mfma_f32_16x16x32_bf16 v[12:15], v[156:159], v[218:221], v[12:15]
	v_mfma_f32_16x16x32_bf16 v[8:11], v[186:189], v[218:221], v[8:11]
	v_mfma_f32_16x16x32_bf16 v[4:7], v[156:159], v[226:229], v[4:7]
	v_mfma_f32_16x16x32_bf16 v[0:3], v[186:189], v[226:229], v[0:3]
	s_setprio 0
	s_barrier
	s_movk_i32 s0, 0x100
	s_andn2_b64 vcc, exec, s[62:63]
	s_mov_b64 s[64:65], -1
	s_mov_b64 s[62:63], 0
	s_cbranch_vccz .LBB0_783
	s_and_b64 vcc, exec, s[40:41]
	s_cbranch_vccz .LBB0_786
	s_barrier

; #define PG8_STAGE(bufoff, gbase, voff) do { _Pragma("unroll") for (int _i = 0; _i < 2; ++_i) \
;         __builtin_amdgcn_global_load_lds((const unsigned*)((const char*)(gbase) + (voff)[_i]), (PG8_LAS unsigned*)(lds + (bufoff) + ldsw + _i * 8192), 16, 0, 0); } while (0)
; #define PG8_LDA(dst, b, h) do { _Pragma("unroll") for (int m = 0; m < 4; ++m) _Pragma("unroll") for (int k = 0; k < 2; ++k) dst[m][k] = *(const PG8_LAS bf16x8*)(lds + PG8_SA(b, h) + aoff + m * 2048 + k * 1024); } while (0)
; #define PG8_LDB(dst, b, h) do { _Pragma("unroll") for (int n = 0; n < 2; ++n) _Pragma("unroll") for (int k = 0; k < 2; ++k) dst[n][k] = *(const PG8_LAS bf16x8*)(lds + PG8_SB(b, h) + boff + n * 2048 + k * 1024); } while (0)
; #define PG8_MMA(ai, bj, At, Bt) do { __builtin_amdgcn_s_setprio(1); _Pragma("unroll") for (int m = 0; m < 4; ++m) _Pragma("unroll") for (int n = 0; n < 2; ++n) _Pragma("unroll") for (int k = 0; k < 2; ++k) \
;         acc[ai][bj][m][n] = __builtin_amdgcn_mfma_f32_16x16x32_bf16(Bt[n][k], At[m][k], acc[ai][bj][m][n], 0, 0, 0); __builtin_amdgcn_s_setprio(0); } while (0)
; #define PG8_WAIT_V(n) asm volatile("s_waitcnt vmcnt(" #n ")" ::: "memory")
; #define PG8_WAIT_L(n) asm volatile("s_waitcnt lgkmcnt(" #n ")" ::: "memory")
; #define PG8_BAR __builtin_amdgcn_s_barrier()
; template <class Epi, class Sched, bool ALIGN_EPI = false, bool SP2 = false>
; __device__ __forceinline__ void gemm_phase(PG8_LAS unsigned char* lds, const Gemm g, const Sched& S, const Epi& E) {
;     ...
;             const char* a1 = cA + (size_t)(t + 1) * kstep;
;             const char* a2 = last ? nA : cA + (size_t)(t + 2) * kstep; const char* b2 = last ? nB : cB + (size_t)(t + 2) * kstep;
;             const char* a3 = a2 + kstep; const char* b3 = b2 + kstep;
;             if (last && has_next) S.a_ready(nxt);
;             if constexpr (SP2) {
;             PG8_LDB(B0, 0, 0); PG8_LDB(B1, 0, 1); PG8_SCHED; PG8_LDA(At, 0, 0); PG8_STAGE(PG8_SA(1, 1), a1 + hstepA, voffA);
;             PG8_WAIT_V(8); PG8_WAIT_L(0); PG8_BAR; PG8_MMA(0, 0, At, B0); PG8_MMA(0, 1, At, B1); PG8_BAR; PG8_SCHED;
;             PG8_LDA(At, 0, 1); PG8_STAGE(PG8_SB(0, 0), b2, voffB); PG8_STAGE(PG8_SB(0, 1), b2 + hstepB, voffB); PG8_STAGE(PG8_SA(0, 0), a2, voffA);
;             PG8_WAIT_V(8); PG8_WAIT_L(0); PG8_BAR; PG8_MMA(1, 0, At, B0); PG8_MMA(1, 1, At, B1); PG8_BAR; PG8_SCHED;
.LBB0_1027:
	s_add_u32 s0, s56, 0xfffc0080
	s_addc_u32 s1, s57, -1
	s_add_i32 s4, 0, 0x10000
	s_cmp_eq_u32 s63, 12
	s_cselect_b32 s1, s16, s1
	s_cselect_b32 s0, s17, s0
	s_cselect_b32 s59, s49, s62
	s_cselect_b32 s58, s51, s61
	s_add_i32 s5, 0, 0x14000
	v_add_u32_e32 v152, s4, v138
	v_add_u32_e32 v186, s5, v138
	ds_read_b128 v[140:143], v152
	ds_read_b128 v[144:147], v152 offset:1024
	ds_read_b128 v[148:151], v152 offset:2048
	ds_read_b128 v[152:155], v152 offset:3072
	ds_read_b128 v[156:159], v186
	ds_read_b128 v[160:163], v186 offset:1024
	ds_read_b128 v[166:169], v186 offset:2048
	ds_read_b128 v[186:189], v186 offset:3072
	v_lshl_add_u64 v[230:231], s[56:57], 0, v[136:137]
	s_add_i32 m0, s43, 0xc000
	ds_read_b128 v[190:193], v139
	ds_read_b128 v[194:197], v139 offset:1024
	ds_read_b128 v[198:201], v139 offset:2048
	ds_read_b128 v[202:205], v139 offset:3072
	ds_read_b128 v[214:217], v139 offset:4096
	ds_read_b128 v[218:221], v139 offset:5120
	ds_read_b128 v[222:225], v139 offset:6144
	ds_read_b128 v[226:229], v139 offset:7168
	global_load_lds_dwordx4 v[230:231], off
	v_lshl_add_u64 v[230:231], s[56:57], 0, v[134:135]
	s_add_i32 m0, s43, 0xe000
	s_nop 0
	global_load_lds_dwordx4 v[230:231], off
	s_waitcnt vmcnt(8)
	s_waitcnt lgkmcnt(0)
	s_barrier
	s_setprio 1
	s_waitcnt lgkmcnt(0)
	v_mfma_f32_16x16x32_bf16 v[124:127], v[140:143], v[190:193], v[124:127]
	v_mfma_f32_16x16x32_bf16 v[120:123], v[148:151], v[190:193], v[120:123]
	v_mfma_f32_16x16x32_bf16 v[116:119], v[140:143], v[198:201], v[116:119]
	v_mfma_f32_16x16x32_bf16 v[112:115], v[148:151], v[198:201], v[112:115]
	v_mfma_f32_16x16x32_bf16 v[100:103], v[140:143], v[214:217], v[100:103]
	v_mfma_f32_16x16x32_bf16 v[96:99], v[148:151], v[214:217], v[96:99]
	v_mfma_f32_16x16x32_bf16 v[84:87], v[140:143], v[222:225], v[84:87]
	v_mfma_f32_16x16x32_bf16 v[80:83], v[148:151], v[222:225], v[80:83]
	v_mfma_f32_16x16x32_bf16 v[124:127], v[144:147], v[194:197], v[124:127]
	v_mfma_f32_16x16x32_bf16 v[120:123], v[152:155], v[194:197], v[120:123]
	v_mfma_f32_16x16x32_bf16 v[116:119], v[144:147], v[202:205], v[116:119]
	v_mfma_f32_16x16x32_bf16 v[112:115], v[152:155], v[202:205], v[112:115]
	v_mfma_f32_16x16x32_bf16 v[100:103], v[144:147], v[218:221], v[100:103]
	v_mfma_f32_16x16x32_bf16 v[96:99], v[152:155], v[218:221], v[96:99]
	v_mfma_f32_16x16x32_bf16 v[84:87], v[144:147], v[226:229], v[84:87]
	v_mfma_f32_16x16x32_bf16 v[80:83], v[152:155], v[226:229], v[80:83]
	v_mfma_f32_16x16x32_bf16 v[108:111], v[156:159], v[190:193], v[108:111]
	v_mfma_f32_16x16x32_bf16 v[104:107], v[166:169], v[190:193], v[104:107]
	v_mfma_f32_16x16x32_bf16 v[92:95], v[156:159], v[198:201], v[92:95]
	v_mfma_f32_16x16x32_bf16 v[88:91], v[166:169], v[198:201], v[88:91]
	v_mfma_f32_16x16x32_bf16 v[76:79], v[156:159], v[214:217], v[76:79]
	v_mfma_f32_16x16x32_bf16 v[72:75], v[166:169], v[214:217], v[72:75]
	v_mfma_f32_16x16x32_bf16 v[68:71], v[156:159], v[222:225], v[68:71]
	v_mfma_f32_16x16x32_bf16 v[64:67], v[166:169], v[222:225], v[64:67]
	v_mfma_f32_16x16x32_bf16 v[108:111], v[160:163], v[194:197], v[108:111]
	v_mfma_f32_16x16x32_bf16 v[104:107], v[186:189], v[194:197], v[104:107]
	v_mfma_f32_16x16x32_bf16 v[92:95], v[160:163], v[202:205], v[92:95]
	v_mfma_f32_16x16x32_bf16 v[88:91], v[186:189], v[202:205], v[88:91]
	v_mfma_f32_16x16x32_bf16 v[76:79], v[160:163], v[218:221], v[76:79]
	v_mfma_f32_16x16x32_bf16 v[72:75], v[186:189], v[218:221], v[72:75]
	v_mfma_f32_16x16x32_bf16 v[68:71], v[160:163], v[226:229], v[68:71]
	v_mfma_f32_16x16x32_bf16 v[64:67], v[186:189], v[226:229], v[64:67]
	s_setprio 0
	s_barrier
	s_add_i32 s4, s4, s13
	v_lshl_add_u64 v[230:231], s[58:59], 0, v[164:165]
	s_mov_b32 m0, s4
	ds_read_b128 v[190:193], v139 offset:16384
	ds_read_b128 v[194:197], v139 offset:17408
	ds_read_b128 v[198:201], v139 offset:18432
	ds_read_b128 v[202:205], v139 offset:19456
	ds_read_b128 v[214:217], v139 offset:20480
	ds_read_b128 v[218:221], v139 offset:21504
	ds_read_b128 v[222:225], v139 offset:22528
	ds_read_b128 v[226:229], v139 offset:23552
	global_load_lds_dwordx4 v[230:231], off
	s_add_i32 m0, s4, 0x2000
	s_add_u32 s36, s58, 0x40000
	v_lshl_add_u64 v[232:233], s[58:59], 0, v[132:133]
	s_addc_u32 s37, s59, 0
	s_add_i32 s4, s5, s13
	global_load_lds_dwordx4 v[232:233], off
	v_lshl_add_u64 v[234:235], s[36:37], 0, v[164:165]
	s_mov_b32 m0, s4
	v_lshl_add_u64 v[236:237], s[0:1], 0, v[130:131]
	global_load_lds_dwordx4 v[234:235], off
	v_lshl_add_u64 v[234:235], s[36:37], 0, v[132:133]
	s_add_i32 m0, s4, 0x2000
	s_nop 0
	global_load_lds_dwordx4 v[234:235], off
	v_lshl_add_u64 v[234:235], s[0:1], 0, v[128:129]
	s_mov_b32 m0, s43
	s_nop 0
	global_load_lds_dwordx4 v[234:235], off
	s_mov_b32 m0, s46
	s_nop 0
	global_load_lds_dwordx4 v[236:237], off
	s_waitcnt vmcnt(8)
	s_waitcnt lgkmcnt(0)
	s_barrier
; #define PG8_STAGE(bufoff, gbase, voff) do { _Pragma("unroll") for (int _i = 0; _i < 2; ++_i) \
;         __builtin_amdgcn_global_load_lds((const unsigned*)((const char*)(gbase) + (voff)[_i]), (PG8_LAS unsigned*)(lds + (bufoff) + ldsw + _i * 8192), 16, 0, 0); } while (0)
; #define PG8_LDA(dst, b, h) do { _Pragma("unroll") for (int m = 0; m < 4; ++m) _Pragma("unroll") for (int k = 0; k < 2; ++k) dst[m][k] = *(const PG8_LAS bf16x8*)(lds + PG8_SA(b, h) + aoff + m * 2048 + k * 1024); } while (0)
; #define PG8_LDB(dst, b, h) do { _Pragma("unroll") for (int n = 0; n < 2; ++n) _Pragma("unroll") for (int k = 0; k < 2; ++k) dst[n][k] = *(const PG8_LAS bf16x8*)(lds + PG8_SB(b, h) + boff + n * 2048 + k * 1024); } while (0)
; #define PG8_MMA(ai, bj, At, Bt) do { __builtin_amdgcn_s_setprio(1); _Pragma("unroll") for (int m = 0; m < 4; ++m) _Pragma("unroll") for (int n = 0; n < 2; ++n) _Pragma("unroll") for (int k = 0; k < 2; ++k) \
;         acc[ai][bj][m][n] = __builtin_amdgcn_mfma_f32_16x16x32_bf16(Bt[n][k], At[m][k], acc[ai][bj][m][n], 0, 0, 0); __builtin_amdgcn_s_setprio(0); } while (0)
; #define PG8_WAIT_V(n) asm volatile("s_waitcnt vmcnt(" #n ")" ::: "memory")
; #define PG8_WAIT_L(n) asm volatile("s_waitcnt lgkmcnt(" #n ")" ::: "memory")
; #define PG8_BAR __builtin_amdgcn_s_barrier()
; #define PG8_SCHED __builtin_amdgcn_sched_barrier(0)
; template <class Epi, class Sched, bool ALIGN_EPI = false, bool SP2 = false>
; __device__ __forceinline__ void gemm_phase(PG8_LAS unsigned char* lds, const Gemm g, const Sched& S, const Epi& E) {
;     ...
;             PG8_WAIT_V(8); PG8_WAIT_L(0); PG8_BAR; PG8_MMA(1, 0, At, B0); PG8_MMA(1, 1, At, B1); PG8_BAR; PG8_SCHED;
;             PG8_LDB(B0, 1, 0); PG8_LDB(B1, 1, 1); PG8_SCHED; PG8_LDA(At, 1, 0); PG8_STAGE(PG8_SA(0, 1), a2 + hstepA, voffA);
;             PG8_WAIT_V(8); PG8_WAIT_L(0); PG8_BAR; PG8_MMA(0, 0, At, B0); PG8_MMA(0, 1, At, B1); PG8_BAR; PG8_SCHED;
	s_setprio 1
	s_waitcnt lgkmcnt(0)
	v_mfma_f32_16x16x32_bf16 v[60:63], v[140:143], v[190:193], v[60:63]
	v_mfma_f32_16x16x32_bf16 v[56:59], v[148:151], v[190:193], v[56:59]
	v_mfma_f32_16x16x32_bf16 v[52:55], v[140:143], v[198:201], v[52:55]
	v_mfma_f32_16x16x32_bf16 v[48:51], v[148:151], v[198:201], v[48:51]
	v_mfma_f32_16x16x32_bf16 v[36:39], v[140:143], v[214:217], v[36:39]
	v_mfma_f32_16x16x32_bf16 v[32:35], v[148:151], v[214:217], v[32:35]
	v_mfma_f32_16x16x32_bf16 v[20:23], v[140:143], v[222:225], v[20:23]
	v_mfma_f32_16x16x32_bf16 v[16:19], v[148:151], v[222:225], v[16:19]
	v_mfma_f32_16x16x32_bf16 v[60:63], v[144:147], v[194:197], v[60:63]
	v_mfma_f32_16x16x32_bf16 v[56:59], v[152:155], v[194:197], v[56:59]
	v_mfma_f32_16x16x32_bf16 v[52:55], v[144:147], v[202:205], v[52:55]
	v_mfma_f32_16x16x32_bf16 v[48:51], v[152:155], v[202:205], v[48:51]
	v_mfma_f32_16x16x32_bf16 v[36:39], v[144:147], v[218:221], v[36:39]
	v_mfma_f32_16x16x32_bf16 v[32:35], v[152:155], v[218:221], v[32:35]
	v_mfma_f32_16x16x32_bf16 v[20:23], v[144:147], v[226:229], v[20:23]
	v_mfma_f32_16x16x32_bf16 v[16:19], v[152:155], v[226:229], v[16:19]
	v_mfma_f32_16x16x32_bf16 v[44:47], v[156:159], v[190:193], v[44:47]
	v_mfma_f32_16x16x32_bf16 v[40:43], v[166:169], v[190:193], v[40:43]
	v_mfma_f32_16x16x32_bf16 v[28:31], v[156:159], v[198:201], v[28:31]
	v_mfma_f32_16x16x32_bf16 v[24:27], v[166:169], v[198:201], v[24:27]
	v_mfma_f32_16x16x32_bf16 v[12:15], v[156:159], v[214:217], v[12:15]
	v_mfma_f32_16x16x32_bf16 v[8:11], v[166:169], v[214:217], v[8:11]
	v_mfma_f32_16x16x32_bf16 v[4:7], v[156:159], v[222:225], v[4:7]
	v_mfma_f32_16x16x32_bf16 v[0:3], v[166:169], v[222:225], v[0:3]
	v_mfma_f32_16x16x32_bf16 v[44:47], v[160:163], v[194:197], v[44:47]
	v_mfma_f32_16x16x32_bf16 v[40:43], v[186:189], v[194:197], v[40:43]
	v_mfma_f32_16x16x32_bf16 v[28:31], v[160:163], v[202:205], v[28:31]
	v_mfma_f32_16x16x32_bf16 v[24:27], v[186:189], v[202:205], v[24:27]
	v_mfma_f32_16x16x32_bf16 v[12:15], v[160:163], v[218:221], v[12:15]
	v_mfma_f32_16x16x32_bf16 v[8:11], v[186:189], v[218:221], v[8:11]
	v_mfma_f32_16x16x32_bf16 v[4:7], v[160:163], v[226:229], v[4:7]
	v_mfma_f32_16x16x32_bf16 v[0:3], v[186:189], v[226:229], v[0:3]
	s_setprio 0
	s_barrier
	s_add_i32 s4, 0, 0x18000
	s_add_i32 s5, 0, 0x1c000
	v_add_u32_e32 v152, s4, v138
	v_add_u32_e32 v186, s5, v138
	ds_read_b128 v[140:143], v152
	ds_read_b128 v[144:147], v152 offset:1024
	ds_read_b128 v[148:151], v152 offset:2048
	ds_read_b128 v[152:155], v152 offset:3072
	ds_read_b128 v[156:159], v186
	ds_read_b128 v[160:163], v186 offset:1024
	ds_read_b128 v[166:169], v186 offset:2048
	ds_read_b128 v[186:189], v186 offset:3072
	s_add_u32 s0, s0, 0x40000
	s_addc_u32 s1, s1, 0
	s_mov_b32 m0, s47
	v_lshl_add_u64 v[238:239], s[0:1], 0, v[128:129]
	ds_read_b128 v[190:193], v139 offset:32768
	ds_read_b128 v[194:197], v139 offset:33792
	ds_read_b128 v[198:201], v139 offset:34816
	ds_read_b128 v[202:205], v139 offset:35840
	ds_read_b128 v[214:217], v139 offset:36864
	ds_read_b128 v[218:221], v139 offset:37888
	ds_read_b128 v[222:225], v139 offset:38912
	ds_read_b128 v[226:229], v139 offset:39936
	global_load_lds_dwordx4 v[238:239], off
	v_lshl_add_u64 v[238:239], s[0:1], 0, v[130:131]
	s_mov_b32 m0, s60
	s_nop 0
	global_load_lds_dwordx4 v[238:239], off
	s_waitcnt vmcnt(8)
	s_waitcnt lgkmcnt(0)
	s_barrier
	s_setprio 1
	s_waitcnt lgkmcnt(0)
	v_mfma_f32_16x16x32_bf16 v[124:127], v[140:143], v[190:193], v[124:127]
	v_mfma_f32_16x16x32_bf16 v[120:123], v[148:151], v[190:193], v[120:123]
	v_mfma_f32_16x16x32_bf16 v[116:119], v[140:143], v[198:201], v[116:119]
	v_mfma_f32_16x16x32_bf16 v[112:115], v[148:151], v[198:201], v[112:115]
	v_mfma_f32_16x16x32_bf16 v[100:103], v[140:143], v[214:217], v[100:103]
	v_mfma_f32_16x16x32_bf16 v[96:99], v[148:151], v[214:217], v[96:99]
	v_mfma_f32_16x16x32_bf16 v[84:87], v[140:143], v[222:225], v[84:87]
	v_mfma_f32_16x16x32_bf16 v[80:83], v[148:151], v[222:225], v[80:83]
	v_mfma_f32_16x16x32_bf16 v[124:127], v[144:147], v[194:197], v[124:127]
	v_mfma_f32_16x16x32_bf16 v[120:123], v[152:155], v[194:197], v[120:123]
	v_mfma_f32_16x16x32_bf16 v[116:119], v[144:147], v[202:205], v[116:119]
	v_mfma_f32_16x16x32_bf16 v[112:115], v[152:155], v[202:205], v[112:115]
	v_mfma_f32_16x16x32_bf16 v[100:103], v[144:147], v[218:221], v[100:103]
	v_mfma_f32_16x16x32_bf16 v[96:99], v[152:155], v[218:221], v[96:99]
	v_mfma_f32_16x16x32_bf16 v[84:87], v[144:147], v[226:229], v[84:87]
	v_mfma_f32_16x16x32_bf16 v[80:83], v[152:155], v[226:229], v[80:83]
	v_mfma_f32_16x16x32_bf16 v[108:111], v[156:159], v[190:193], v[108:111]
	v_mfma_f32_16x16x32_bf16 v[104:107], v[166:169], v[190:193], v[104:107]
	v_mfma_f32_16x16x32_bf16 v[92:95], v[156:159], v[198:201], v[92:95]
	v_mfma_f32_16x16x32_bf16 v[88:91], v[166:169], v[198:201], v[88:91]
	v_mfma_f32_16x16x32_bf16 v[76:79], v[156:159], v[214:217], v[76:79]
	v_mfma_f32_16x16x32_bf16 v[72:75], v[166:169], v[214:217], v[72:75]
	v_mfma_f32_16x16x32_bf16 v[68:71], v[156:159], v[222:225], v[68:71]
	v_mfma_f32_16x16x32_bf16 v[64:67], v[166:169], v[222:225], v[64:67]
	v_mfma_f32_16x16x32_bf16 v[108:111], v[160:163], v[194:197], v[108:111]
	v_mfma_f32_16x16x32_bf16 v[104:107], v[186:189], v[194:197], v[104:107]
	v_mfma_f32_16x16x32_bf16 v[92:95], v[160:163], v[202:205], v[92:95]
	v_mfma_f32_16x16x32_bf16 v[88:91], v[186:189], v[202:205], v[88:91]
	v_mfma_f32_16x16x32_bf16 v[76:79], v[160:163], v[218:221], v[76:79]
	v_mfma_f32_16x16x32_bf16 v[72:75], v[186:189], v[218:221], v[72:75]
	v_mfma_f32_16x16x32_bf16 v[68:71], v[160:163], v[226:229], v[68:71]
	v_mfma_f32_16x16x32_bf16 v[64:67], v[186:189], v[226:229], v[64:67]
	s_setprio 0
	s_barrier
; #define PG8_STAGE(bufoff, gbase, voff) do { _Pragma("unroll") for (int _i = 0; _i < 2; ++_i) \
;         __builtin_amdgcn_global_load_lds((const unsigned*)((const char*)(gbase) + (voff)[_i]), (PG8_LAS unsigned*)(lds + (bufoff) + ldsw + _i * 8192), 16, 0, 0); } while (0)
; #define PG8_LDA(dst, b, h) do { _Pragma("unroll") for (int m = 0; m < 4; ++m) _Pragma("unroll") for (int k = 0; k < 2; ++k) dst[m][k] = *(const PG8_LAS bf16x8*)(lds + PG8_SA(b, h) + aoff + m * 2048 + k * 1024); } while (0)
; #define PG8_MMA(ai, bj, At, Bt) do { __builtin_amdgcn_s_setprio(1); _Pragma("unroll") for (int m = 0; m < 4; ++m) _Pragma("unroll") for (int n = 0; n < 2; ++n) _Pragma("unroll") for (int k = 0; k < 2; ++k) \
;         acc[ai][bj][m][n] = __builtin_amdgcn_mfma_f32_16x16x32_bf16(Bt[n][k], At[m][k], acc[ai][bj][m][n], 0, 0, 0); __builtin_amdgcn_s_setprio(0); } while (0)
; #define PG8_WAIT_V(n) asm volatile("s_waitcnt vmcnt(" #n ")" ::: "memory")
; #define PG8_WAIT_L(n) asm volatile("s_waitcnt lgkmcnt(" #n ")" ::: "memory")
; #define PG8_BAR __builtin_amdgcn_s_barrier()
; #define PG8_SCHED __builtin_amdgcn_sched_barrier(0)
; template <class Epi, class Sched, bool ALIGN_EPI = false, bool SP2 = false>
; __device__ __forceinline__ void gemm_phase(PG8_LAS unsigned char* lds, const Gemm g, const Sched& S, const Epi& E) {
;     ...
;             PG8_LDA(At, 1, 1); PG8_STAGE(PG8_SB(1, 0), b3, voffB); PG8_STAGE(PG8_SB(1, 1), b3 + hstepB, voffB); PG8_STAGE(PG8_SA(1, 0), a3, voffA);
;             PG8_WAIT_V(8); PG8_WAIT_L(0); PG8_BAR; PG8_MMA(1, 0, At, B0); PG8_MMA(1, 1, At, B1); PG8_BAR; PG8_SCHED;
;     ...
;         if constexpr (ALIGN_EPI) { if (wr == 0) PG8_BAR; }
	s_add_i32 s0, s4, s13
	v_lshl_add_u64 v[230:231], v[230:231], 0, s[14:15]
	s_mov_b32 m0, s0
	ds_read_b128 v[190:193], v139 offset:49152
	ds_read_b128 v[194:197], v139 offset:50176
	ds_read_b128 v[198:201], v139 offset:51200
	ds_read_b128 v[202:205], v139 offset:52224
	ds_read_b128 v[214:217], v139 offset:53248
	ds_read_b128 v[218:221], v139 offset:54272
	ds_read_b128 v[222:225], v139 offset:55296
	ds_read_b128 v[226:229], v139 offset:56320
	global_load_lds_dwordx4 v[230:231], off
	s_add_i32 m0, s0, 0x2000
	s_add_u32 s0, s58, 0x40080
	v_lshl_add_u64 v[230:231], v[232:233], 0, s[14:15]
	s_addc_u32 s1, s59, 0
	s_add_i32 s4, s5, s13
	global_load_lds_dwordx4 v[230:231], off
	v_lshl_add_u64 v[230:231], s[0:1], 0, v[164:165]
	s_mov_b32 m0, s4
	s_nop 0
	global_load_lds_dwordx4 v[230:231], off
	v_lshl_add_u64 v[230:231], s[0:1], 0, v[132:133]
	s_add_i32 m0, s4, 0x2000
	s_nop 0
	global_load_lds_dwordx4 v[230:231], off
	v_lshl_add_u64 v[230:231], v[234:235], 0, s[14:15]
	s_mov_b32 m0, s9
	s_nop 0
	global_load_lds_dwordx4 v[230:231], off
	v_lshl_add_u64 v[230:231], v[236:237], 0, s[14:15]
	s_mov_b32 m0, s25
	s_nop 0
	global_load_lds_dwordx4 v[230:231], off
	s_waitcnt vmcnt(8)
	s_waitcnt lgkmcnt(0)
	s_barrier
	s_setprio 1
	s_waitcnt lgkmcnt(0)
	v_mfma_f32_16x16x32_bf16 v[60:63], v[140:143], v[190:193], v[60:63]
	v_mfma_f32_16x16x32_bf16 v[56:59], v[148:151], v[190:193], v[56:59]
	v_mfma_f32_16x16x32_bf16 v[52:55], v[140:143], v[198:201], v[52:55]
	v_mfma_f32_16x16x32_bf16 v[48:51], v[148:151], v[198:201], v[48:51]
	v_mfma_f32_16x16x32_bf16 v[36:39], v[140:143], v[214:217], v[36:39]
	v_mfma_f32_16x16x32_bf16 v[32:35], v[148:151], v[214:217], v[32:35]
	v_mfma_f32_16x16x32_bf16 v[20:23], v[140:143], v[222:225], v[20:23]
	v_mfma_f32_16x16x32_bf16 v[16:19], v[148:151], v[222:225], v[16:19]
	v_mfma_f32_16x16x32_bf16 v[60:63], v[144:147], v[194:197], v[60:63]
	v_mfma_f32_16x16x32_bf16 v[56:59], v[152:155], v[194:197], v[56:59]
	v_mfma_f32_16x16x32_bf16 v[52:55], v[144:147], v[202:205], v[52:55]
	v_mfma_f32_16x16x32_bf16 v[48:51], v[152:155], v[202:205], v[48:51]
	v_mfma_f32_16x16x32_bf16 v[36:39], v[144:147], v[218:221], v[36:39]
	v_mfma_f32_16x16x32_bf16 v[32:35], v[152:155], v[218:221], v[32:35]
	v_mfma_f32_16x16x32_bf16 v[20:23], v[144:147], v[226:229], v[20:23]
	v_mfma_f32_16x16x32_bf16 v[16:19], v[152:155], v[226:229], v[16:19]
	v_mfma_f32_16x16x32_bf16 v[44:47], v[156:159], v[190:193], v[44:47]
	v_mfma_f32_16x16x32_bf16 v[40:43], v[166:169], v[190:193], v[40:43]
	v_mfma_f32_16x16x32_bf16 v[28:31], v[156:159], v[198:201], v[28:31]
	v_mfma_f32_16x16x32_bf16 v[24:27], v[166:169], v[198:201], v[24:27]
	v_mfma_f32_16x16x32_bf16 v[12:15], v[156:159], v[214:217], v[12:15]
	v_mfma_f32_16x16x32_bf16 v[8:11], v[166:169], v[214:217], v[8:11]
	v_mfma_f32_16x16x32_bf16 v[4:7], v[156:159], v[222:225], v[4:7]
	v_mfma_f32_16x16x32_bf16 v[0:3], v[166:169], v[222:225], v[0:3]
	v_mfma_f32_16x16x32_bf16 v[44:47], v[160:163], v[194:197], v[44:47]
	v_mfma_f32_16x16x32_bf16 v[40:43], v[186:189], v[194:197], v[40:43]
	v_mfma_f32_16x16x32_bf16 v[28:31], v[160:163], v[202:205], v[28:31]
	v_mfma_f32_16x16x32_bf16 v[24:27], v[186:189], v[202:205], v[24:27]
	v_mfma_f32_16x16x32_bf16 v[12:15], v[160:163], v[218:221], v[12:15]
	v_mfma_f32_16x16x32_bf16 v[8:11], v[186:189], v[218:221], v[8:11]
	v_mfma_f32_16x16x32_bf16 v[4:7], v[160:163], v[226:229], v[4:7]
	v_mfma_f32_16x16x32_bf16 v[0:3], v[186:189], v[226:229], v[0:3]
	s_setprio 0
	s_barrier
	s_add_i32 s63, s63, 2
	s_add_u32 s61, s61, 0x100
	s_addc_u32 s62, s62, 0
	s_add_u32 s56, s56, 0x100
	s_addc_u32 s57, s57, 0
	s_cmp_gt_u32 s63, 13
	s_cbranch_scc0 .LBB0_1027
	s_and_b64 vcc, exec, s[40:41]
	s_cbranch_vccz .LBB0_1030
	s_barrier

; #define PG8_STAGE(bufoff, gbase, voff) do { _Pragma("unroll") for (int _i = 0; _i < 2; ++_i) \
;         __builtin_amdgcn_global_load_lds((const unsigned*)((const char*)(gbase) + (voff)[_i]), (PG8_LAS unsigned*)(lds + (bufoff) + ldsw + _i * 8192), 16, 0, 0); } while (0)
; #define PG8_LDA(dst, b, h) do { _Pragma("unroll") for (int m = 0; m < 4; ++m) _Pragma("unroll") for (int k = 0; k < 2; ++k) dst[m][k] = *(const PG8_LAS bf16x8*)(lds + PG8_SA(b, h) + aoff + m * 2048 + k * 1024); } while (0)
; #define PG8_LDB(dst, b, h) do { _Pragma("unroll") for (int n = 0; n < 2; ++n) _Pragma("unroll") for (int k = 0; k < 2; ++k) dst[n][k] = *(const PG8_LAS bf16x8*)(lds + PG8_SB(b, h) + boff + n * 2048 + k * 1024); } while (0)
; #define PG8_MMA(ai, bj, At, Bt) do { __builtin_amdgcn_s_setprio(1); _Pragma("unroll") for (int m = 0; m < 4; ++m) _Pragma("unroll") for (int n = 0; n < 2; ++n) _Pragma("unroll") for (int k = 0; k < 2; ++k) \
;         acc[ai][bj][m][n] = __builtin_amdgcn_mfma_f32_16x16x32_bf16(Bt[n][k], At[m][k], acc[ai][bj][m][n], 0, 0, 0); __builtin_amdgcn_s_setprio(0); } while (0)
; #define PG8_WAIT_V(n) asm volatile("s_waitcnt vmcnt(" #n ")" ::: "memory")
; #define PG8_WAIT_L(n) asm volatile("s_waitcnt lgkmcnt(" #n ")" ::: "memory")
; #define PG8_BAR __builtin_amdgcn_s_barrier()
; template <class Epi, class Sched, bool ALIGN_EPI = false, bool SP2 = false>
; __device__ __forceinline__ void gemm_phase(PG8_LAS unsigned char* lds, const Gemm g, const Sched& S, const Epi& E) {
;     ...
;             const char* a1 = cA + (size_t)(t + 1) * kstep;
;             const char* a2 = last ? nA : cA + (size_t)(t + 2) * kstep; const char* b2 = last ? nB : cB + (size_t)(t + 2) * kstep;
;             const char* a3 = a2 + kstep; const char* b3 = b2 + kstep;
;             if (last && has_next) S.a_ready(nxt);
;             if constexpr (SP2) {
;             PG8_LDB(B0, 0, 0); PG8_LDB(B1, 0, 1); PG8_SCHED; PG8_LDA(At, 0, 0); PG8_STAGE(PG8_SA(1, 1), a1 + hstepA, voffA);
;             PG8_WAIT_V(8); PG8_WAIT_L(0); PG8_BAR; PG8_MMA(0, 0, At, B0); PG8_MMA(0, 1, At, B1); PG8_BAR; PG8_SCHED;
;             PG8_LDA(At, 0, 1); PG8_STAGE(PG8_SB(0, 0), b2, voffB); PG8_STAGE(PG8_SB(0, 1), b2 + hstepB, voffB); PG8_STAGE(PG8_SA(0, 0), a2, voffA);
;             PG8_WAIT_V(8); PG8_WAIT_L(0); PG8_BAR; PG8_MMA(1, 0, At, B0); PG8_MMA(1, 1, At, B1); PG8_BAR; PG8_SCHED;
.LBB0_1047:
	s_add_u32 s4, s56, s0
	s_addc_u32 s5, s57, 0
	s_add_u32 s1, s4, 0x100
	s_addc_u32 s16, s5, 0
	s_and_b64 s[2:3], s[64:65], exec
	s_cselect_b32 s69, s59, s16
	s_cselect_b32 s68, s58, s1
	s_add_u32 s0, s48, s0
	s_addc_u32 s1, s49, 0
	s_add_u32 s2, s0, 0x100
	s_addc_u32 s3, s1, 0
	s_add_i32 s44, 0, 0x10000
	s_and_b64 s[0:1], s[64:65], exec
	s_cselect_b32 s71, s61, s3
	s_cselect_b32 s70, s60, s2
	s_add_i32 s45, 0, 0x14000
	s_add_u32 s0, s4, 0x40080
	s_addc_u32 s1, s5, 0
	s_add_i32 s41, s44, s10
	s_add_i32 m0, s13, 0xc000
	s_add_i32 s4, s13, 0xe000
	s_add_i32 s33, s41, 0x2000
	s_add_u32 s72, s70, 0x40000
	v_add_u32_e32 v146, s44, v132
	v_add_u32_e32 v162, s45, v132
	s_addc_u32 s73, s71, 0
	s_add_i32 s37, s45, s10
	ds_read_b128 v[134:137], v146
	ds_read_b128 v[138:141], v146 offset:1024
	ds_read_b128 v[142:145], v146 offset:2048
	ds_read_b128 v[146:149], v146 offset:3072
	ds_read_b128 v[150:153], v162
	ds_read_b128 v[154:157], v162 offset:1024
	ds_read_b128 v[158:161], v162 offset:2048
	ds_read_b128 v[166:169], v162 offset:3072
	s_add_i32 s36, s37, 0x2000
	s_add_i32 s17, 0, 0x18000
	s_add_i32 s16, 0, 0x1c000
	s_add_u32 s66, s68, 0x40000
	s_addc_u32 s67, s69, 0
	s_add_i32 s3, s17, s10
	s_add_i32 s2, s3, 0x2000
	s_add_u32 s64, s70, 0x40080
	s_addc_u32 s65, s71, 0
	s_add_i32 s45, s16, s10
	s_add_i32 s44, s45, 0x2000
	v_lshl_add_u64 v[162:163], s[0:1], 0, v[130:131]
	ds_read_b128 v[186:189], v133
	ds_read_b128 v[190:193], v133 offset:1024
	ds_read_b128 v[194:197], v133 offset:2048
	ds_read_b128 v[198:201], v133 offset:3072
	ds_read_b128 v[202:205], v133 offset:4096
	ds_read_b128 v[214:217], v133 offset:5120
	ds_read_b128 v[218:221], v133 offset:6144
	ds_read_b128 v[222:225], v133 offset:7168
	global_load_lds_dwordx4 v[162:163], off
	v_lshl_add_u64 v[162:163], s[0:1], 0, v[128:129]
	s_mov_b32 m0, s4
	s_nop 0
	global_load_lds_dwordx4 v[162:163], off
	s_waitcnt vmcnt(8)
	s_waitcnt lgkmcnt(0)
	s_barrier
	s_setprio 1
	s_waitcnt lgkmcnt(0)
	v_mfma_f32_16x16x32_bf16 v[124:127], v[134:137], v[186:189], v[124:127]
	v_mfma_f32_16x16x32_bf16 v[120:123], v[142:145], v[186:189], v[120:123]
	v_mfma_f32_16x16x32_bf16 v[116:119], v[134:137], v[194:197], v[116:119]
	v_mfma_f32_16x16x32_bf16 v[112:115], v[142:145], v[194:197], v[112:115]
	v_mfma_f32_16x16x32_bf16 v[108:111], v[134:137], v[202:205], v[108:111]
	v_mfma_f32_16x16x32_bf16 v[100:103], v[142:145], v[202:205], v[100:103]
	v_mfma_f32_16x16x32_bf16 v[92:95], v[134:137], v[218:221], v[92:95]
	v_mfma_f32_16x16x32_bf16 v[84:87], v[142:145], v[218:221], v[84:87]
	v_mfma_f32_16x16x32_bf16 v[124:127], v[138:141], v[190:193], v[124:127]
	v_mfma_f32_16x16x32_bf16 v[120:123], v[146:149], v[190:193], v[120:123]
	v_mfma_f32_16x16x32_bf16 v[116:119], v[138:141], v[198:201], v[116:119]
	v_mfma_f32_16x16x32_bf16 v[112:115], v[146:149], v[198:201], v[112:115]
	v_mfma_f32_16x16x32_bf16 v[108:111], v[138:141], v[214:217], v[108:111]
	v_mfma_f32_16x16x32_bf16 v[100:103], v[146:149], v[214:217], v[100:103]
	v_mfma_f32_16x16x32_bf16 v[92:95], v[138:141], v[222:225], v[92:95]
	v_mfma_f32_16x16x32_bf16 v[84:87], v[146:149], v[222:225], v[84:87]
	v_mfma_f32_16x16x32_bf16 v[104:107], v[150:153], v[186:189], v[104:107]
	v_mfma_f32_16x16x32_bf16 v[96:99], v[158:161], v[186:189], v[96:99]
	v_mfma_f32_16x16x32_bf16 v[88:91], v[150:153], v[194:197], v[88:91]
	v_mfma_f32_16x16x32_bf16 v[80:83], v[158:161], v[194:197], v[80:83]
	v_mfma_f32_16x16x32_bf16 v[76:79], v[150:153], v[202:205], v[76:79]
	v_mfma_f32_16x16x32_bf16 v[72:75], v[158:161], v[202:205], v[72:75]
	v_mfma_f32_16x16x32_bf16 v[68:71], v[150:153], v[218:221], v[68:71]
	v_mfma_f32_16x16x32_bf16 v[64:67], v[158:161], v[218:221], v[64:67]
	v_mfma_f32_16x16x32_bf16 v[104:107], v[154:157], v[190:193], v[104:107]
	v_mfma_f32_16x16x32_bf16 v[96:99], v[166:169], v[190:193], v[96:99]
	v_mfma_f32_16x16x32_bf16 v[88:91], v[154:157], v[198:201], v[88:91]
	v_mfma_f32_16x16x32_bf16 v[80:83], v[166:169], v[198:201], v[80:83]
	v_mfma_f32_16x16x32_bf16 v[76:79], v[154:157], v[214:217], v[76:79]
	v_mfma_f32_16x16x32_bf16 v[72:75], v[166:169], v[214:217], v[72:75]
	v_mfma_f32_16x16x32_bf16 v[68:71], v[154:157], v[222:225], v[68:71]
	v_mfma_f32_16x16x32_bf16 v[64:67], v[166:169], v[222:225], v[64:67]
	s_setprio 0
	s_barrier
	s_mov_b32 m0, s41
	v_lshl_add_u64 v[162:163], s[70:71], 0, v[130:131]
	ds_read_b128 v[186:189], v133 offset:16384
	ds_read_b128 v[190:193], v133 offset:17408
	ds_read_b128 v[194:197], v133 offset:18432
	ds_read_b128 v[198:201], v133 offset:19456
	ds_read_b128 v[202:205], v133 offset:20480
	ds_read_b128 v[214:217], v133 offset:21504
	ds_read_b128 v[218:221], v133 offset:22528
	ds_read_b128 v[222:225], v133 offset:23552
	global_load_lds_dwordx4 v[162:163], off
	v_lshl_add_u64 v[226:227], s[70:71], 0, v[128:129]
	s_mov_b32 m0, s33
	v_lshl_add_u64 v[228:229], s[72:73], 0, v[130:131]
	global_load_lds_dwordx4 v[226:227], off
	s_mov_b32 m0, s37
	v_lshl_add_u64 v[230:231], s[68:69], 0, v[128:129]
	global_load_lds_dwordx4 v[228:229], off
	v_lshl_add_u64 v[228:229], s[72:73], 0, v[128:129]
	s_mov_b32 m0, s36
	s_nop 0
	global_load_lds_dwordx4 v[228:229], off
	v_lshl_add_u64 v[228:229], s[68:69], 0, v[130:131]
	s_mov_b32 m0, s13
	s_nop 0
	global_load_lds_dwordx4 v[228:229], off
	s_mov_b32 m0, s18
	s_nop 0
	global_load_lds_dwordx4 v[230:231], off
	s_waitcnt vmcnt(8)
	s_waitcnt lgkmcnt(0)
	s_barrier
; #define PG8_STAGE(bufoff, gbase, voff) do { _Pragma("unroll") for (int _i = 0; _i < 2; ++_i) \
;         __builtin_amdgcn_global_load_lds((const unsigned*)((const char*)(gbase) + (voff)[_i]), (PG8_LAS unsigned*)(lds + (bufoff) + ldsw + _i * 8192), 16, 0, 0); } while (0)
; #define PG8_LDA(dst, b, h) do { _Pragma("unroll") for (int m = 0; m < 4; ++m) _Pragma("unroll") for (int k = 0; k < 2; ++k) dst[m][k] = *(const PG8_LAS bf16x8*)(lds + PG8_SA(b, h) + aoff + m * 2048 + k * 1024); } while (0)
; #define PG8_LDB(dst, b, h) do { _Pragma("unroll") for (int n = 0; n < 2; ++n) _Pragma("unroll") for (int k = 0; k < 2; ++k) dst[n][k] = *(const PG8_LAS bf16x8*)(lds + PG8_SB(b, h) + boff + n * 2048 + k * 1024); } while (0)
; #define PG8_MMA(ai, bj, At, Bt) do { __builtin_amdgcn_s_setprio(1); _Pragma("unroll") for (int m = 0; m < 4; ++m) _Pragma("unroll") for (int n = 0; n < 2; ++n) _Pragma("unroll") for (int k = 0; k < 2; ++k) \
;         acc[ai][bj][m][n] = __builtin_amdgcn_mfma_f32_16x16x32_bf16(Bt[n][k], At[m][k], acc[ai][bj][m][n], 0, 0, 0); __builtin_amdgcn_s_setprio(0); } while (0)
; #define PG8_WAIT_V(n) asm volatile("s_waitcnt vmcnt(" #n ")" ::: "memory")
; #define PG8_WAIT_L(n) asm volatile("s_waitcnt lgkmcnt(" #n ")" ::: "memory")
; #define PG8_BAR __builtin_amdgcn_s_barrier()
; #define PG8_SCHED __builtin_amdgcn_sched_barrier(0)
; template <class Epi, class Sched, bool ALIGN_EPI = false, bool SP2 = false>
; __device__ __forceinline__ void gemm_phase(PG8_LAS unsigned char* lds, const Gemm g, const Sched& S, const Epi& E) {
;     ...
;             PG8_WAIT_V(8); PG8_WAIT_L(0); PG8_BAR; PG8_MMA(1, 0, At, B0); PG8_MMA(1, 1, At, B1); PG8_BAR; PG8_SCHED;
;             PG8_LDB(B0, 1, 0); PG8_LDB(B1, 1, 1); PG8_SCHED; PG8_LDA(At, 1, 0); PG8_STAGE(PG8_SA(0, 1), a2 + hstepA, voffA);
;             PG8_WAIT_V(8); PG8_WAIT_L(0); PG8_BAR; PG8_MMA(0, 0, At, B0); PG8_MMA(0, 1, At, B1); PG8_BAR; PG8_SCHED;
	s_setprio 1
	s_waitcnt lgkmcnt(0)
	v_mfma_f32_16x16x32_bf16 v[60:63], v[134:137], v[186:189], v[60:63]
	v_mfma_f32_16x16x32_bf16 v[56:59], v[142:145], v[186:189], v[56:59]
	v_mfma_f32_16x16x32_bf16 v[52:55], v[134:137], v[194:197], v[52:55]
	v_mfma_f32_16x16x32_bf16 v[48:51], v[142:145], v[194:197], v[48:51]
	v_mfma_f32_16x16x32_bf16 v[40:43], v[134:137], v[202:205], v[40:43]
	v_mfma_f32_16x16x32_bf16 v[32:35], v[142:145], v[202:205], v[32:35]
	v_mfma_f32_16x16x32_bf16 v[24:27], v[134:137], v[218:221], v[24:27]
	v_mfma_f32_16x16x32_bf16 v[16:19], v[142:145], v[218:221], v[16:19]
	v_mfma_f32_16x16x32_bf16 v[60:63], v[138:141], v[190:193], v[60:63]
	v_mfma_f32_16x16x32_bf16 v[56:59], v[146:149], v[190:193], v[56:59]
	v_mfma_f32_16x16x32_bf16 v[52:55], v[138:141], v[198:201], v[52:55]
	v_mfma_f32_16x16x32_bf16 v[48:51], v[146:149], v[198:201], v[48:51]
	v_mfma_f32_16x16x32_bf16 v[40:43], v[138:141], v[214:217], v[40:43]
	v_mfma_f32_16x16x32_bf16 v[32:35], v[146:149], v[214:217], v[32:35]
	v_mfma_f32_16x16x32_bf16 v[24:27], v[138:141], v[222:225], v[24:27]
	v_mfma_f32_16x16x32_bf16 v[16:19], v[146:149], v[222:225], v[16:19]
	v_mfma_f32_16x16x32_bf16 v[44:47], v[150:153], v[186:189], v[44:47]
	v_mfma_f32_16x16x32_bf16 v[36:39], v[158:161], v[186:189], v[36:39]
	v_mfma_f32_16x16x32_bf16 v[28:31], v[150:153], v[194:197], v[28:31]
	v_mfma_f32_16x16x32_bf16 v[20:23], v[158:161], v[194:197], v[20:23]
	v_mfma_f32_16x16x32_bf16 v[12:15], v[150:153], v[202:205], v[12:15]
	v_mfma_f32_16x16x32_bf16 v[8:11], v[158:161], v[202:205], v[8:11]
	v_mfma_f32_16x16x32_bf16 v[4:7], v[150:153], v[218:221], v[4:7]
	v_mfma_f32_16x16x32_bf16 v[0:3], v[158:161], v[218:221], v[0:3]
	v_mfma_f32_16x16x32_bf16 v[44:47], v[154:157], v[190:193], v[44:47]
	v_mfma_f32_16x16x32_bf16 v[36:39], v[166:169], v[190:193], v[36:39]
	v_mfma_f32_16x16x32_bf16 v[28:31], v[154:157], v[198:201], v[28:31]
	v_mfma_f32_16x16x32_bf16 v[20:23], v[166:169], v[198:201], v[20:23]
	v_mfma_f32_16x16x32_bf16 v[12:15], v[154:157], v[214:217], v[12:15]
	v_mfma_f32_16x16x32_bf16 v[8:11], v[166:169], v[214:217], v[8:11]
	v_mfma_f32_16x16x32_bf16 v[4:7], v[154:157], v[222:225], v[4:7]
	v_mfma_f32_16x16x32_bf16 v[0:3], v[166:169], v[222:225], v[0:3]
	s_setprio 0
	s_barrier
	v_add_u32_e32 v146, s17, v132
	v_add_u32_e32 v164, s16, v132
	ds_read_b128 v[134:137], v146
	ds_read_b128 v[138:141], v146 offset:1024
	ds_read_b128 v[142:145], v146 offset:2048
	ds_read_b128 v[146:149], v146 offset:3072
	ds_read_b128 v[150:153], v164
	ds_read_b128 v[154:157], v164 offset:1024
	ds_read_b128 v[158:161], v164 offset:2048
	ds_read_b128 v[166:169], v164 offset:3072
	s_mov_b32 m0, s19
	v_lshl_add_u64 v[232:233], s[66:67], 0, v[130:131]
	ds_read_b128 v[186:189], v133 offset:32768
	ds_read_b128 v[190:193], v133 offset:33792
	ds_read_b128 v[194:197], v133 offset:34816
	ds_read_b128 v[198:201], v133 offset:35840
	ds_read_b128 v[202:205], v133 offset:36864
	ds_read_b128 v[214:217], v133 offset:37888
	ds_read_b128 v[218:221], v133 offset:38912
	ds_read_b128 v[222:225], v133 offset:39936
	global_load_lds_dwordx4 v[232:233], off
	v_lshl_add_u64 v[232:233], s[66:67], 0, v[128:129]
	s_mov_b32 m0, s24
	s_nop 0
	global_load_lds_dwordx4 v[232:233], off
	s_waitcnt vmcnt(8)
	s_waitcnt lgkmcnt(0)
	s_barrier
	s_setprio 1
	s_waitcnt lgkmcnt(0)
	v_mfma_f32_16x16x32_bf16 v[124:127], v[134:137], v[186:189], v[124:127]
	v_mfma_f32_16x16x32_bf16 v[120:123], v[142:145], v[186:189], v[120:123]
	v_mfma_f32_16x16x32_bf16 v[116:119], v[134:137], v[194:197], v[116:119]
	v_mfma_f32_16x16x32_bf16 v[112:115], v[142:145], v[194:197], v[112:115]
	v_mfma_f32_16x16x32_bf16 v[108:111], v[134:137], v[202:205], v[108:111]
	v_mfma_f32_16x16x32_bf16 v[100:103], v[142:145], v[202:205], v[100:103]
	v_mfma_f32_16x16x32_bf16 v[92:95], v[134:137], v[218:221], v[92:95]
	v_mfma_f32_16x16x32_bf16 v[84:87], v[142:145], v[218:221], v[84:87]
	v_mfma_f32_16x16x32_bf16 v[124:127], v[138:141], v[190:193], v[124:127]
	v_mfma_f32_16x16x32_bf16 v[120:123], v[146:149], v[190:193], v[120:123]
	v_mfma_f32_16x16x32_bf16 v[116:119], v[138:141], v[198:201], v[116:119]
	v_mfma_f32_16x16x32_bf16 v[112:115], v[146:149], v[198:201], v[112:115]
	v_mfma_f32_16x16x32_bf16 v[108:111], v[138:141], v[214:217], v[108:111]
	v_mfma_f32_16x16x32_bf16 v[100:103], v[146:149], v[214:217], v[100:103]
	v_mfma_f32_16x16x32_bf16 v[92:95], v[138:141], v[222:225], v[92:95]
	v_mfma_f32_16x16x32_bf16 v[84:87], v[146:149], v[222:225], v[84:87]
	v_mfma_f32_16x16x32_bf16 v[104:107], v[150:153], v[186:189], v[104:107]
	v_mfma_f32_16x16x32_bf16 v[96:99], v[158:161], v[186:189], v[96:99]
	v_mfma_f32_16x16x32_bf16 v[88:91], v[150:153], v[194:197], v[88:91]
	v_mfma_f32_16x16x32_bf16 v[80:83], v[158:161], v[194:197], v[80:83]
	v_mfma_f32_16x16x32_bf16 v[76:79], v[150:153], v[202:205], v[76:79]
	v_mfma_f32_16x16x32_bf16 v[72:75], v[158:161], v[202:205], v[72:75]
	v_mfma_f32_16x16x32_bf16 v[68:71], v[150:153], v[218:221], v[68:71]
	v_mfma_f32_16x16x32_bf16 v[64:67], v[158:161], v[218:221], v[64:67]
	v_mfma_f32_16x16x32_bf16 v[104:107], v[154:157], v[190:193], v[104:107]
	v_mfma_f32_16x16x32_bf16 v[96:99], v[166:169], v[190:193], v[96:99]
	v_mfma_f32_16x16x32_bf16 v[88:91], v[154:157], v[198:201], v[88:91]
	v_mfma_f32_16x16x32_bf16 v[80:83], v[166:169], v[198:201], v[80:83]
	v_mfma_f32_16x16x32_bf16 v[76:79], v[154:157], v[214:217], v[76:79]
	v_mfma_f32_16x16x32_bf16 v[72:75], v[166:169], v[214:217], v[72:75]
	v_mfma_f32_16x16x32_bf16 v[68:71], v[154:157], v[222:225], v[68:71]
	v_mfma_f32_16x16x32_bf16 v[64:67], v[166:169], v[222:225], v[64:67]
	s_setprio 0
	s_barrier
; #define PG8_STAGE(bufoff, gbase, voff) do { _Pragma("unroll") for (int _i = 0; _i < 2; ++_i) \
;         __builtin_amdgcn_global_load_lds((const unsigned*)((const char*)(gbase) + (voff)[_i]), (PG8_LAS unsigned*)(lds + (bufoff) + ldsw + _i * 8192), 16, 0, 0); } while (0)
; #define PG8_LDA(dst, b, h) do { _Pragma("unroll") for (int m = 0; m < 4; ++m) _Pragma("unroll") for (int k = 0; k < 2; ++k) dst[m][k] = *(const PG8_LAS bf16x8*)(lds + PG8_SA(b, h) + aoff + m * 2048 + k * 1024); } while (0)
; #define PG8_MMA(ai, bj, At, Bt) do { __builtin_amdgcn_s_setprio(1); _Pragma("unroll") for (int m = 0; m < 4; ++m) _Pragma("unroll") for (int n = 0; n < 2; ++n) _Pragma("unroll") for (int k = 0; k < 2; ++k) \
;         acc[ai][bj][m][n] = __builtin_amdgcn_mfma_f32_16x16x32_bf16(Bt[n][k], At[m][k], acc[ai][bj][m][n], 0, 0, 0); __builtin_amdgcn_s_setprio(0); } while (0)
; #define PG8_WAIT_V(n) asm volatile("s_waitcnt vmcnt(" #n ")" ::: "memory")
; #define PG8_WAIT_L(n) asm volatile("s_waitcnt lgkmcnt(" #n ")" ::: "memory")
; #define PG8_BAR __builtin_amdgcn_s_barrier()
; #define PG8_SCHED __builtin_amdgcn_sched_barrier(0)
; template <class Epi, class Sched, bool ALIGN_EPI = false, bool SP2 = false>
; __device__ __forceinline__ void gemm_phase(PG8_LAS unsigned char* lds, const Gemm g, const Sched& S, const Epi& E) {
;     ...
;             PG8_LDA(At, 1, 1); PG8_STAGE(PG8_SB(1, 0), b3, voffB); PG8_STAGE(PG8_SB(1, 1), b3 + hstepB, voffB); PG8_STAGE(PG8_SA(1, 0), a3, voffA);
;             PG8_WAIT_V(8); PG8_WAIT_L(0); PG8_BAR; PG8_MMA(1, 0, At, B0); PG8_MMA(1, 1, At, B1); PG8_BAR; PG8_SCHED;
;     ...
;         if constexpr (ALIGN_EPI) { if (wr == 0) PG8_BAR; }
	s_mov_b32 m0, s3
	v_lshl_add_u64 v[162:163], v[162:163], 0, s[14:15]
	ds_read_b128 v[186:189], v133 offset:49152
	ds_read_b128 v[190:193], v133 offset:50176
	ds_read_b128 v[194:197], v133 offset:51200
	ds_read_b128 v[198:201], v133 offset:52224
	ds_read_b128 v[202:205], v133 offset:53248
	ds_read_b128 v[214:217], v133 offset:54272
	ds_read_b128 v[218:221], v133 offset:55296
	ds_read_b128 v[222:225], v133 offset:56320
	global_load_lds_dwordx4 v[162:163], off
	v_lshl_add_u64 v[162:163], v[226:227], 0, s[14:15]
	s_mov_b32 m0, s2
	s_nop 0
	global_load_lds_dwordx4 v[162:163], off
	v_lshl_add_u64 v[162:163], s[64:65], 0, v[130:131]
	s_mov_b32 m0, s45
	s_nop 0
	global_load_lds_dwordx4 v[162:163], off
	v_lshl_add_u64 v[162:163], s[64:65], 0, v[128:129]
	s_mov_b32 m0, s44
	s_nop 0
	global_load_lds_dwordx4 v[162:163], off
	v_lshl_add_u64 v[162:163], v[228:229], 0, s[14:15]
	s_mov_b32 m0, s46
	s_nop 0
	global_load_lds_dwordx4 v[162:163], off
	v_lshl_add_u64 v[162:163], v[230:231], 0, s[14:15]
	s_mov_b32 m0, s47
	s_nop 0
	global_load_lds_dwordx4 v[162:163], off
	s_waitcnt vmcnt(8)
	s_waitcnt lgkmcnt(0)
	s_barrier
	s_setprio 1
	s_waitcnt lgkmcnt(0)
	v_mfma_f32_16x16x32_bf16 v[60:63], v[134:137], v[186:189], v[60:63]
	v_mfma_f32_16x16x32_bf16 v[56:59], v[142:145], v[186:189], v[56:59]
	v_mfma_f32_16x16x32_bf16 v[52:55], v[134:137], v[194:197], v[52:55]
	v_mfma_f32_16x16x32_bf16 v[48:51], v[142:145], v[194:197], v[48:51]
	v_mfma_f32_16x16x32_bf16 v[40:43], v[134:137], v[202:205], v[40:43]
	v_mfma_f32_16x16x32_bf16 v[32:35], v[142:145], v[202:205], v[32:35]
	v_mfma_f32_16x16x32_bf16 v[24:27], v[134:137], v[218:221], v[24:27]
	v_mfma_f32_16x16x32_bf16 v[16:19], v[142:145], v[218:221], v[16:19]
	v_mfma_f32_16x16x32_bf16 v[60:63], v[138:141], v[190:193], v[60:63]
	v_mfma_f32_16x16x32_bf16 v[56:59], v[146:149], v[190:193], v[56:59]
	v_mfma_f32_16x16x32_bf16 v[52:55], v[138:141], v[198:201], v[52:55]
	v_mfma_f32_16x16x32_bf16 v[48:51], v[146:149], v[198:201], v[48:51]
	v_mfma_f32_16x16x32_bf16 v[40:43], v[138:141], v[214:217], v[40:43]
	v_mfma_f32_16x16x32_bf16 v[32:35], v[146:149], v[214:217], v[32:35]
	v_mfma_f32_16x16x32_bf16 v[24:27], v[138:141], v[222:225], v[24:27]
	v_mfma_f32_16x16x32_bf16 v[16:19], v[146:149], v[222:225], v[16:19]
	v_mfma_f32_16x16x32_bf16 v[44:47], v[150:153], v[186:189], v[44:47]
	v_mfma_f32_16x16x32_bf16 v[36:39], v[158:161], v[186:189], v[36:39]
	v_mfma_f32_16x16x32_bf16 v[28:31], v[150:153], v[194:197], v[28:31]
	v_mfma_f32_16x16x32_bf16 v[20:23], v[158:161], v[194:197], v[20:23]
	v_mfma_f32_16x16x32_bf16 v[12:15], v[150:153], v[202:205], v[12:15]
	v_mfma_f32_16x16x32_bf16 v[8:11], v[158:161], v[202:205], v[8:11]
	v_mfma_f32_16x16x32_bf16 v[4:7], v[150:153], v[218:221], v[4:7]
	v_mfma_f32_16x16x32_bf16 v[0:3], v[158:161], v[218:221], v[0:3]
	v_mfma_f32_16x16x32_bf16 v[44:47], v[154:157], v[190:193], v[44:47]
	v_mfma_f32_16x16x32_bf16 v[36:39], v[166:169], v[190:193], v[36:39]
	v_mfma_f32_16x16x32_bf16 v[28:31], v[154:157], v[198:201], v[28:31]
	v_mfma_f32_16x16x32_bf16 v[20:23], v[166:169], v[198:201], v[20:23]
	v_mfma_f32_16x16x32_bf16 v[12:15], v[154:157], v[214:217], v[12:15]
	v_mfma_f32_16x16x32_bf16 v[8:11], v[166:169], v[214:217], v[8:11]
	v_mfma_f32_16x16x32_bf16 v[4:7], v[154:157], v[222:225], v[4:7]
	v_mfma_f32_16x16x32_bf16 v[0:3], v[166:169], v[222:225], v[0:3]
	s_setprio 0
	s_barrier
	s_movk_i32 s0, 0x100
	s_andn2_b64 vcc, exec, s[62:63]
	s_mov_b64 s[64:65], -1
	s_mov_b64 s[62:63], 0
	s_cbranch_vccz .LBB0_1047
	s_and_b64 vcc, exec, s[30:31]
	s_cbranch_vccz .LBB0_1050
	s_barrier

; #define PG8_STAGE(bufoff, gbase, voff) do { _Pragma("unroll") for (int _i = 0; _i < 2; ++_i) \
;         __builtin_amdgcn_global_load_lds((const unsigned*)((const char*)(gbase) + (voff)[_i]), (PG8_LAS unsigned*)(lds + (bufoff) + ldsw + _i * 8192), 16, 0, 0); } while (0)
; #define PG8_LDA(dst, b, h) do { _Pragma("unroll") for (int m = 0; m < 4; ++m) _Pragma("unroll") for (int k = 0; k < 2; ++k) dst[m][k] = *(const PG8_LAS bf16x8*)(lds + PG8_SA(b, h) + aoff + m * 2048 + k * 1024); } while (0)
; #define PG8_LDB(dst, b, h) do { _Pragma("unroll") for (int n = 0; n < 2; ++n) _Pragma("unroll") for (int k = 0; k < 2; ++k) dst[n][k] = *(const PG8_LAS bf16x8*)(lds + PG8_SB(b, h) + boff + n * 2048 + k * 1024); } while (0)
; #define PG8_MMA(ai, bj, At, Bt) do { __builtin_amdgcn_s_setprio(1); _Pragma("unroll") for (int m = 0; m < 4; ++m) _Pragma("unroll") for (int n = 0; n < 2; ++n) _Pragma("unroll") for (int k = 0; k < 2; ++k) \
;         acc[ai][bj][m][n] = __builtin_amdgcn_mfma_f32_16x16x32_bf16(Bt[n][k], At[m][k], acc[ai][bj][m][n], 0, 0, 0); __builtin_amdgcn_s_setprio(0); } while (0)
; #define PG8_WAIT_V(n) asm volatile("s_waitcnt vmcnt(" #n ")" ::: "memory")
; #define PG8_WAIT_L(n) asm volatile("s_waitcnt lgkmcnt(" #n ")" ::: "memory")
; #define PG8_BAR __builtin_amdgcn_s_barrier()
; template <class Epi, class Sched, bool ALIGN_EPI = false, bool SP2 = false>
; __device__ __forceinline__ void gemm_phase(PG8_LAS unsigned char* lds, const Gemm g, const Sched& S, const Epi& E) {
;     ...
;             const char* a1 = cA + (size_t)(t + 1) * kstep;
;             const char* a2 = last ? nA : cA + (size_t)(t + 2) * kstep; const char* b2 = last ? nB : cB + (size_t)(t + 2) * kstep;
;             const char* a3 = a2 + kstep; const char* b3 = b2 + kstep;
;             if (last && has_next) S.a_ready(nxt);
;             if constexpr (SP2) {
;             PG8_LDB(B0, 0, 0); PG8_LDB(B1, 0, 1); PG8_SCHED; PG8_LDA(At, 0, 0); PG8_STAGE(PG8_SA(1, 1), a1 + hstepA, voffA);
;             PG8_WAIT_V(8); PG8_WAIT_L(0); PG8_BAR; PG8_MMA(0, 0, At, B0); PG8_MMA(0, 1, At, B1); PG8_BAR; PG8_SCHED;
;             PG8_LDA(At, 0, 1); PG8_STAGE(PG8_SB(0, 0), b2, voffB); PG8_STAGE(PG8_SB(0, 1), b2 + hstepB, voffB); PG8_STAGE(PG8_SA(0, 0), a2, voffA);
;             PG8_WAIT_V(8); PG8_WAIT_L(0); PG8_BAR; PG8_MMA(1, 0, At, B0); PG8_MMA(1, 1, At, B1); PG8_BAR; PG8_SCHED;
.LBB0_1218:
	s_add_u32 s0, s48, 0xfffc0080
	s_addc_u32 s1, s49, -1
	s_add_i32 s4, 0, 0x10000
	s_cmp_eq_u32 s18, 12
	s_cselect_b32 s1, s9, s1
	s_cselect_b32 s0, s10, s0
	s_cselect_b32 s51, s12, s17
	s_cselect_b32 s50, s13, s16
	s_add_i32 s5, 0, 0x14000
	v_add_u32_e32 v152, s4, v146
	v_add_u32_e32 v186, s5, v146
	ds_read_b128 v[138:141], v152
	ds_read_b128 v[142:145], v152 offset:1024
	ds_read_b128 v[148:151], v152 offset:2048
	ds_read_b128 v[152:155], v152 offset:3072
	ds_read_b128 v[156:159], v186
	ds_read_b128 v[160:163], v186 offset:1024
	ds_read_b128 v[166:169], v186 offset:2048
	ds_read_b128 v[186:189], v186 offset:3072
	v_lshl_add_u64 v[230:231], s[48:49], 0, v[136:137]
	s_add_i32 m0, s56, 0xc000
	ds_read_b128 v[190:193], v147
	ds_read_b128 v[194:197], v147 offset:1024
	ds_read_b128 v[198:201], v147 offset:2048
	ds_read_b128 v[202:205], v147 offset:3072
	ds_read_b128 v[214:217], v147 offset:4096
	ds_read_b128 v[218:221], v147 offset:5120
	ds_read_b128 v[222:225], v147 offset:6144
	ds_read_b128 v[226:229], v147 offset:7168
	global_load_lds_dwordx4 v[230:231], off
	v_lshl_add_u64 v[230:231], s[48:49], 0, v[134:135]
	s_add_i32 m0, s56, 0xe000
	s_nop 0
	global_load_lds_dwordx4 v[230:231], off
	s_waitcnt vmcnt(8)
	s_waitcnt lgkmcnt(0)
	s_barrier
	s_setprio 1
	s_waitcnt lgkmcnt(0)
	v_mfma_f32_16x16x32_bf16 v[124:127], v[138:141], v[190:193], v[124:127]
	v_mfma_f32_16x16x32_bf16 v[120:123], v[148:151], v[190:193], v[120:123]
	v_mfma_f32_16x16x32_bf16 v[108:111], v[138:141], v[198:201], v[108:111]
	v_mfma_f32_16x16x32_bf16 v[104:107], v[148:151], v[198:201], v[104:107]
	v_mfma_f32_16x16x32_bf16 v[92:95], v[138:141], v[214:217], v[92:95]
	v_mfma_f32_16x16x32_bf16 v[88:91], v[148:151], v[214:217], v[88:91]
	v_mfma_f32_16x16x32_bf16 v[76:79], v[138:141], v[222:225], v[76:79]
	v_mfma_f32_16x16x32_bf16 v[72:75], v[148:151], v[222:225], v[72:75]
	v_mfma_f32_16x16x32_bf16 v[124:127], v[142:145], v[194:197], v[124:127]
	v_mfma_f32_16x16x32_bf16 v[120:123], v[152:155], v[194:197], v[120:123]
	v_mfma_f32_16x16x32_bf16 v[108:111], v[142:145], v[202:205], v[108:111]
	v_mfma_f32_16x16x32_bf16 v[104:107], v[152:155], v[202:205], v[104:107]
	v_mfma_f32_16x16x32_bf16 v[92:95], v[142:145], v[218:221], v[92:95]
	v_mfma_f32_16x16x32_bf16 v[88:91], v[152:155], v[218:221], v[88:91]
	v_mfma_f32_16x16x32_bf16 v[76:79], v[142:145], v[226:229], v[76:79]
	v_mfma_f32_16x16x32_bf16 v[72:75], v[152:155], v[226:229], v[72:75]
	v_mfma_f32_16x16x32_bf16 v[116:119], v[156:159], v[190:193], v[116:119]
	v_mfma_f32_16x16x32_bf16 v[112:115], v[166:169], v[190:193], v[112:115]
	v_mfma_f32_16x16x32_bf16 v[100:103], v[156:159], v[198:201], v[100:103]
	v_mfma_f32_16x16x32_bf16 v[96:99], v[166:169], v[198:201], v[96:99]
	v_mfma_f32_16x16x32_bf16 v[84:87], v[156:159], v[214:217], v[84:87]
	v_mfma_f32_16x16x32_bf16 v[80:83], v[166:169], v[214:217], v[80:83]
	v_mfma_f32_16x16x32_bf16 v[68:71], v[156:159], v[222:225], v[68:71]
	v_mfma_f32_16x16x32_bf16 v[64:67], v[166:169], v[222:225], v[64:67]
	v_mfma_f32_16x16x32_bf16 v[116:119], v[160:163], v[194:197], v[116:119]
	v_mfma_f32_16x16x32_bf16 v[112:115], v[186:189], v[194:197], v[112:115]
	v_mfma_f32_16x16x32_bf16 v[100:103], v[160:163], v[202:205], v[100:103]
	v_mfma_f32_16x16x32_bf16 v[96:99], v[186:189], v[202:205], v[96:99]
	v_mfma_f32_16x16x32_bf16 v[84:87], v[160:163], v[218:221], v[84:87]
	v_mfma_f32_16x16x32_bf16 v[80:83], v[186:189], v[218:221], v[80:83]
	v_mfma_f32_16x16x32_bf16 v[68:71], v[160:163], v[226:229], v[68:71]
	v_mfma_f32_16x16x32_bf16 v[64:67], v[186:189], v[226:229], v[64:67]
	s_setprio 0
	s_barrier
	s_add_i32 s4, s4, s54
	v_lshl_add_u64 v[230:231], s[50:51], 0, v[164:165]
	s_mov_b32 m0, s4
	ds_read_b128 v[190:193], v147 offset:16384
	ds_read_b128 v[194:197], v147 offset:17408
	ds_read_b128 v[198:201], v147 offset:18432
	ds_read_b128 v[202:205], v147 offset:19456
	ds_read_b128 v[214:217], v147 offset:20480
	ds_read_b128 v[218:221], v147 offset:21504
	ds_read_b128 v[222:225], v147 offset:22528
	ds_read_b128 v[226:229], v147 offset:23552
	global_load_lds_dwordx4 v[230:231], off
	s_add_i32 m0, s4, 0x2000
	s_add_u32 s24, s50, 0x40000
	v_lshl_add_u64 v[232:233], s[50:51], 0, v[128:129]
	s_addc_u32 s25, s51, 0
	s_add_i32 s4, s5, s54
	global_load_lds_dwordx4 v[232:233], off
	v_lshl_add_u64 v[234:235], s[24:25], 0, v[164:165]
	s_mov_b32 m0, s4
	v_lshl_add_u64 v[236:237], s[0:1], 0, v[130:131]
	global_load_lds_dwordx4 v[234:235], off
	v_lshl_add_u64 v[234:235], s[24:25], 0, v[128:129]
	s_add_i32 m0, s4, 0x2000
	s_nop 0
	global_load_lds_dwordx4 v[234:235], off
	v_lshl_add_u64 v[234:235], s[0:1], 0, v[132:133]
	s_mov_b32 m0, s56
	s_nop 0
	global_load_lds_dwordx4 v[234:235], off
	s_mov_b32 m0, s57
	s_nop 0
	global_load_lds_dwordx4 v[236:237], off
	s_waitcnt vmcnt(8)
	s_waitcnt lgkmcnt(0)
	s_barrier
; #define PG8_STAGE(bufoff, gbase, voff) do { _Pragma("unroll") for (int _i = 0; _i < 2; ++_i) \
;         __builtin_amdgcn_global_load_lds((const unsigned*)((const char*)(gbase) + (voff)[_i]), (PG8_LAS unsigned*)(lds + (bufoff) + ldsw + _i * 8192), 16, 0, 0); } while (0)
; #define PG8_LDA(dst, b, h) do { _Pragma("unroll") for (int m = 0; m < 4; ++m) _Pragma("unroll") for (int k = 0; k < 2; ++k) dst[m][k] = *(const PG8_LAS bf16x8*)(lds + PG8_SA(b, h) + aoff + m * 2048 + k * 1024); } while (0)
; #define PG8_LDB(dst, b, h) do { _Pragma("unroll") for (int n = 0; n < 2; ++n) _Pragma("unroll") for (int k = 0; k < 2; ++k) dst[n][k] = *(const PG8_LAS bf16x8*)(lds + PG8_SB(b, h) + boff + n * 2048 + k * 1024); } while (0)
; #define PG8_MMA(ai, bj, At, Bt) do { __builtin_amdgcn_s_setprio(1); _Pragma("unroll") for (int m = 0; m < 4; ++m) _Pragma("unroll") for (int n = 0; n < 2; ++n) _Pragma("unroll") for (int k = 0; k < 2; ++k) \
;         acc[ai][bj][m][n] = __builtin_amdgcn_mfma_f32_16x16x32_bf16(Bt[n][k], At[m][k], acc[ai][bj][m][n], 0, 0, 0); __builtin_amdgcn_s_setprio(0); } while (0)
; #define PG8_WAIT_V(n) asm volatile("s_waitcnt vmcnt(" #n ")" ::: "memory")
; #define PG8_WAIT_L(n) asm volatile("s_waitcnt lgkmcnt(" #n ")" ::: "memory")
; #define PG8_BAR __builtin_amdgcn_s_barrier()
; #define PG8_SCHED __builtin_amdgcn_sched_barrier(0)
; template <class Epi, class Sched, bool ALIGN_EPI = false, bool SP2 = false>
; __device__ __forceinline__ void gemm_phase(PG8_LAS unsigned char* lds, const Gemm g, const Sched& S, const Epi& E) {
;     ...
;             PG8_WAIT_V(8); PG8_WAIT_L(0); PG8_BAR; PG8_MMA(1, 0, At, B0); PG8_MMA(1, 1, At, B1); PG8_BAR; PG8_SCHED;
;             PG8_LDB(B0, 1, 0); PG8_LDB(B1, 1, 1); PG8_SCHED; PG8_LDA(At, 1, 0); PG8_STAGE(PG8_SA(0, 1), a2 + hstepA, voffA);
;             PG8_WAIT_V(8); PG8_WAIT_L(0); PG8_BAR; PG8_MMA(0, 0, At, B0); PG8_MMA(0, 1, At, B1); PG8_BAR; PG8_SCHED;
	s_setprio 1
	s_waitcnt lgkmcnt(0)
	v_mfma_f32_16x16x32_bf16 v[60:63], v[138:141], v[190:193], v[60:63]
	v_mfma_f32_16x16x32_bf16 v[56:59], v[148:151], v[190:193], v[56:59]
	v_mfma_f32_16x16x32_bf16 v[44:47], v[138:141], v[198:201], v[44:47]
	v_mfma_f32_16x16x32_bf16 v[40:43], v[148:151], v[198:201], v[40:43]
	v_mfma_f32_16x16x32_bf16 v[28:31], v[138:141], v[214:217], v[28:31]
	v_mfma_f32_16x16x32_bf16 v[24:27], v[148:151], v[214:217], v[24:27]
	v_mfma_f32_16x16x32_bf16 v[12:15], v[138:141], v[222:225], v[12:15]
	v_mfma_f32_16x16x32_bf16 v[8:11], v[148:151], v[222:225], v[8:11]
	v_mfma_f32_16x16x32_bf16 v[60:63], v[142:145], v[194:197], v[60:63]
	v_mfma_f32_16x16x32_bf16 v[56:59], v[152:155], v[194:197], v[56:59]
	v_mfma_f32_16x16x32_bf16 v[44:47], v[142:145], v[202:205], v[44:47]
	v_mfma_f32_16x16x32_bf16 v[40:43], v[152:155], v[202:205], v[40:43]
	v_mfma_f32_16x16x32_bf16 v[28:31], v[142:145], v[218:221], v[28:31]
	v_mfma_f32_16x16x32_bf16 v[24:27], v[152:155], v[218:221], v[24:27]
	v_mfma_f32_16x16x32_bf16 v[12:15], v[142:145], v[226:229], v[12:15]
	v_mfma_f32_16x16x32_bf16 v[8:11], v[152:155], v[226:229], v[8:11]
	v_mfma_f32_16x16x32_bf16 v[52:55], v[156:159], v[190:193], v[52:55]
	v_mfma_f32_16x16x32_bf16 v[48:51], v[166:169], v[190:193], v[48:51]
	v_mfma_f32_16x16x32_bf16 v[36:39], v[156:159], v[198:201], v[36:39]
	v_mfma_f32_16x16x32_bf16 v[32:35], v[166:169], v[198:201], v[32:35]
	v_mfma_f32_16x16x32_bf16 v[20:23], v[156:159], v[214:217], v[20:23]
	v_mfma_f32_16x16x32_bf16 v[16:19], v[166:169], v[214:217], v[16:19]
	v_mfma_f32_16x16x32_bf16 v[4:7], v[156:159], v[222:225], v[4:7]
	v_mfma_f32_16x16x32_bf16 v[0:3], v[166:169], v[222:225], v[0:3]
	v_mfma_f32_16x16x32_bf16 v[52:55], v[160:163], v[194:197], v[52:55]
	v_mfma_f32_16x16x32_bf16 v[48:51], v[186:189], v[194:197], v[48:51]
	v_mfma_f32_16x16x32_bf16 v[36:39], v[160:163], v[202:205], v[36:39]
	v_mfma_f32_16x16x32_bf16 v[32:35], v[186:189], v[202:205], v[32:35]
	v_mfma_f32_16x16x32_bf16 v[20:23], v[160:163], v[218:221], v[20:23]
	v_mfma_f32_16x16x32_bf16 v[16:19], v[186:189], v[218:221], v[16:19]
	v_mfma_f32_16x16x32_bf16 v[4:7], v[160:163], v[226:229], v[4:7]
	v_mfma_f32_16x16x32_bf16 v[0:3], v[186:189], v[226:229], v[0:3]
	s_setprio 0
	s_barrier
	s_add_i32 s4, 0, 0x18000
	s_add_i32 s5, 0, 0x1c000
	v_add_u32_e32 v152, s4, v146
	v_add_u32_e32 v186, s5, v146
	ds_read_b128 v[138:141], v152
	ds_read_b128 v[142:145], v152 offset:1024
	ds_read_b128 v[148:151], v152 offset:2048
	ds_read_b128 v[152:155], v152 offset:3072
	ds_read_b128 v[156:159], v186
	ds_read_b128 v[160:163], v186 offset:1024
	ds_read_b128 v[166:169], v186 offset:2048
	ds_read_b128 v[186:189], v186 offset:3072
	s_add_u32 s0, s0, 0x40000
	s_addc_u32 s1, s1, 0
	s_mov_b32 m0, s58
	v_lshl_add_u64 v[238:239], s[0:1], 0, v[132:133]
	ds_read_b128 v[190:193], v147 offset:32768
	ds_read_b128 v[194:197], v147 offset:33792
	ds_read_b128 v[198:201], v147 offset:34816
	ds_read_b128 v[202:205], v147 offset:35840
	ds_read_b128 v[214:217], v147 offset:36864
	ds_read_b128 v[218:221], v147 offset:37888
	ds_read_b128 v[222:225], v147 offset:38912
	ds_read_b128 v[226:229], v147 offset:39936
	global_load_lds_dwordx4 v[238:239], off
	v_lshl_add_u64 v[238:239], s[0:1], 0, v[130:131]
	s_mov_b32 m0, s59
	s_nop 0
	global_load_lds_dwordx4 v[238:239], off
	s_waitcnt vmcnt(8)
	s_waitcnt lgkmcnt(0)
	s_barrier
	s_setprio 1
	s_waitcnt lgkmcnt(0)
	v_mfma_f32_16x16x32_bf16 v[124:127], v[138:141], v[190:193], v[124:127]
	v_mfma_f32_16x16x32_bf16 v[120:123], v[148:151], v[190:193], v[120:123]
	v_mfma_f32_16x16x32_bf16 v[108:111], v[138:141], v[198:201], v[108:111]
	v_mfma_f32_16x16x32_bf16 v[104:107], v[148:151], v[198:201], v[104:107]
	v_mfma_f32_16x16x32_bf16 v[92:95], v[138:141], v[214:217], v[92:95]
	v_mfma_f32_16x16x32_bf16 v[88:91], v[148:151], v[214:217], v[88:91]
	v_mfma_f32_16x16x32_bf16 v[76:79], v[138:141], v[222:225], v[76:79]
	v_mfma_f32_16x16x32_bf16 v[72:75], v[148:151], v[222:225], v[72:75]
	v_mfma_f32_16x16x32_bf16 v[124:127], v[142:145], v[194:197], v[124:127]
	v_mfma_f32_16x16x32_bf16 v[120:123], v[152:155], v[194:197], v[120:123]
	v_mfma_f32_16x16x32_bf16 v[108:111], v[142:145], v[202:205], v[108:111]
	v_mfma_f32_16x16x32_bf16 v[104:107], v[152:155], v[202:205], v[104:107]
	v_mfma_f32_16x16x32_bf16 v[92:95], v[142:145], v[218:221], v[92:95]
	v_mfma_f32_16x16x32_bf16 v[88:91], v[152:155], v[218:221], v[88:91]
	v_mfma_f32_16x16x32_bf16 v[76:79], v[142:145], v[226:229], v[76:79]
	v_mfma_f32_16x16x32_bf16 v[72:75], v[152:155], v[226:229], v[72:75]
	v_mfma_f32_16x16x32_bf16 v[116:119], v[156:159], v[190:193], v[116:119]
	v_mfma_f32_16x16x32_bf16 v[112:115], v[166:169], v[190:193], v[112:115]
	v_mfma_f32_16x16x32_bf16 v[100:103], v[156:159], v[198:201], v[100:103]
	v_mfma_f32_16x16x32_bf16 v[96:99], v[166:169], v[198:201], v[96:99]
	v_mfma_f32_16x16x32_bf16 v[84:87], v[156:159], v[214:217], v[84:87]
	v_mfma_f32_16x16x32_bf16 v[80:83], v[166:169], v[214:217], v[80:83]
	v_mfma_f32_16x16x32_bf16 v[68:71], v[156:159], v[222:225], v[68:71]
	v_mfma_f32_16x16x32_bf16 v[64:67], v[166:169], v[222:225], v[64:67]
	v_mfma_f32_16x16x32_bf16 v[116:119], v[160:163], v[194:197], v[116:119]
	v_mfma_f32_16x16x32_bf16 v[112:115], v[186:189], v[194:197], v[112:115]
	v_mfma_f32_16x16x32_bf16 v[100:103], v[160:163], v[202:205], v[100:103]
	v_mfma_f32_16x16x32_bf16 v[96:99], v[186:189], v[202:205], v[96:99]
	v_mfma_f32_16x16x32_bf16 v[84:87], v[160:163], v[218:221], v[84:87]
	v_mfma_f32_16x16x32_bf16 v[80:83], v[186:189], v[218:221], v[80:83]
	v_mfma_f32_16x16x32_bf16 v[68:71], v[160:163], v[226:229], v[68:71]
	v_mfma_f32_16x16x32_bf16 v[64:67], v[186:189], v[226:229], v[64:67]
	s_setprio 0
	s_barrier
; #define PG8_STAGE(bufoff, gbase, voff) do { _Pragma("unroll") for (int _i = 0; _i < 2; ++_i) \
;         __builtin_amdgcn_global_load_lds((const unsigned*)((const char*)(gbase) + (voff)[_i]), (PG8_LAS unsigned*)(lds + (bufoff) + ldsw + _i * 8192), 16, 0, 0); } while (0)
; #define PG8_LDA(dst, b, h) do { _Pragma("unroll") for (int m = 0; m < 4; ++m) _Pragma("unroll") for (int k = 0; k < 2; ++k) dst[m][k] = *(const PG8_LAS bf16x8*)(lds + PG8_SA(b, h) + aoff + m * 2048 + k * 1024); } while (0)
; #define PG8_MMA(ai, bj, At, Bt) do { __builtin_amdgcn_s_setprio(1); _Pragma("unroll") for (int m = 0; m < 4; ++m) _Pragma("unroll") for (int n = 0; n < 2; ++n) _Pragma("unroll") for (int k = 0; k < 2; ++k) \
;         acc[ai][bj][m][n] = __builtin_amdgcn_mfma_f32_16x16x32_bf16(Bt[n][k], At[m][k], acc[ai][bj][m][n], 0, 0, 0); __builtin_amdgcn_s_setprio(0); } while (0)
; #define PG8_WAIT_V(n) asm volatile("s_waitcnt vmcnt(" #n ")" ::: "memory")
; #define PG8_WAIT_L(n) asm volatile("s_waitcnt lgkmcnt(" #n ")" ::: "memory")
; #define PG8_BAR __builtin_amdgcn_s_barrier()
; #define PG8_SCHED __builtin_amdgcn_sched_barrier(0)
; template <class Epi, class Sched, bool ALIGN_EPI = false, bool SP2 = false>
; __device__ __forceinline__ void gemm_phase(PG8_LAS unsigned char* lds, const Gemm g, const Sched& S, const Epi& E) {
;     ...
;             PG8_LDA(At, 1, 1); PG8_STAGE(PG8_SB(1, 0), b3, voffB); PG8_STAGE(PG8_SB(1, 1), b3 + hstepB, voffB); PG8_STAGE(PG8_SA(1, 0), a3, voffA);
;             PG8_WAIT_V(8); PG8_WAIT_L(0); PG8_BAR; PG8_MMA(1, 0, At, B0); PG8_MMA(1, 1, At, B1); PG8_BAR; PG8_SCHED;
;     ...
;         if constexpr (ALIGN_EPI) { if (wr == 0) PG8_BAR; }
	s_add_i32 s0, s4, s54
	v_lshl_add_u64 v[230:231], v[230:231], 0, s[14:15]
	s_mov_b32 m0, s0
	ds_read_b128 v[190:193], v147 offset:49152
	ds_read_b128 v[194:197], v147 offset:50176
	ds_read_b128 v[198:201], v147 offset:51200
	ds_read_b128 v[202:205], v147 offset:52224
	ds_read_b128 v[214:217], v147 offset:53248
	ds_read_b128 v[218:221], v147 offset:54272
	ds_read_b128 v[222:225], v147 offset:55296
	ds_read_b128 v[226:229], v147 offset:56320
	global_load_lds_dwordx4 v[230:231], off
	s_add_i32 m0, s0, 0x2000
	s_add_u32 s0, s50, 0x40080
	v_lshl_add_u64 v[230:231], v[232:233], 0, s[14:15]
	s_addc_u32 s1, s51, 0
	s_add_i32 s4, s5, s54
	global_load_lds_dwordx4 v[230:231], off
	v_lshl_add_u64 v[230:231], s[0:1], 0, v[164:165]
	s_mov_b32 m0, s4
	s_nop 0
	global_load_lds_dwordx4 v[230:231], off
	v_lshl_add_u64 v[230:231], s[0:1], 0, v[128:129]
	s_add_i32 m0, s4, 0x2000
	s_nop 0
	global_load_lds_dwordx4 v[230:231], off
	v_lshl_add_u64 v[230:231], v[234:235], 0, s[14:15]
	s_mov_b32 m0, s62
	s_nop 0
	global_load_lds_dwordx4 v[230:231], off
	v_lshl_add_u64 v[230:231], v[236:237], 0, s[14:15]
	s_mov_b32 m0, s63
	s_nop 0
	global_load_lds_dwordx4 v[230:231], off
	s_waitcnt vmcnt(8)
	s_waitcnt lgkmcnt(0)
	s_barrier
	s_setprio 1
	s_waitcnt lgkmcnt(0)
	v_mfma_f32_16x16x32_bf16 v[60:63], v[138:141], v[190:193], v[60:63]
	v_mfma_f32_16x16x32_bf16 v[56:59], v[148:151], v[190:193], v[56:59]
	v_mfma_f32_16x16x32_bf16 v[44:47], v[138:141], v[198:201], v[44:47]
	v_mfma_f32_16x16x32_bf16 v[40:43], v[148:151], v[198:201], v[40:43]
	v_mfma_f32_16x16x32_bf16 v[28:31], v[138:141], v[214:217], v[28:31]
	v_mfma_f32_16x16x32_bf16 v[24:27], v[148:151], v[214:217], v[24:27]
	v_mfma_f32_16x16x32_bf16 v[12:15], v[138:141], v[222:225], v[12:15]
	v_mfma_f32_16x16x32_bf16 v[8:11], v[148:151], v[222:225], v[8:11]
	v_mfma_f32_16x16x32_bf16 v[60:63], v[142:145], v[194:197], v[60:63]
	v_mfma_f32_16x16x32_bf16 v[56:59], v[152:155], v[194:197], v[56:59]
	v_mfma_f32_16x16x32_bf16 v[44:47], v[142:145], v[202:205], v[44:47]
	v_mfma_f32_16x16x32_bf16 v[40:43], v[152:155], v[202:205], v[40:43]
	v_mfma_f32_16x16x32_bf16 v[28:31], v[142:145], v[218:221], v[28:31]
	v_mfma_f32_16x16x32_bf16 v[24:27], v[152:155], v[218:221], v[24:27]
	v_mfma_f32_16x16x32_bf16 v[12:15], v[142:145], v[226:229], v[12:15]
	v_mfma_f32_16x16x32_bf16 v[8:11], v[152:155], v[226:229], v[8:11]
	v_mfma_f32_16x16x32_bf16 v[52:55], v[156:159], v[190:193], v[52:55]
	v_mfma_f32_16x16x32_bf16 v[48:51], v[166:169], v[190:193], v[48:51]
	v_mfma_f32_16x16x32_bf16 v[36:39], v[156:159], v[198:201], v[36:39]
	v_mfma_f32_16x16x32_bf16 v[32:35], v[166:169], v[198:201], v[32:35]
	v_mfma_f32_16x16x32_bf16 v[20:23], v[156:159], v[214:217], v[20:23]
	v_mfma_f32_16x16x32_bf16 v[16:19], v[166:169], v[214:217], v[16:19]
	v_mfma_f32_16x16x32_bf16 v[4:7], v[156:159], v[222:225], v[4:7]
	v_mfma_f32_16x16x32_bf16 v[0:3], v[166:169], v[222:225], v[0:3]
	v_mfma_f32_16x16x32_bf16 v[52:55], v[160:163], v[194:197], v[52:55]
	v_mfma_f32_16x16x32_bf16 v[48:51], v[186:189], v[194:197], v[48:51]
	v_mfma_f32_16x16x32_bf16 v[36:39], v[160:163], v[202:205], v[36:39]
	v_mfma_f32_16x16x32_bf16 v[32:35], v[186:189], v[202:205], v[32:35]
	v_mfma_f32_16x16x32_bf16 v[20:23], v[160:163], v[218:221], v[20:23]
	v_mfma_f32_16x16x32_bf16 v[16:19], v[186:189], v[218:221], v[16:19]
	v_mfma_f32_16x16x32_bf16 v[4:7], v[160:163], v[226:229], v[4:7]
	v_mfma_f32_16x16x32_bf16 v[0:3], v[186:189], v[226:229], v[0:3]
	s_setprio 0
	s_barrier
	s_add_i32 s18, s18, 2
	s_add_u32 s16, s16, 0x100
	s_addc_u32 s17, s17, 0
	s_add_u32 s48, s48, 0x100
	s_addc_u32 s49, s49, 0
	s_cmp_gt_u32 s18, 13
	s_cbranch_scc0 .LBB0_1218
	s_and_b64 vcc, exec, s[42:43]
	s_cbranch_vccz .LBB0_1221
	s_barrier

; #define PG8_STAGE(bufoff, gbase, voff) do { _Pragma("unroll") for (int _i = 0; _i < 2; ++_i) \
;         __builtin_amdgcn_global_load_lds((const unsigned*)((const char*)(gbase) + (voff)[_i]), (PG8_LAS unsigned*)(lds + (bufoff) + ldsw + _i * 8192), 16, 0, 0); } while (0)
; #define PG8_LDA(dst, b, h) do { _Pragma("unroll") for (int m = 0; m < 4; ++m) _Pragma("unroll") for (int k = 0; k < 2; ++k) dst[m][k] = *(const PG8_LAS bf16x8*)(lds + PG8_SA(b, h) + aoff + m * 2048 + k * 1024); } while (0)
; #define PG8_LDB(dst, b, h) do { _Pragma("unroll") for (int n = 0; n < 2; ++n) _Pragma("unroll") for (int k = 0; k < 2; ++k) dst[n][k] = *(const PG8_LAS bf16x8*)(lds + PG8_SB(b, h) + boff + n * 2048 + k * 1024); } while (0)
; #define PG8_MMA(ai, bj, At, Bt) do { __builtin_amdgcn_s_setprio(1); _Pragma("unroll") for (int m = 0; m < 4; ++m) _Pragma("unroll") for (int n = 0; n < 2; ++n) _Pragma("unroll") for (int k = 0; k < 2; ++k) \
;         acc[ai][bj][m][n] = __builtin_amdgcn_mfma_f32_16x16x32_bf16(Bt[n][k], At[m][k], acc[ai][bj][m][n], 0, 0, 0); __builtin_amdgcn_s_setprio(0); } while (0)
; #define PG8_WAIT_V(n) asm volatile("s_waitcnt vmcnt(" #n ")" ::: "memory")
; #define PG8_WAIT_L(n) asm volatile("s_waitcnt lgkmcnt(" #n ")" ::: "memory")
; #define PG8_BAR __builtin_amdgcn_s_barrier()
; template <class Epi, class Sched, bool ALIGN_EPI = false, bool SP2 = false>
; __device__ __forceinline__ void gemm_phase(PG8_LAS unsigned char* lds, const Gemm g, const Sched& S, const Epi& E) {
;     ...
;             const char* a1 = cA + (size_t)(t + 1) * kstep;
;             const char* a2 = last ? nA : cA + (size_t)(t + 2) * kstep; const char* b2 = last ? nB : cB + (size_t)(t + 2) * kstep;
;             const char* a3 = a2 + kstep; const char* b3 = b2 + kstep;
;             if (last && has_next) S.a_ready(nxt);
;             if constexpr (SP2) {
;             PG8_LDB(B0, 0, 0); PG8_LDB(B1, 0, 1); PG8_SCHED; PG8_LDA(At, 0, 0); PG8_STAGE(PG8_SA(1, 1), a1 + hstepA, voffA);
;             PG8_WAIT_V(8); PG8_WAIT_L(0); PG8_BAR; PG8_MMA(0, 0, At, B0); PG8_MMA(0, 1, At, B1); PG8_BAR; PG8_SCHED;
;             PG8_LDA(At, 0, 1); PG8_STAGE(PG8_SB(0, 0), b2, voffB); PG8_STAGE(PG8_SB(0, 1), b2 + hstepB, voffB); PG8_STAGE(PG8_SA(0, 0), a2, voffA);
;             PG8_WAIT_V(8); PG8_WAIT_L(0); PG8_BAR; PG8_MMA(1, 0, At, B0); PG8_MMA(1, 1, At, B1); PG8_BAR; PG8_SCHED;
.LBB0_1297:
	s_add_u32 s0, s56, 0xfff00080
	s_addc_u32 s1, s57, -1
	s_add_i32 s4, 0, 0x10000
	s_cmp_eq_u32 s63, 60
	s_cselect_b32 s1, s16, s1
	s_cselect_b32 s0, s17, s0
	s_cselect_b32 s59, s49, s62
	s_cselect_b32 s58, s51, s61
	s_add_i32 s5, 0, 0x14000
	v_add_u32_e32 v152, s4, v138
	v_add_u32_e32 v186, s5, v138
	ds_read_b128 v[140:143], v152
	ds_read_b128 v[144:147], v152 offset:1024
	ds_read_b128 v[148:151], v152 offset:2048
	ds_read_b128 v[152:155], v152 offset:3072
	ds_read_b128 v[156:159], v186
	ds_read_b128 v[160:163], v186 offset:1024
	ds_read_b128 v[166:169], v186 offset:2048
	ds_read_b128 v[186:189], v186 offset:3072
	v_lshl_add_u64 v[230:231], s[56:57], 0, v[136:137]
	s_add_i32 m0, s43, 0xc000
	ds_read_b128 v[190:193], v139
	ds_read_b128 v[194:197], v139 offset:1024
	ds_read_b128 v[198:201], v139 offset:2048
	ds_read_b128 v[202:205], v139 offset:3072
	ds_read_b128 v[214:217], v139 offset:4096
	ds_read_b128 v[218:221], v139 offset:5120
	ds_read_b128 v[222:225], v139 offset:6144
	ds_read_b128 v[226:229], v139 offset:7168
	global_load_lds_dwordx4 v[230:231], off
	v_lshl_add_u64 v[230:231], s[56:57], 0, v[134:135]
	s_add_i32 m0, s43, 0xe000
	s_nop 0
	global_load_lds_dwordx4 v[230:231], off
	s_waitcnt vmcnt(8)
	s_waitcnt lgkmcnt(0)
	s_barrier
	s_setprio 1
	s_waitcnt lgkmcnt(0)
	v_mfma_f32_16x16x32_bf16 v[124:127], v[140:143], v[190:193], v[124:127]
	v_mfma_f32_16x16x32_bf16 v[120:123], v[148:151], v[190:193], v[120:123]
	v_mfma_f32_16x16x32_bf16 v[116:119], v[140:143], v[198:201], v[116:119]
	v_mfma_f32_16x16x32_bf16 v[112:115], v[148:151], v[198:201], v[112:115]
	v_mfma_f32_16x16x32_bf16 v[100:103], v[140:143], v[214:217], v[100:103]
	v_mfma_f32_16x16x32_bf16 v[96:99], v[148:151], v[214:217], v[96:99]
	v_mfma_f32_16x16x32_bf16 v[84:87], v[140:143], v[222:225], v[84:87]
	v_mfma_f32_16x16x32_bf16 v[80:83], v[148:151], v[222:225], v[80:83]
	v_mfma_f32_16x16x32_bf16 v[124:127], v[144:147], v[194:197], v[124:127]
	v_mfma_f32_16x16x32_bf16 v[120:123], v[152:155], v[194:197], v[120:123]
	v_mfma_f32_16x16x32_bf16 v[116:119], v[144:147], v[202:205], v[116:119]
	v_mfma_f32_16x16x32_bf16 v[112:115], v[152:155], v[202:205], v[112:115]
	v_mfma_f32_16x16x32_bf16 v[100:103], v[144:147], v[218:221], v[100:103]
	v_mfma_f32_16x16x32_bf16 v[96:99], v[152:155], v[218:221], v[96:99]
	v_mfma_f32_16x16x32_bf16 v[84:87], v[144:147], v[226:229], v[84:87]
	v_mfma_f32_16x16x32_bf16 v[80:83], v[152:155], v[226:229], v[80:83]
	v_mfma_f32_16x16x32_bf16 v[108:111], v[156:159], v[190:193], v[108:111]
	v_mfma_f32_16x16x32_bf16 v[104:107], v[166:169], v[190:193], v[104:107]
	v_mfma_f32_16x16x32_bf16 v[92:95], v[156:159], v[198:201], v[92:95]
	v_mfma_f32_16x16x32_bf16 v[88:91], v[166:169], v[198:201], v[88:91]
	v_mfma_f32_16x16x32_bf16 v[76:79], v[156:159], v[214:217], v[76:79]
	v_mfma_f32_16x16x32_bf16 v[72:75], v[166:169], v[214:217], v[72:75]
	v_mfma_f32_16x16x32_bf16 v[68:71], v[156:159], v[222:225], v[68:71]
	v_mfma_f32_16x16x32_bf16 v[64:67], v[166:169], v[222:225], v[64:67]
	v_mfma_f32_16x16x32_bf16 v[108:111], v[160:163], v[194:197], v[108:111]
	v_mfma_f32_16x16x32_bf16 v[104:107], v[186:189], v[194:197], v[104:107]
	v_mfma_f32_16x16x32_bf16 v[92:95], v[160:163], v[202:205], v[92:95]
	v_mfma_f32_16x16x32_bf16 v[88:91], v[186:189], v[202:205], v[88:91]
	v_mfma_f32_16x16x32_bf16 v[76:79], v[160:163], v[218:221], v[76:79]
	v_mfma_f32_16x16x32_bf16 v[72:75], v[186:189], v[218:221], v[72:75]
	v_mfma_f32_16x16x32_bf16 v[68:71], v[160:163], v[226:229], v[68:71]
	v_mfma_f32_16x16x32_bf16 v[64:67], v[186:189], v[226:229], v[64:67]
	s_setprio 0
	s_barrier
	s_add_i32 s4, s4, s29
	v_lshl_add_u64 v[230:231], s[58:59], 0, v[164:165]
	s_mov_b32 m0, s4
	ds_read_b128 v[190:193], v139 offset:16384
	ds_read_b128 v[194:197], v139 offset:17408
	ds_read_b128 v[198:201], v139 offset:18432
	ds_read_b128 v[202:205], v139 offset:19456
	ds_read_b128 v[214:217], v139 offset:20480
	ds_read_b128 v[218:221], v139 offset:21504
	ds_read_b128 v[222:225], v139 offset:22528
	ds_read_b128 v[226:229], v139 offset:23552
	global_load_lds_dwordx4 v[230:231], off
	s_add_i32 m0, s4, 0x2000
	s_add_u32 s36, s58, 0x100000
	v_lshl_add_u64 v[232:233], s[58:59], 0, v[132:133]
	s_addc_u32 s37, s59, 0
	s_add_i32 s4, s5, s29
	global_load_lds_dwordx4 v[232:233], off
	v_lshl_add_u64 v[234:235], s[36:37], 0, v[164:165]
	s_mov_b32 m0, s4
	v_lshl_add_u64 v[236:237], s[0:1], 0, v[130:131]
	global_load_lds_dwordx4 v[234:235], off
	v_lshl_add_u64 v[234:235], s[36:37], 0, v[132:133]
	s_add_i32 m0, s4, 0x2000
	s_nop 0
	global_load_lds_dwordx4 v[234:235], off
	v_lshl_add_u64 v[234:235], s[0:1], 0, v[128:129]
	s_mov_b32 m0, s43
	s_nop 0
	global_load_lds_dwordx4 v[234:235], off
	s_mov_b32 m0, s46
	s_nop 0
	global_load_lds_dwordx4 v[236:237], off
	s_waitcnt vmcnt(8)
	s_waitcnt lgkmcnt(0)
	s_barrier
; #define PG8_STAGE(bufoff, gbase, voff) do { _Pragma("unroll") for (int _i = 0; _i < 2; ++_i) \
;         __builtin_amdgcn_global_load_lds((const unsigned*)((const char*)(gbase) + (voff)[_i]), (PG8_LAS unsigned*)(lds + (bufoff) + ldsw + _i * 8192), 16, 0, 0); } while (0)
; #define PG8_LDA(dst, b, h) do { _Pragma("unroll") for (int m = 0; m < 4; ++m) _Pragma("unroll") for (int k = 0; k < 2; ++k) dst[m][k] = *(const PG8_LAS bf16x8*)(lds + PG8_SA(b, h) + aoff + m * 2048 + k * 1024); } while (0)
; #define PG8_LDB(dst, b, h) do { _Pragma("unroll") for (int n = 0; n < 2; ++n) _Pragma("unroll") for (int k = 0; k < 2; ++k) dst[n][k] = *(const PG8_LAS bf16x8*)(lds + PG8_SB(b, h) + boff + n * 2048 + k * 1024); } while (0)
; #define PG8_MMA(ai, bj, At, Bt) do { __builtin_amdgcn_s_setprio(1); _Pragma("unroll") for (int m = 0; m < 4; ++m) _Pragma("unroll") for (int n = 0; n < 2; ++n) _Pragma("unroll") for (int k = 0; k < 2; ++k) \
;         acc[ai][bj][m][n] = __builtin_amdgcn_mfma_f32_16x16x32_bf16(Bt[n][k], At[m][k], acc[ai][bj][m][n], 0, 0, 0); __builtin_amdgcn_s_setprio(0); } while (0)
; #define PG8_WAIT_V(n) asm volatile("s_waitcnt vmcnt(" #n ")" ::: "memory")
; #define PG8_WAIT_L(n) asm volatile("s_waitcnt lgkmcnt(" #n ")" ::: "memory")
; #define PG8_BAR __builtin_amdgcn_s_barrier()
; #define PG8_SCHED __builtin_amdgcn_sched_barrier(0)
; template <class Epi, class Sched, bool ALIGN_EPI = false, bool SP2 = false>
; __device__ __forceinline__ void gemm_phase(PG8_LAS unsigned char* lds, const Gemm g, const Sched& S, const Epi& E) {
;     ...
;             PG8_WAIT_V(8); PG8_WAIT_L(0); PG8_BAR; PG8_MMA(1, 0, At, B0); PG8_MMA(1, 1, At, B1); PG8_BAR; PG8_SCHED;
;             PG8_LDB(B0, 1, 0); PG8_LDB(B1, 1, 1); PG8_SCHED; PG8_LDA(At, 1, 0); PG8_STAGE(PG8_SA(0, 1), a2 + hstepA, voffA);
;             PG8_WAIT_V(8); PG8_WAIT_L(0); PG8_BAR; PG8_MMA(0, 0, At, B0); PG8_MMA(0, 1, At, B1); PG8_BAR; PG8_SCHED;
	s_setprio 1
	s_waitcnt lgkmcnt(0)
	v_mfma_f32_16x16x32_bf16 v[60:63], v[140:143], v[190:193], v[60:63]
	v_mfma_f32_16x16x32_bf16 v[56:59], v[148:151], v[190:193], v[56:59]
	v_mfma_f32_16x16x32_bf16 v[52:55], v[140:143], v[198:201], v[52:55]
	v_mfma_f32_16x16x32_bf16 v[48:51], v[148:151], v[198:201], v[48:51]
	v_mfma_f32_16x16x32_bf16 v[36:39], v[140:143], v[214:217], v[36:39]
	v_mfma_f32_16x16x32_bf16 v[32:35], v[148:151], v[214:217], v[32:35]
	v_mfma_f32_16x16x32_bf16 v[20:23], v[140:143], v[222:225], v[20:23]
	v_mfma_f32_16x16x32_bf16 v[16:19], v[148:151], v[222:225], v[16:19]
	v_mfma_f32_16x16x32_bf16 v[60:63], v[144:147], v[194:197], v[60:63]
	v_mfma_f32_16x16x32_bf16 v[56:59], v[152:155], v[194:197], v[56:59]
	v_mfma_f32_16x16x32_bf16 v[52:55], v[144:147], v[202:205], v[52:55]
	v_mfma_f32_16x16x32_bf16 v[48:51], v[152:155], v[202:205], v[48:51]
	v_mfma_f32_16x16x32_bf16 v[36:39], v[144:147], v[218:221], v[36:39]
	v_mfma_f32_16x16x32_bf16 v[32:35], v[152:155], v[218:221], v[32:35]
	v_mfma_f32_16x16x32_bf16 v[20:23], v[144:147], v[226:229], v[20:23]
	v_mfma_f32_16x16x32_bf16 v[16:19], v[152:155], v[226:229], v[16:19]
	v_mfma_f32_16x16x32_bf16 v[44:47], v[156:159], v[190:193], v[44:47]
	v_mfma_f32_16x16x32_bf16 v[40:43], v[166:169], v[190:193], v[40:43]
	v_mfma_f32_16x16x32_bf16 v[28:31], v[156:159], v[198:201], v[28:31]
	v_mfma_f32_16x16x32_bf16 v[24:27], v[166:169], v[198:201], v[24:27]
	v_mfma_f32_16x16x32_bf16 v[12:15], v[156:159], v[214:217], v[12:15]
	v_mfma_f32_16x16x32_bf16 v[8:11], v[166:169], v[214:217], v[8:11]
	v_mfma_f32_16x16x32_bf16 v[4:7], v[156:159], v[222:225], v[4:7]
	v_mfma_f32_16x16x32_bf16 v[0:3], v[166:169], v[222:225], v[0:3]
	v_mfma_f32_16x16x32_bf16 v[44:47], v[160:163], v[194:197], v[44:47]
	v_mfma_f32_16x16x32_bf16 v[40:43], v[186:189], v[194:197], v[40:43]
	v_mfma_f32_16x16x32_bf16 v[28:31], v[160:163], v[202:205], v[28:31]
	v_mfma_f32_16x16x32_bf16 v[24:27], v[186:189], v[202:205], v[24:27]
	v_mfma_f32_16x16x32_bf16 v[12:15], v[160:163], v[218:221], v[12:15]
	v_mfma_f32_16x16x32_bf16 v[8:11], v[186:189], v[218:221], v[8:11]
	v_mfma_f32_16x16x32_bf16 v[4:7], v[160:163], v[226:229], v[4:7]
	v_mfma_f32_16x16x32_bf16 v[0:3], v[186:189], v[226:229], v[0:3]
	s_setprio 0
	s_barrier
	s_add_i32 s4, 0, 0x18000
	s_add_i32 s5, 0, 0x1c000
	v_add_u32_e32 v152, s4, v138
	v_add_u32_e32 v186, s5, v138
	ds_read_b128 v[140:143], v152
	ds_read_b128 v[144:147], v152 offset:1024
	ds_read_b128 v[148:151], v152 offset:2048
	ds_read_b128 v[152:155], v152 offset:3072
	ds_read_b128 v[156:159], v186
	ds_read_b128 v[160:163], v186 offset:1024
	ds_read_b128 v[166:169], v186 offset:2048
	ds_read_b128 v[186:189], v186 offset:3072
	s_add_u32 s0, s0, 0x100000
	s_addc_u32 s1, s1, 0
	s_mov_b32 m0, s47
	v_lshl_add_u64 v[238:239], s[0:1], 0, v[128:129]
	ds_read_b128 v[190:193], v139 offset:32768
	ds_read_b128 v[194:197], v139 offset:33792
	ds_read_b128 v[198:201], v139 offset:34816
	ds_read_b128 v[202:205], v139 offset:35840
	ds_read_b128 v[214:217], v139 offset:36864
	ds_read_b128 v[218:221], v139 offset:37888
	ds_read_b128 v[222:225], v139 offset:38912
	ds_read_b128 v[226:229], v139 offset:39936
	global_load_lds_dwordx4 v[238:239], off
	v_lshl_add_u64 v[238:239], s[0:1], 0, v[130:131]
	s_mov_b32 m0, s60
	s_nop 0
	global_load_lds_dwordx4 v[238:239], off
	s_waitcnt vmcnt(8)
	s_waitcnt lgkmcnt(0)
	s_barrier
	s_setprio 1
	s_waitcnt lgkmcnt(0)
	v_mfma_f32_16x16x32_bf16 v[124:127], v[140:143], v[190:193], v[124:127]
	v_mfma_f32_16x16x32_bf16 v[120:123], v[148:151], v[190:193], v[120:123]
	v_mfma_f32_16x16x32_bf16 v[116:119], v[140:143], v[198:201], v[116:119]
	v_mfma_f32_16x16x32_bf16 v[112:115], v[148:151], v[198:201], v[112:115]
	v_mfma_f32_16x16x32_bf16 v[100:103], v[140:143], v[214:217], v[100:103]
	v_mfma_f32_16x16x32_bf16 v[96:99], v[148:151], v[214:217], v[96:99]
	v_mfma_f32_16x16x32_bf16 v[84:87], v[140:143], v[222:225], v[84:87]
	v_mfma_f32_16x16x32_bf16 v[80:83], v[148:151], v[222:225], v[80:83]
	v_mfma_f32_16x16x32_bf16 v[124:127], v[144:147], v[194:197], v[124:127]
	v_mfma_f32_16x16x32_bf16 v[120:123], v[152:155], v[194:197], v[120:123]
	v_mfma_f32_16x16x32_bf16 v[116:119], v[144:147], v[202:205], v[116:119]
	v_mfma_f32_16x16x32_bf16 v[112:115], v[152:155], v[202:205], v[112:115]
	v_mfma_f32_16x16x32_bf16 v[100:103], v[144:147], v[218:221], v[100:103]
	v_mfma_f32_16x16x32_bf16 v[96:99], v[152:155], v[218:221], v[96:99]
	v_mfma_f32_16x16x32_bf16 v[84:87], v[144:147], v[226:229], v[84:87]
	v_mfma_f32_16x16x32_bf16 v[80:83], v[152:155], v[226:229], v[80:83]
	v_mfma_f32_16x16x32_bf16 v[108:111], v[156:159], v[190:193], v[108:111]
	v_mfma_f32_16x16x32_bf16 v[104:107], v[166:169], v[190:193], v[104:107]
	v_mfma_f32_16x16x32_bf16 v[92:95], v[156:159], v[198:201], v[92:95]
	v_mfma_f32_16x16x32_bf16 v[88:91], v[166:169], v[198:201], v[88:91]
	v_mfma_f32_16x16x32_bf16 v[76:79], v[156:159], v[214:217], v[76:79]
	v_mfma_f32_16x16x32_bf16 v[72:75], v[166:169], v[214:217], v[72:75]
	v_mfma_f32_16x16x32_bf16 v[68:71], v[156:159], v[222:225], v[68:71]
	v_mfma_f32_16x16x32_bf16 v[64:67], v[166:169], v[222:225], v[64:67]
	v_mfma_f32_16x16x32_bf16 v[108:111], v[160:163], v[194:197], v[108:111]
	v_mfma_f32_16x16x32_bf16 v[104:107], v[186:189], v[194:197], v[104:107]
	v_mfma_f32_16x16x32_bf16 v[92:95], v[160:163], v[202:205], v[92:95]
	v_mfma_f32_16x16x32_bf16 v[88:91], v[186:189], v[202:205], v[88:91]
	v_mfma_f32_16x16x32_bf16 v[76:79], v[160:163], v[218:221], v[76:79]
	v_mfma_f32_16x16x32_bf16 v[72:75], v[186:189], v[218:221], v[72:75]
	v_mfma_f32_16x16x32_bf16 v[68:71], v[160:163], v[226:229], v[68:71]
	v_mfma_f32_16x16x32_bf16 v[64:67], v[186:189], v[226:229], v[64:67]
	s_setprio 0
	s_barrier
; #define PG8_STAGE(bufoff, gbase, voff) do { _Pragma("unroll") for (int _i = 0; _i < 2; ++_i) \
;         __builtin_amdgcn_global_load_lds((const unsigned*)((const char*)(gbase) + (voff)[_i]), (PG8_LAS unsigned*)(lds + (bufoff) + ldsw + _i * 8192), 16, 0, 0); } while (0)
; #define PG8_LDA(dst, b, h) do { _Pragma("unroll") for (int m = 0; m < 4; ++m) _Pragma("unroll") for (int k = 0; k < 2; ++k) dst[m][k] = *(const PG8_LAS bf16x8*)(lds + PG8_SA(b, h) + aoff + m * 2048 + k * 1024); } while (0)
; #define PG8_WAIT_V(n) asm volatile("s_waitcnt vmcnt(" #n ")" ::: "memory")
; template <class Epi, class Sched, bool ALIGN_EPI = false, bool SP2 = false>
; __device__ __forceinline__ void gemm_phase(PG8_LAS unsigned char* lds, const Gemm g, const Sched& S, const Epi& E) {
;     ...
;             PG8_LDA(At, 1, 1); PG8_STAGE(PG8_SB(1, 0), b3, voffB); PG8_STAGE(PG8_SB(1, 1), b3 + hstepB, voffB); PG8_STAGE(PG8_SA(1, 0), a3, voffA);
;             PG8_WAIT_V(8); PG8_WAIT_L(0); PG8_BAR; PG8_MMA(1, 0, At, B0); PG8_MMA(1, 1, At, B1); PG8_BAR; PG8_SCHED;
;             } else {
;             PG8_LDB(B0, 0, 0); PG8_SCHED; PG8_LDA(At, 0, 0); PG8_STAGE(PG8_SA(1, 1), a1 + hstepA, voffA);
;             PG8_WAIT_L(8); PG8_BAR; PG8_WAIT_L(0); PG8_MMA(0, 0, At, B0); PG8_BAR; PG8_SCHED;
;             PG8_LDB(B1, 0, 1); PG8_STAGE(PG8_SB(0, 0), b2, voffB);
;             PG8_BAR; PG8_WAIT_L(0); PG8_MMA(0, 1, At, B1); PG8_BAR;
;             PG8_LDA(At, 0, 1); PG8_STAGE(PG8_SA(0, 0), a2, voffA);
;             PG8_BAR; PG8_WAIT_L(0); PG8_MMA(1, 0, At, B0); PG8_BAR; PG8_SCHED;
;             PG8_STAGE(PG8_SB(0, 1), b2 + hstepB, voffB);
;             PG8_WAIT_V(6); PG8_BAR; PG8_MMA(1, 1, At, B1); PG8_BAR;
;             PG8_LDB(B0, 1, 0); PG8_SCHED; PG8_LDA(At, 1, 0); PG8_STAGE(PG8_SA(0, 1), a2 + hstepA, voffA);
;             PG8_WAIT_L(8); PG8_BAR; PG8_WAIT_L(0); PG8_MMA(0, 0, At, B0); PG8_BAR; PG8_SCHED;
;             PG8_LDB(B1, 1, 1); PG8_STAGE(PG8_SB(1, 0), b3, voffB);
;             PG8_BAR; PG8_WAIT_L(0); PG8_MMA(0, 1, At, B1); PG8_BAR;
;             PG8_LDA(At, 1, 1); PG8_STAGE(PG8_SA(1, 0), a3, voffA);
;             PG8_BAR; PG8_WAIT_L(0); PG8_MMA(1, 0, At, B0); PG8_BAR; PG8_SCHED;
;             PG8_STAGE(PG8_SB(1, 1), b3 + hstepB, voffB);
;             PG8_WAIT_V(6); PG8_BAR; PG8_MMA(1, 1, At, B1); PG8_BAR;
;             }
;         }
;         if constexpr (ALIGN_EPI) { if (wr == 0) PG8_BAR; }
	s_add_i32 s0, s4, s29
	v_lshl_add_u64 v[230:231], v[230:231], 0, s[14:15]
	s_mov_b32 m0, s0
	ds_read_b128 v[190:193], v139 offset:49152
	ds_read_b128 v[194:197], v139 offset:50176
	ds_read_b128 v[198:201], v139 offset:51200
	ds_read_b128 v[202:205], v139 offset:52224
	ds_read_b128 v[214:217], v139 offset:53248
	ds_read_b128 v[218:221], v139 offset:54272
	ds_read_b128 v[222:225], v139 offset:55296
	ds_read_b128 v[226:229], v139 offset:56320
	global_load_lds_dwordx4 v[230:231], off
	s_add_i32 m0, s0, 0x2000
	s_add_u32 s0, s58, 0x100080
	v_lshl_add_u64 v[230:231], v[232:233], 0, s[14:15]
	s_addc_u32 s1, s59, 0
	s_add_i32 s4, s5, s29
	global_load_lds_dwordx4 v[230:231], off
	v_lshl_add_u64 v[230:231], s[0:1], 0, v[164:165]
	s_mov_b32 m0, s4
	s_nop 0
	global_load_lds_dwordx4 v[230:231], off
	v_lshl_add_u64 v[230:231], s[0:1], 0, v[132:133]
	s_add_i32 m0, s4, 0x2000
	s_nop 0
	global_load_lds_dwordx4 v[230:231], off
	v_lshl_add_u64 v[230:231], v[234:235], 0, s[14:15]
	s_mov_b32 m0, s9
	s_nop 0
	global_load_lds_dwordx4 v[230:231], off
	v_lshl_add_u64 v[230:231], v[236:237], 0, s[14:15]
	s_mov_b32 m0, s25
	s_nop 0
	global_load_lds_dwordx4 v[230:231], off
	s_waitcnt vmcnt(8)
	s_waitcnt lgkmcnt(0)
	s_barrier
	s_setprio 1
	s_waitcnt lgkmcnt(0)
	v_mfma_f32_16x16x32_bf16 v[60:63], v[140:143], v[190:193], v[60:63]
	v_mfma_f32_16x16x32_bf16 v[56:59], v[148:151], v[190:193], v[56:59]
	v_mfma_f32_16x16x32_bf16 v[52:55], v[140:143], v[198:201], v[52:55]
	v_mfma_f32_16x16x32_bf16 v[48:51], v[148:151], v[198:201], v[48:51]
	v_mfma_f32_16x16x32_bf16 v[36:39], v[140:143], v[214:217], v[36:39]
	v_mfma_f32_16x16x32_bf16 v[32:35], v[148:151], v[214:217], v[32:35]
	v_mfma_f32_16x16x32_bf16 v[20:23], v[140:143], v[222:225], v[20:23]
	v_mfma_f32_16x16x32_bf16 v[16:19], v[148:151], v[222:225], v[16:19]
	v_mfma_f32_16x16x32_bf16 v[60:63], v[144:147], v[194:197], v[60:63]
	v_mfma_f32_16x16x32_bf16 v[56:59], v[152:155], v[194:197], v[56:59]
	v_mfma_f32_16x16x32_bf16 v[52:55], v[144:147], v[202:205], v[52:55]
	v_mfma_f32_16x16x32_bf16 v[48:51], v[152:155], v[202:205], v[48:51]
	v_mfma_f32_16x16x32_bf16 v[36:39], v[144:147], v[218:221], v[36:39]
	v_mfma_f32_16x16x32_bf16 v[32:35], v[152:155], v[218:221], v[32:35]
	v_mfma_f32_16x16x32_bf16 v[20:23], v[144:147], v[226:229], v[20:23]
	v_mfma_f32_16x16x32_bf16 v[16:19], v[152:155], v[226:229], v[16:19]
	v_mfma_f32_16x16x32_bf16 v[44:47], v[156:159], v[190:193], v[44:47]
	v_mfma_f32_16x16x32_bf16 v[40:43], v[166:169], v[190:193], v[40:43]
	v_mfma_f32_16x16x32_bf16 v[28:31], v[156:159], v[198:201], v[28:31]
	v_mfma_f32_16x16x32_bf16 v[24:27], v[166:169], v[198:201], v[24:27]
	v_mfma_f32_16x16x32_bf16 v[12:15], v[156:159], v[214:217], v[12:15]
	v_mfma_f32_16x16x32_bf16 v[8:11], v[166:169], v[214:217], v[8:11]
	v_mfma_f32_16x16x32_bf16 v[4:7], v[156:159], v[222:225], v[4:7]
	v_mfma_f32_16x16x32_bf16 v[0:3], v[166:169], v[222:225], v[0:3]
	v_mfma_f32_16x16x32_bf16 v[44:47], v[160:163], v[194:197], v[44:47]
	v_mfma_f32_16x16x32_bf16 v[40:43], v[186:189], v[194:197], v[40:43]
	v_mfma_f32_16x16x32_bf16 v[28:31], v[160:163], v[202:205], v[28:31]
	v_mfma_f32_16x16x32_bf16 v[24:27], v[186:189], v[202:205], v[24:27]
	v_mfma_f32_16x16x32_bf16 v[12:15], v[160:163], v[218:221], v[12:15]
	v_mfma_f32_16x16x32_bf16 v[8:11], v[186:189], v[218:221], v[8:11]
	v_mfma_f32_16x16x32_bf16 v[4:7], v[160:163], v[226:229], v[4:7]
	v_mfma_f32_16x16x32_bf16 v[0:3], v[186:189], v[226:229], v[0:3]
	s_setprio 0
	s_barrier
	s_add_i32 s63, s63, 2
	s_add_u32 s61, s61, 0x100
	s_addc_u32 s62, s62, 0
	s_add_u32 s56, s56, 0x100
	s_addc_u32 s57, s57, 0
	s_cmp_gt_u32 s63, 61
	s_cbranch_scc0 .LBB0_1297
	s_and_b64 vcc, exec, s[40:41]
	s_cbranch_vccz .LBB0_1300
	s_barrier

; #define PG8_STAGE(bufoff, gbase, voff) do { _Pragma("unroll") for (int _i = 0; _i < 2; ++_i) \
;         __builtin_amdgcn_global_load_lds((const unsigned*)((const char*)(gbase) + (voff)[_i]), (PG8_LAS unsigned*)(lds + (bufoff) + ldsw + _i * 8192), 16, 0, 0); } while (0)
; #define PG8_LDA(dst, b, h) do { _Pragma("unroll") for (int m = 0; m < 4; ++m) _Pragma("unroll") for (int k = 0; k < 2; ++k) dst[m][k] = *(const PG8_LAS bf16x8*)(lds + PG8_SA(b, h) + aoff + m * 2048 + k * 1024); } while (0)
; #define PG8_LDB(dst, b, h) do { _Pragma("unroll") for (int n = 0; n < 2; ++n) _Pragma("unroll") for (int k = 0; k < 2; ++k) dst[n][k] = *(const PG8_LAS bf16x8*)(lds + PG8_SB(b, h) + boff + n * 2048 + k * 1024); } while (0)
; #define PG8_MMA(ai, bj, At, Bt) do { __builtin_amdgcn_s_setprio(1); _Pragma("unroll") for (int m = 0; m < 4; ++m) _Pragma("unroll") for (int n = 0; n < 2; ++n) _Pragma("unroll") for (int k = 0; k < 2; ++k) \
;         acc[ai][bj][m][n] = __builtin_amdgcn_mfma_f32_16x16x32_bf16(Bt[n][k], At[m][k], acc[ai][bj][m][n], 0, 0, 0); __builtin_amdgcn_s_setprio(0); } while (0)
; #define PG8_WAIT_V(n) asm volatile("s_waitcnt vmcnt(" #n ")" ::: "memory")
; #define PG8_WAIT_L(n) asm volatile("s_waitcnt lgkmcnt(" #n ")" ::: "memory")
; template <class Epi, class Sched, bool ALIGN_EPI = false, bool SP2 = false>
; __device__ __forceinline__ void gemm_phase(PG8_LAS unsigned char* lds, const Gemm g, const Sched& S, const Epi& E) {
;     ...
;             const bool last = (t == nt - 2);
;             const char* a1 = cA + (size_t)(t + 1) * kstep;
;             const char* a2 = last ? nA : cA + (size_t)(t + 2) * kstep; const char* b2 = last ? nB : cB + (size_t)(t + 2) * kstep;
;             const char* a3 = a2 + kstep; const char* b3 = b2 + kstep;
;             if (last && has_next) S.a_ready(nxt);
;             if constexpr (SP2) {
;             PG8_LDB(B0, 0, 0); PG8_LDB(B1, 0, 1); PG8_SCHED; PG8_LDA(At, 0, 0); PG8_STAGE(PG8_SA(1, 1), a1 + hstepA, voffA);
;             PG8_WAIT_V(8); PG8_WAIT_L(0); PG8_BAR; PG8_MMA(0, 0, At, B0); PG8_MMA(0, 1, At, B1); PG8_BAR; PG8_SCHED;
;             PG8_LDA(At, 0, 1); PG8_STAGE(PG8_SB(0, 0), b2, voffB); PG8_STAGE(PG8_SB(0, 1), b2 + hstepB, voffB); PG8_STAGE(PG8_SA(0, 0), a2, voffA);
;             PG8_WAIT_V(8); PG8_WAIT_L(0); PG8_BAR; PG8_MMA(1, 0, At, B0); PG8_MMA(1, 1, At, B1); PG8_BAR; PG8_SCHED;
.LBB0_1317:
	s_add_u32 s0, s58, 0xfff00080
	s_addc_u32 s1, s59, -1
	s_add_i32 s4, 0, 0x10000
	s_cmp_eq_u32 s43, 4
	s_cselect_b32 s1, s41, s1
	s_cselect_b32 s0, s40, s0
	s_cselect_b32 s61, s57, s17
	s_cselect_b32 s60, s56, s16
	s_add_i32 s5, 0, 0x14000
	v_add_u32_e32 v150, s4, v136
	v_add_u32_e32 v162, s5, v136
	ds_read_b128 v[138:141], v150
	ds_read_b128 v[142:145], v150 offset:1024
	ds_read_b128 v[146:149], v150 offset:2048
	ds_read_b128 v[150:153], v150 offset:3072
	ds_read_b128 v[154:157], v162
	ds_read_b128 v[158:161], v162 offset:1024
	ds_read_b128 v[166:169], v162 offset:2048
	ds_read_b128 v[186:189], v162 offset:3072
	v_lshl_add_u64 v[162:163], s[58:59], 0, v[134:135]
	s_add_i32 m0, s13, 0xc000
	ds_read_b128 v[190:193], v137
	ds_read_b128 v[194:197], v137 offset:1024
	ds_read_b128 v[198:201], v137 offset:2048
	ds_read_b128 v[202:205], v137 offset:3072
	ds_read_b128 v[214:217], v137 offset:4096
	ds_read_b128 v[218:221], v137 offset:5120
	ds_read_b128 v[222:225], v137 offset:6144
	ds_read_b128 v[226:229], v137 offset:7168
	global_load_lds_dwordx4 v[162:163], off
	v_lshl_add_u64 v[162:163], s[58:59], 0, v[132:133]
	s_add_i32 m0, s13, 0xe000
	s_nop 0
	global_load_lds_dwordx4 v[162:163], off
	s_waitcnt vmcnt(8)
	s_waitcnt lgkmcnt(0)
	s_barrier
	s_setprio 1
	s_waitcnt lgkmcnt(0)
	v_mfma_f32_16x16x32_bf16 v[124:127], v[138:141], v[190:193], v[124:127]
	v_mfma_f32_16x16x32_bf16 v[120:123], v[146:149], v[190:193], v[120:123]
	v_mfma_f32_16x16x32_bf16 v[116:119], v[138:141], v[198:201], v[116:119]
	v_mfma_f32_16x16x32_bf16 v[112:115], v[146:149], v[198:201], v[112:115]
	v_mfma_f32_16x16x32_bf16 v[108:111], v[138:141], v[214:217], v[108:111]
	v_mfma_f32_16x16x32_bf16 v[100:103], v[146:149], v[214:217], v[100:103]
	v_mfma_f32_16x16x32_bf16 v[92:95], v[138:141], v[222:225], v[92:95]
	v_mfma_f32_16x16x32_bf16 v[84:87], v[146:149], v[222:225], v[84:87]
	v_mfma_f32_16x16x32_bf16 v[124:127], v[142:145], v[194:197], v[124:127]
	v_mfma_f32_16x16x32_bf16 v[120:123], v[150:153], v[194:197], v[120:123]
	v_mfma_f32_16x16x32_bf16 v[116:119], v[142:145], v[202:205], v[116:119]
	v_mfma_f32_16x16x32_bf16 v[112:115], v[150:153], v[202:205], v[112:115]
	v_mfma_f32_16x16x32_bf16 v[108:111], v[142:145], v[218:221], v[108:111]
	v_mfma_f32_16x16x32_bf16 v[100:103], v[150:153], v[218:221], v[100:103]
	v_mfma_f32_16x16x32_bf16 v[92:95], v[142:145], v[226:229], v[92:95]
	v_mfma_f32_16x16x32_bf16 v[84:87], v[150:153], v[226:229], v[84:87]
	v_mfma_f32_16x16x32_bf16 v[104:107], v[154:157], v[190:193], v[104:107]
	v_mfma_f32_16x16x32_bf16 v[96:99], v[166:169], v[190:193], v[96:99]
	v_mfma_f32_16x16x32_bf16 v[88:91], v[154:157], v[198:201], v[88:91]
	v_mfma_f32_16x16x32_bf16 v[80:83], v[166:169], v[198:201], v[80:83]
	v_mfma_f32_16x16x32_bf16 v[76:79], v[154:157], v[214:217], v[76:79]
	v_mfma_f32_16x16x32_bf16 v[72:75], v[166:169], v[214:217], v[72:75]
	v_mfma_f32_16x16x32_bf16 v[68:71], v[154:157], v[222:225], v[68:71]
	v_mfma_f32_16x16x32_bf16 v[64:67], v[166:169], v[222:225], v[64:67]
	v_mfma_f32_16x16x32_bf16 v[104:107], v[158:161], v[194:197], v[104:107]
	v_mfma_f32_16x16x32_bf16 v[96:99], v[186:189], v[194:197], v[96:99]
	v_mfma_f32_16x16x32_bf16 v[88:91], v[158:161], v[202:205], v[88:91]
	v_mfma_f32_16x16x32_bf16 v[80:83], v[186:189], v[202:205], v[80:83]
	v_mfma_f32_16x16x32_bf16 v[76:79], v[158:161], v[218:221], v[76:79]
	v_mfma_f32_16x16x32_bf16 v[72:75], v[186:189], v[218:221], v[72:75]
	v_mfma_f32_16x16x32_bf16 v[68:71], v[158:161], v[226:229], v[68:71]
	v_mfma_f32_16x16x32_bf16 v[64:67], v[186:189], v[226:229], v[64:67]
	s_setprio 0
	s_barrier
	s_add_i32 s4, s4, s8
	v_lshl_add_u64 v[162:163], s[60:61], 0, v[130:131]
	s_mov_b32 m0, s4
	ds_read_b128 v[190:193], v137 offset:16384
	ds_read_b128 v[194:197], v137 offset:17408
	ds_read_b128 v[198:201], v137 offset:18432
	ds_read_b128 v[202:205], v137 offset:19456
	ds_read_b128 v[214:217], v137 offset:20480
	ds_read_b128 v[218:221], v137 offset:21504
	ds_read_b128 v[222:225], v137 offset:22528
	ds_read_b128 v[226:229], v137 offset:23552
	global_load_lds_dwordx4 v[162:163], off
	s_add_i32 m0, s4, 0x2000
	s_add_u32 s36, s60, 0x100000
	v_lshl_add_u64 v[230:231], s[60:61], 0, v[128:129]
	s_addc_u32 s37, s61, 0
	s_add_i32 s4, s5, s8
	global_load_lds_dwordx4 v[230:231], off
	v_lshl_add_u64 v[232:233], s[36:37], 0, v[130:131]
	s_mov_b32 m0, s4
	v_lshl_add_u64 v[234:235], s[0:1], 0, v[128:129]
	global_load_lds_dwordx4 v[232:233], off
	v_lshl_add_u64 v[232:233], s[36:37], 0, v[128:129]
	s_add_i32 m0, s4, 0x2000
	s_nop 0
	global_load_lds_dwordx4 v[232:233], off
	v_lshl_add_u64 v[232:233], s[0:1], 0, v[130:131]
	s_mov_b32 m0, s13
	s_nop 0
	global_load_lds_dwordx4 v[232:233], off
	s_mov_b32 m0, s18
	s_nop 0
	global_load_lds_dwordx4 v[234:235], off
	s_waitcnt vmcnt(8)
	s_waitcnt lgkmcnt(0)
	s_barrier
; #define PG8_STAGE(bufoff, gbase, voff) do { _Pragma("unroll") for (int _i = 0; _i < 2; ++_i) \
;         __builtin_amdgcn_global_load_lds((const unsigned*)((const char*)(gbase) + (voff)[_i]), (PG8_LAS unsigned*)(lds + (bufoff) + ldsw + _i * 8192), 16, 0, 0); } while (0)
; #define PG8_LDA(dst, b, h) do { _Pragma("unroll") for (int m = 0; m < 4; ++m) _Pragma("unroll") for (int k = 0; k < 2; ++k) dst[m][k] = *(const PG8_LAS bf16x8*)(lds + PG8_SA(b, h) + aoff + m * 2048 + k * 1024); } while (0)
; #define PG8_LDB(dst, b, h) do { _Pragma("unroll") for (int n = 0; n < 2; ++n) _Pragma("unroll") for (int k = 0; k < 2; ++k) dst[n][k] = *(const PG8_LAS bf16x8*)(lds + PG8_SB(b, h) + boff + n * 2048 + k * 1024); } while (0)
; #define PG8_MMA(ai, bj, At, Bt) do { __builtin_amdgcn_s_setprio(1); _Pragma("unroll") for (int m = 0; m < 4; ++m) _Pragma("unroll") for (int n = 0; n < 2; ++n) _Pragma("unroll") for (int k = 0; k < 2; ++k) \
;         acc[ai][bj][m][n] = __builtin_amdgcn_mfma_f32_16x16x32_bf16(Bt[n][k], At[m][k], acc[ai][bj][m][n], 0, 0, 0); __builtin_amdgcn_s_setprio(0); } while (0)
; #define PG8_WAIT_V(n) asm volatile("s_waitcnt vmcnt(" #n ")" ::: "memory")
; #define PG8_WAIT_L(n) asm volatile("s_waitcnt lgkmcnt(" #n ")" ::: "memory")
; #define PG8_BAR __builtin_amdgcn_s_barrier()
; #define PG8_SCHED __builtin_amdgcn_sched_barrier(0)
; template <class Epi, class Sched, bool ALIGN_EPI = false, bool SP2 = false>
; __device__ __forceinline__ void gemm_phase(PG8_LAS unsigned char* lds, const Gemm g, const Sched& S, const Epi& E) {
;     ...
;             PG8_WAIT_V(8); PG8_WAIT_L(0); PG8_BAR; PG8_MMA(1, 0, At, B0); PG8_MMA(1, 1, At, B1); PG8_BAR; PG8_SCHED;
;             PG8_LDB(B0, 1, 0); PG8_LDB(B1, 1, 1); PG8_SCHED; PG8_LDA(At, 1, 0); PG8_STAGE(PG8_SA(0, 1), a2 + hstepA, voffA);
;             PG8_WAIT_V(8); PG8_WAIT_L(0); PG8_BAR; PG8_MMA(0, 0, At, B0); PG8_MMA(0, 1, At, B1); PG8_BAR; PG8_SCHED;
	s_setprio 1
	s_waitcnt lgkmcnt(0)
	v_mfma_f32_16x16x32_bf16 v[60:63], v[138:141], v[190:193], v[60:63]
	v_mfma_f32_16x16x32_bf16 v[56:59], v[146:149], v[190:193], v[56:59]
	v_mfma_f32_16x16x32_bf16 v[52:55], v[138:141], v[198:201], v[52:55]
	v_mfma_f32_16x16x32_bf16 v[48:51], v[146:149], v[198:201], v[48:51]
	v_mfma_f32_16x16x32_bf16 v[40:43], v[138:141], v[214:217], v[40:43]
	v_mfma_f32_16x16x32_bf16 v[32:35], v[146:149], v[214:217], v[32:35]
	v_mfma_f32_16x16x32_bf16 v[24:27], v[138:141], v[222:225], v[24:27]
	v_mfma_f32_16x16x32_bf16 v[16:19], v[146:149], v[222:225], v[16:19]
	v_mfma_f32_16x16x32_bf16 v[60:63], v[142:145], v[194:197], v[60:63]
	v_mfma_f32_16x16x32_bf16 v[56:59], v[150:153], v[194:197], v[56:59]
	v_mfma_f32_16x16x32_bf16 v[52:55], v[142:145], v[202:205], v[52:55]
	v_mfma_f32_16x16x32_bf16 v[48:51], v[150:153], v[202:205], v[48:51]
	v_mfma_f32_16x16x32_bf16 v[40:43], v[142:145], v[218:221], v[40:43]
	v_mfma_f32_16x16x32_bf16 v[32:35], v[150:153], v[218:221], v[32:35]
	v_mfma_f32_16x16x32_bf16 v[24:27], v[142:145], v[226:229], v[24:27]
	v_mfma_f32_16x16x32_bf16 v[16:19], v[150:153], v[226:229], v[16:19]
	v_mfma_f32_16x16x32_bf16 v[44:47], v[154:157], v[190:193], v[44:47]
	v_mfma_f32_16x16x32_bf16 v[36:39], v[166:169], v[190:193], v[36:39]
	v_mfma_f32_16x16x32_bf16 v[28:31], v[154:157], v[198:201], v[28:31]
	v_mfma_f32_16x16x32_bf16 v[20:23], v[166:169], v[198:201], v[20:23]
	v_mfma_f32_16x16x32_bf16 v[12:15], v[154:157], v[214:217], v[12:15]
	v_mfma_f32_16x16x32_bf16 v[8:11], v[166:169], v[214:217], v[8:11]
	v_mfma_f32_16x16x32_bf16 v[4:7], v[154:157], v[222:225], v[4:7]
	v_mfma_f32_16x16x32_bf16 v[0:3], v[166:169], v[222:225], v[0:3]
	v_mfma_f32_16x16x32_bf16 v[44:47], v[158:161], v[194:197], v[44:47]
	v_mfma_f32_16x16x32_bf16 v[36:39], v[186:189], v[194:197], v[36:39]
	v_mfma_f32_16x16x32_bf16 v[28:31], v[158:161], v[202:205], v[28:31]
	v_mfma_f32_16x16x32_bf16 v[20:23], v[186:189], v[202:205], v[20:23]
	v_mfma_f32_16x16x32_bf16 v[12:15], v[158:161], v[218:221], v[12:15]
	v_mfma_f32_16x16x32_bf16 v[8:11], v[186:189], v[218:221], v[8:11]
	v_mfma_f32_16x16x32_bf16 v[4:7], v[158:161], v[226:229], v[4:7]
	v_mfma_f32_16x16x32_bf16 v[0:3], v[186:189], v[226:229], v[0:3]
	s_setprio 0
	s_barrier
	s_add_i32 s4, 0, 0x18000
	s_add_i32 s5, 0, 0x1c000
	v_add_u32_e32 v150, s4, v136
	v_add_u32_e32 v164, s5, v136
	ds_read_b128 v[138:141], v150
	ds_read_b128 v[142:145], v150 offset:1024
	ds_read_b128 v[146:149], v150 offset:2048
	ds_read_b128 v[150:153], v150 offset:3072
	ds_read_b128 v[154:157], v164
	ds_read_b128 v[158:161], v164 offset:1024
	ds_read_b128 v[166:169], v164 offset:2048
	ds_read_b128 v[186:189], v164 offset:3072
	s_add_u32 s0, s0, 0x100000
	s_addc_u32 s1, s1, 0
	s_mov_b32 m0, s19
	v_lshl_add_u64 v[236:237], s[0:1], 0, v[130:131]
	ds_read_b128 v[190:193], v137 offset:32768
	ds_read_b128 v[194:197], v137 offset:33792
	ds_read_b128 v[198:201], v137 offset:34816
	ds_read_b128 v[202:205], v137 offset:35840
	ds_read_b128 v[214:217], v137 offset:36864
	ds_read_b128 v[218:221], v137 offset:37888
	ds_read_b128 v[222:225], v137 offset:38912
	ds_read_b128 v[226:229], v137 offset:39936
	global_load_lds_dwordx4 v[236:237], off
	v_lshl_add_u64 v[236:237], s[0:1], 0, v[128:129]
	s_mov_b32 m0, s24
	s_nop 0
	global_load_lds_dwordx4 v[236:237], off
	s_waitcnt vmcnt(8)
	s_waitcnt lgkmcnt(0)
	s_barrier
	s_setprio 1
	s_waitcnt lgkmcnt(0)
	v_mfma_f32_16x16x32_bf16 v[124:127], v[138:141], v[190:193], v[124:127]
	v_mfma_f32_16x16x32_bf16 v[120:123], v[146:149], v[190:193], v[120:123]
	v_mfma_f32_16x16x32_bf16 v[116:119], v[138:141], v[198:201], v[116:119]
	v_mfma_f32_16x16x32_bf16 v[112:115], v[146:149], v[198:201], v[112:115]
	v_mfma_f32_16x16x32_bf16 v[108:111], v[138:141], v[214:217], v[108:111]
	v_mfma_f32_16x16x32_bf16 v[100:103], v[146:149], v[214:217], v[100:103]
	v_mfma_f32_16x16x32_bf16 v[92:95], v[138:141], v[222:225], v[92:95]
	v_mfma_f32_16x16x32_bf16 v[84:87], v[146:149], v[222:225], v[84:87]
	v_mfma_f32_16x16x32_bf16 v[124:127], v[142:145], v[194:197], v[124:127]
	v_mfma_f32_16x16x32_bf16 v[120:123], v[150:153], v[194:197], v[120:123]
	v_mfma_f32_16x16x32_bf16 v[116:119], v[142:145], v[202:205], v[116:119]
	v_mfma_f32_16x16x32_bf16 v[112:115], v[150:153], v[202:205], v[112:115]
	v_mfma_f32_16x16x32_bf16 v[108:111], v[142:145], v[218:221], v[108:111]
	v_mfma_f32_16x16x32_bf16 v[100:103], v[150:153], v[218:221], v[100:103]
	v_mfma_f32_16x16x32_bf16 v[92:95], v[142:145], v[226:229], v[92:95]
	v_mfma_f32_16x16x32_bf16 v[84:87], v[150:153], v[226:229], v[84:87]
	v_mfma_f32_16x16x32_bf16 v[104:107], v[154:157], v[190:193], v[104:107]
	v_mfma_f32_16x16x32_bf16 v[96:99], v[166:169], v[190:193], v[96:99]
	v_mfma_f32_16x16x32_bf16 v[88:91], v[154:157], v[198:201], v[88:91]
	v_mfma_f32_16x16x32_bf16 v[80:83], v[166:169], v[198:201], v[80:83]
	v_mfma_f32_16x16x32_bf16 v[76:79], v[154:157], v[214:217], v[76:79]
	v_mfma_f32_16x16x32_bf16 v[72:75], v[166:169], v[214:217], v[72:75]
	v_mfma_f32_16x16x32_bf16 v[68:71], v[154:157], v[222:225], v[68:71]
	v_mfma_f32_16x16x32_bf16 v[64:67], v[166:169], v[222:225], v[64:67]
	v_mfma_f32_16x16x32_bf16 v[104:107], v[158:161], v[194:197], v[104:107]
	v_mfma_f32_16x16x32_bf16 v[96:99], v[186:189], v[194:197], v[96:99]
	v_mfma_f32_16x16x32_bf16 v[88:91], v[158:161], v[202:205], v[88:91]
	v_mfma_f32_16x16x32_bf16 v[80:83], v[186:189], v[202:205], v[80:83]
	v_mfma_f32_16x16x32_bf16 v[76:79], v[158:161], v[218:221], v[76:79]
	v_mfma_f32_16x16x32_bf16 v[72:75], v[186:189], v[218:221], v[72:75]
	v_mfma_f32_16x16x32_bf16 v[68:71], v[158:161], v[226:229], v[68:71]
	v_mfma_f32_16x16x32_bf16 v[64:67], v[186:189], v[226:229], v[64:67]
	s_setprio 0
	s_barrier
; #define PG8_STAGE(bufoff, gbase, voff) do { _Pragma("unroll") for (int _i = 0; _i < 2; ++_i) \
;         __builtin_amdgcn_global_load_lds((const unsigned*)((const char*)(gbase) + (voff)[_i]), (PG8_LAS unsigned*)(lds + (bufoff) + ldsw + _i * 8192), 16, 0, 0); } while (0)
; #define PG8_LDA(dst, b, h) do { _Pragma("unroll") for (int m = 0; m < 4; ++m) _Pragma("unroll") for (int k = 0; k < 2; ++k) dst[m][k] = *(const PG8_LAS bf16x8*)(lds + PG8_SA(b, h) + aoff + m * 2048 + k * 1024); } while (0)
; #define PG8_WAIT_V(n) asm volatile("s_waitcnt vmcnt(" #n ")" ::: "memory")
; template <class Epi, class Sched, bool ALIGN_EPI = false, bool SP2 = false>
; __device__ __forceinline__ void gemm_phase(PG8_LAS unsigned char* lds, const Gemm g, const Sched& S, const Epi& E) {
;     ...
;             PG8_LDA(At, 1, 1); PG8_STAGE(PG8_SB(1, 0), b3, voffB); PG8_STAGE(PG8_SB(1, 1), b3 + hstepB, voffB); PG8_STAGE(PG8_SA(1, 0), a3, voffA);
;             PG8_WAIT_V(8); PG8_WAIT_L(0); PG8_BAR; PG8_MMA(1, 0, At, B0); PG8_MMA(1, 1, At, B1); PG8_BAR; PG8_SCHED;
;             } else {
;             PG8_LDB(B0, 0, 0); PG8_SCHED; PG8_LDA(At, 0, 0); PG8_STAGE(PG8_SA(1, 1), a1 + hstepA, voffA);
;             PG8_WAIT_L(8); PG8_BAR; PG8_WAIT_L(0); PG8_MMA(0, 0, At, B0); PG8_BAR; PG8_SCHED;
;             PG8_LDB(B1, 0, 1); PG8_STAGE(PG8_SB(0, 0), b2, voffB);
;             PG8_BAR; PG8_WAIT_L(0); PG8_MMA(0, 1, At, B1); PG8_BAR;
;             PG8_LDA(At, 0, 1); PG8_STAGE(PG8_SA(0, 0), a2, voffA);
;             PG8_BAR; PG8_WAIT_L(0); PG8_MMA(1, 0, At, B0); PG8_BAR; PG8_SCHED;
;             PG8_STAGE(PG8_SB(0, 1), b2 + hstepB, voffB);
;             PG8_WAIT_V(6); PG8_BAR; PG8_MMA(1, 1, At, B1); PG8_BAR;
;             PG8_LDB(B0, 1, 0); PG8_SCHED; PG8_LDA(At, 1, 0); PG8_STAGE(PG8_SA(0, 1), a2 + hstepA, voffA);
;             PG8_WAIT_L(8); PG8_BAR; PG8_WAIT_L(0); PG8_MMA(0, 0, At, B0); PG8_BAR; PG8_SCHED;
;             PG8_LDB(B1, 1, 1); PG8_STAGE(PG8_SB(1, 0), b3, voffB);
;             PG8_BAR; PG8_WAIT_L(0); PG8_MMA(0, 1, At, B1); PG8_BAR;
;             PG8_LDA(At, 1, 1); PG8_STAGE(PG8_SA(1, 0), a3, voffA);
;             PG8_BAR; PG8_WAIT_L(0); PG8_MMA(1, 0, At, B0); PG8_BAR; PG8_SCHED;
;             PG8_STAGE(PG8_SB(1, 1), b3 + hstepB, voffB);
;             PG8_WAIT_V(6); PG8_BAR; PG8_MMA(1, 1, At, B1); PG8_BAR;
;             }
;         }
;         if constexpr (ALIGN_EPI) { if (wr == 0) PG8_BAR; }
	s_add_i32 s0, s4, s8
	v_lshl_add_u64 v[162:163], v[162:163], 0, s[14:15]
	s_mov_b32 m0, s0
	ds_read_b128 v[190:193], v137 offset:49152
	ds_read_b128 v[194:197], v137 offset:50176
	ds_read_b128 v[198:201], v137 offset:51200
	ds_read_b128 v[202:205], v137 offset:52224
	ds_read_b128 v[214:217], v137 offset:53248
	ds_read_b128 v[218:221], v137 offset:54272
	ds_read_b128 v[222:225], v137 offset:55296
	ds_read_b128 v[226:229], v137 offset:56320
	global_load_lds_dwordx4 v[162:163], off
	s_add_i32 m0, s0, 0x2000
	s_add_u32 s0, s60, 0x100080
	v_lshl_add_u64 v[162:163], v[230:231], 0, s[14:15]
	s_addc_u32 s1, s61, 0
	s_add_i32 s4, s5, s8
	global_load_lds_dwordx4 v[162:163], off
	v_lshl_add_u64 v[162:163], s[0:1], 0, v[130:131]
	s_mov_b32 m0, s4
	s_nop 0
	global_load_lds_dwordx4 v[162:163], off
	v_lshl_add_u64 v[162:163], s[0:1], 0, v[128:129]
	s_add_i32 m0, s4, 0x2000
	s_nop 0
	global_load_lds_dwordx4 v[162:163], off
	v_lshl_add_u64 v[162:163], v[232:233], 0, s[14:15]
	s_mov_b32 m0, s35
	s_nop 0
	global_load_lds_dwordx4 v[162:163], off
	v_lshl_add_u64 v[162:163], v[234:235], 0, s[14:15]
	s_mov_b32 m0, s46
	s_nop 0
	global_load_lds_dwordx4 v[162:163], off
	s_waitcnt vmcnt(8)
	s_waitcnt lgkmcnt(0)
	s_barrier
	s_setprio 1
	s_waitcnt lgkmcnt(0)
	v_mfma_f32_16x16x32_bf16 v[60:63], v[138:141], v[190:193], v[60:63]
	v_mfma_f32_16x16x32_bf16 v[56:59], v[146:149], v[190:193], v[56:59]
	v_mfma_f32_16x16x32_bf16 v[52:55], v[138:141], v[198:201], v[52:55]
	v_mfma_f32_16x16x32_bf16 v[48:51], v[146:149], v[198:201], v[48:51]
	v_mfma_f32_16x16x32_bf16 v[40:43], v[138:141], v[214:217], v[40:43]
	v_mfma_f32_16x16x32_bf16 v[32:35], v[146:149], v[214:217], v[32:35]
	v_mfma_f32_16x16x32_bf16 v[24:27], v[138:141], v[222:225], v[24:27]
	v_mfma_f32_16x16x32_bf16 v[16:19], v[146:149], v[222:225], v[16:19]
	v_mfma_f32_16x16x32_bf16 v[60:63], v[142:145], v[194:197], v[60:63]
	v_mfma_f32_16x16x32_bf16 v[56:59], v[150:153], v[194:197], v[56:59]
	v_mfma_f32_16x16x32_bf16 v[52:55], v[142:145], v[202:205], v[52:55]
	v_mfma_f32_16x16x32_bf16 v[48:51], v[150:153], v[202:205], v[48:51]
	v_mfma_f32_16x16x32_bf16 v[40:43], v[142:145], v[218:221], v[40:43]
	v_mfma_f32_16x16x32_bf16 v[32:35], v[150:153], v[218:221], v[32:35]
	v_mfma_f32_16x16x32_bf16 v[24:27], v[142:145], v[226:229], v[24:27]
	v_mfma_f32_16x16x32_bf16 v[16:19], v[150:153], v[226:229], v[16:19]
	v_mfma_f32_16x16x32_bf16 v[44:47], v[154:157], v[190:193], v[44:47]
	v_mfma_f32_16x16x32_bf16 v[36:39], v[166:169], v[190:193], v[36:39]
	v_mfma_f32_16x16x32_bf16 v[28:31], v[154:157], v[198:201], v[28:31]
	v_mfma_f32_16x16x32_bf16 v[20:23], v[166:169], v[198:201], v[20:23]
	v_mfma_f32_16x16x32_bf16 v[12:15], v[154:157], v[214:217], v[12:15]
	v_mfma_f32_16x16x32_bf16 v[8:11], v[166:169], v[214:217], v[8:11]
	v_mfma_f32_16x16x32_bf16 v[4:7], v[154:157], v[222:225], v[4:7]
	v_mfma_f32_16x16x32_bf16 v[0:3], v[166:169], v[222:225], v[0:3]
	v_mfma_f32_16x16x32_bf16 v[44:47], v[158:161], v[194:197], v[44:47]
	v_mfma_f32_16x16x32_bf16 v[36:39], v[186:189], v[194:197], v[36:39]
	v_mfma_f32_16x16x32_bf16 v[28:31], v[158:161], v[202:205], v[28:31]
	v_mfma_f32_16x16x32_bf16 v[20:23], v[186:189], v[202:205], v[20:23]
	v_mfma_f32_16x16x32_bf16 v[12:15], v[158:161], v[218:221], v[12:15]
	v_mfma_f32_16x16x32_bf16 v[8:11], v[186:189], v[218:221], v[8:11]
	v_mfma_f32_16x16x32_bf16 v[4:7], v[158:161], v[226:229], v[4:7]
	v_mfma_f32_16x16x32_bf16 v[0:3], v[186:189], v[226:229], v[0:3]
	s_setprio 0
	s_barrier
	s_add_i32 s43, s43, 2
	s_add_u32 s16, s16, 0x100
	s_addc_u32 s17, s17, 0
	s_add_u32 s58, s58, 0x100
	s_addc_u32 s59, s59, 0
	s_cmp_gt_u32 s43, 5
	s_cbranch_scc0 .LBB0_1317
	s_and_b64 vcc, exec, s[30:31]
	s_cbranch_vccz .LBB0_1320
	s_barrier
